# the three adaLN RMSNorm phases by hand with XCD-aware row assignment (a wave normalises 8 consecutive rows written by its own XCD's output-projection tiles), one shift/scale load per wave, DPP wave su
# baseline (speedup 1.0000x reference)
.LBB0_1520:
	s_or_b64 exec, exec, s[0:1]
	v_mov_b32_e32 v32, v174
	s_waitcnt lgkmcnt(0)
	s_barrier
	s_movk_i32 s3, 0x4080
	s_waitcnt vmcnt(22)
	v_ashrrev_i32_e32 v0, 6, v32
	v_add_u32_e32 v54, s94, v0
	v_cmp_gt_i32_e32 vcc, s3, v54
	s_mul_hi_i32 s55, s74, 0x880
	s_mul_i32 s54, s74, 0x880
	s_and_saveexec_b64 s[6:7], vcc
	s_cbranch_execz .LBB0_1525
	s_cmpk_lg_i32 s86, 0x100
	s_cbranch_scc1 .Lnl0_orig
	s_waitcnt vmcnt(0)
	v_readlane_b32 s20, v192, 13
	v_readlane_b32 s21, v192, 14
	v_lshrrev_b32_e32 v238, 6, v174
	s_nop 1
	v_readfirstlane_b32 s1, v238
	v_and_b32_e32 v236, 63, v174
	v_lshlrev_b32_e32 v237, 3, v236
	v_lshlrev_b32_e32 v236, 4, v236
	s_lshr_b32 s3, s94, 3
	s_and_b32 s18, s3, 7
	s_lshr_b32 s19, s3, 3
	s_lshl_b32 s0, s18, 11
	s_lshl_b32 s3, s19, 6
	s_add_i32 s0, s0, s3
	s_lshl_b32 s3, s1, 3
	s_add_i32 s0, s0, s3
	global_load_dwordx4 v[48:51], v236, s[20:21] offset:0
	global_load_dwordx4 v[52:55], v236, s[20:21] offset:1024
	global_load_dwordx4 v[56:59], v236, s[20:21] offset:2048
	global_load_dwordx4 v[60:63], v236, s[20:21] offset:3072
	s_lshl_b32 s8, s0, 12
	s_add_u32 s8, s82, s8
	s_addc_u32 s9, s83, 0
	s_mul_i32 s10, s0, 0x880
	s_add_u32 s10, s10, 0x3018000
	s_add_u32 s10, s84, s10
	s_addc_u32 s11, s85, 0
	s_lshr_b32 s1, s0, 12
	s_mul_i32 s3, s1, 0x6000
	s_add_u32 s12, s84, 0x52a3880
	s_addc_u32 s13, s85, 0
	s_add_u32 s12, s12, s3
	s_addc_u32 s13, s13, 0
	s_add_u32 s14, s12, 0x1000
	s_addc_u32 s15, s13, 0
	global_load_dwordx4 v[0:3], v236, s[8:9] offset:0
	global_load_dwordx4 v[4:7], v236, s[8:9] offset:1024
	global_load_dwordx4 v[8:11], v236, s[8:9] offset:2048
	global_load_dwordx4 v[12:15], v236, s[8:9] offset:3072
	s_add_u32 s8, s8, 0x1000
	s_addc_u32 s9, s9, 0
	global_load_dwordx4 v[64:67], v236, s[12:13] offset:0
	global_load_dwordx4 v[68:71], v236, s[12:13] offset:1024
	global_load_dwordx4 v[72:75], v236, s[12:13] offset:2048
	global_load_dwordx4 v[76:79], v236, s[12:13] offset:3072
	global_load_dwordx4 v[194:197], v236, s[14:15] offset:0
	global_load_dwordx4 v[198:201], v236, s[14:15] offset:1024
	global_load_dwordx4 v[202:205], v236, s[14:15] offset:2048
	global_load_dwordx4 v[206:209], v236, s[14:15] offset:3072
	global_load_dwordx4 v[16:19], v236, s[8:9] offset:0
	global_load_dwordx4 v[20:23], v236, s[8:9] offset:1024
	global_load_dwordx4 v[24:27], v236, s[8:9] offset:2048
	global_load_dwordx4 v[28:31], v236, s[8:9] offset:3072
	s_add_u32 s8, s8, 0x1000
	s_addc_u32 s9, s9, 0
	global_load_dwordx4 v[32:35], v236, s[8:9] offset:0
	global_load_dwordx4 v[36:39], v236, s[8:9] offset:1024
	global_load_dwordx4 v[40:43], v236, s[8:9] offset:2048
	global_load_dwordx4 v[44:47], v236, s[8:9] offset:3072
	s_add_u32 s8, s8, 0x1000
	s_addc_u32 s9, s9, 0
	s_waitcnt vmcnt(16)
	v_mul_f32_e32 v238, v0, v0
	v_mul_f32_e32 v239, v1, v1
	v_fmac_f32_e32 v238, v2, v2
	v_fmac_f32_e32 v239, v3, v3
	v_fmac_f32_e32 v238, v4, v4
	v_fmac_f32_e32 v239, v5, v5
	v_fmac_f32_e32 v238, v6, v6
	v_fmac_f32_e32 v239, v7, v7
	v_fmac_f32_e32 v238, v8, v8
	v_fmac_f32_e32 v239, v9, v9
	v_fmac_f32_e32 v238, v10, v10
	v_fmac_f32_e32 v239, v11, v11
	v_fmac_f32_e32 v238, v12, v12
	v_fmac_f32_e32 v239, v13, v13
	v_fmac_f32_e32 v238, v14, v14
	v_fmac_f32_e32 v239, v15, v15
	v_add_f32_e32 v238, v238, v239
	s_nop 1
	v_add_f32_dpp v238, v238, v238 quad_perm:[1,0,3,2] row_mask:0xf bank_mask:0xf bound_ctrl:1
	s_nop 1
	v_add_f32_dpp v238, v238, v238 quad_perm:[2,3,0,1] row_mask:0xf bank_mask:0xf bound_ctrl:1
	s_nop 1
	v_add_f32_dpp v238, v238, v238 row_ror:4 row_mask:0xf bank_mask:0xf bound_ctrl:1
	s_nop 1
	v_add_f32_dpp v238, v238, v238 row_ror:8 row_mask:0xf bank_mask:0xf bound_ctrl:1
	s_nop 1
	v_readlane_b32 s1, v238, 0
	v_readlane_b32 s3, v238, 16
	v_readlane_b32 s16, v238, 32
	v_readlane_b32 s17, v238, 48
	s_nop 1
	v_mov_b32_e32 v238, s1
	v_add_f32_e32 v238, s3, v238
	v_add_f32_e32 v238, s16, v238
	v_add_f32_e32 v238, s17, v238
	v_mov_b32_e32 v239, 0x358637bd
	v_fmac_f32_e32 v239, 0x3a800000, v238
	v_rsq_f32_e32 v238, v239
	s_nop 0
	s_waitcnt vmcnt(8)
	v_add_f32_e32 v194, 1.0, v194
	v_add_f32_e32 v195, 1.0, v195
	v_add_f32_e32 v196, 1.0, v196
	v_add_f32_e32 v197, 1.0, v197
	v_add_f32_e32 v198, 1.0, v198
	v_add_f32_e32 v199, 1.0, v199
	v_add_f32_e32 v200, 1.0, v200
	v_add_f32_e32 v201, 1.0, v201
	v_add_f32_e32 v202, 1.0, v202
	v_add_f32_e32 v203, 1.0, v203
	v_add_f32_e32 v204, 1.0, v204
	v_add_f32_e32 v205, 1.0, v205
	v_add_f32_e32 v206, 1.0, v206
	v_add_f32_e32 v207, 1.0, v207
	v_add_f32_e32 v208, 1.0, v208
	v_add_f32_e32 v209, 1.0, v209
	v_mul_f32_e32 v0, v0, v238
	v_mul_f32_e32 v1, v1, v238
	v_mul_f32_e32 v2, v2, v238
	v_mul_f32_e32 v3, v3, v238
	v_mul_f32_e32 v4, v4, v238
	v_mul_f32_e32 v5, v5, v238
	v_mul_f32_e32 v6, v6, v238
	v_mul_f32_e32 v7, v7, v238
	v_mul_f32_e32 v8, v8, v238
	v_mul_f32_e32 v9, v9, v238
	v_mul_f32_e32 v10, v10, v238
	v_mul_f32_e32 v11, v11, v238
	v_mul_f32_e32 v12, v12, v238
	v_mul_f32_e32 v13, v13, v238
	v_mul_f32_e32 v14, v14, v238
	v_mul_f32_e32 v15, v15, v238
	v_mul_f32_e32 v0, v48, v0
	v_mul_f32_e32 v1, v49, v1
	v_mul_f32_e32 v2, v50, v2
	v_mul_f32_e32 v3, v51, v3
	v_mul_f32_e32 v4, v52, v4
	v_mul_f32_e32 v5, v53, v5
	v_mul_f32_e32 v6, v54, v6
	v_mul_f32_e32 v7, v55, v7
	v_mul_f32_e32 v8, v56, v8
	v_mul_f32_e32 v9, v57, v9
	v_mul_f32_e32 v10, v58, v10
	v_mul_f32_e32 v11, v59, v11
	v_mul_f32_e32 v12, v60, v12
	v_mul_f32_e32 v13, v61, v13
	v_mul_f32_e32 v14, v62, v14
	v_mul_f32_e32 v15, v63, v15
	v_fma_f32 v0, v194, v0, v64
	v_fma_f32 v1, v195, v1, v65
	v_fma_f32 v2, v196, v2, v66
	v_fma_f32 v3, v197, v3, v67
	v_fma_f32 v4, v198, v4, v68
	v_fma_f32 v5, v199, v5, v69
	v_fma_f32 v6, v200, v6, v70
	v_fma_f32 v7, v201, v7, v71
	v_fma_f32 v8, v202, v8, v72
	v_fma_f32 v9, v203, v9, v73
	v_fma_f32 v10, v204, v10, v74
	v_fma_f32 v11, v205, v11, v75
	v_fma_f32 v12, v206, v12, v76
	v_fma_f32 v13, v207, v13, v77
	v_fma_f32 v14, v208, v14, v78
	v_fma_f32 v15, v209, v15, v79
	v_cvt_pk_bf16_f32 v240, v0, v1
	v_cvt_pk_bf16_f32 v241, v2, v3
	v_cvt_pk_bf16_f32 v242, v4, v5
	v_cvt_pk_bf16_f32 v243, v6, v7
	v_cvt_pk_bf16_f32 v244, v8, v9
	v_cvt_pk_bf16_f32 v245, v10, v11
	v_cvt_pk_bf16_f32 v246, v12, v13
	v_cvt_pk_bf16_f32 v247, v14, v15
	global_store_dwordx2 v237, v[240:241], s[10:11] offset:0
	global_store_dwordx2 v237, v[242:243], s[10:11] offset:512
	global_store_dwordx2 v237, v[244:245], s[10:11] offset:1024
	global_store_dwordx2 v237, v[246:247], s[10:11] offset:1536
	s_add_u32 s10, s10, 0x880
	s_addc_u32 s11, s11, 0
	global_load_dwordx4 v[0:3], v236, s[8:9] offset:0
	global_load_dwordx4 v[4:7], v236, s[8:9] offset:1024
	global_load_dwordx4 v[8:11], v236, s[8:9] offset:2048
	global_load_dwordx4 v[12:15], v236, s[8:9] offset:3072
	s_add_u32 s8, s8, 0x1000
	s_addc_u32 s9, s9, 0
	s_waitcnt vmcnt(12)
	v_mul_f32_e32 v238, v16, v16
	v_mul_f32_e32 v239, v17, v17
	v_fmac_f32_e32 v238, v18, v18
	v_fmac_f32_e32 v239, v19, v19
	v_fmac_f32_e32 v238, v20, v20
	v_fmac_f32_e32 v239, v21, v21
	v_fmac_f32_e32 v238, v22, v22
	v_fmac_f32_e32 v239, v23, v23
	v_fmac_f32_e32 v238, v24, v24
	v_fmac_f32_e32 v239, v25, v25
	v_fmac_f32_e32 v238, v26, v26
	v_fmac_f32_e32 v239, v27, v27
	v_fmac_f32_e32 v238, v28, v28
	v_fmac_f32_e32 v239, v29, v29
	v_fmac_f32_e32 v238, v30, v30
	v_fmac_f32_e32 v239, v31, v31
	v_add_f32_e32 v238, v238, v239
	s_nop 1
	v_add_f32_dpp v238, v238, v238 quad_perm:[1,0,3,2] row_mask:0xf bank_mask:0xf bound_ctrl:1
	s_nop 1
	v_add_f32_dpp v238, v238, v238 quad_perm:[2,3,0,1] row_mask:0xf bank_mask:0xf bound_ctrl:1
	s_nop 1
	v_add_f32_dpp v238, v238, v238 row_ror:4 row_mask:0xf bank_mask:0xf bound_ctrl:1
	s_nop 1
	v_add_f32_dpp v238, v238, v238 row_ror:8 row_mask:0xf bank_mask:0xf bound_ctrl:1
	s_nop 1
	v_readlane_b32 s1, v238, 0
	v_readlane_b32 s3, v238, 16
	v_readlane_b32 s16, v238, 32
	v_readlane_b32 s17, v238, 48
	s_nop 1
	v_mov_b32_e32 v238, s1
	v_add_f32_e32 v238, s3, v238
	v_add_f32_e32 v238, s16, v238
	v_add_f32_e32 v238, s17, v238
	v_mov_b32_e32 v239, 0x358637bd
	v_fmac_f32_e32 v239, 0x3a800000, v238
	v_rsq_f32_e32 v238, v239
	s_nop 0
	v_mul_f32_e32 v16, v16, v238
	v_mul_f32_e32 v17, v17, v238
	v_mul_f32_e32 v18, v18, v238
	v_mul_f32_e32 v19, v19, v238
	v_mul_f32_e32 v20, v20, v238
	v_mul_f32_e32 v21, v21, v238
	v_mul_f32_e32 v22, v22, v238
	v_mul_f32_e32 v23, v23, v238
	v_mul_f32_e32 v24, v24, v238
	v_mul_f32_e32 v25, v25, v238
	v_mul_f32_e32 v26, v26, v238
	v_mul_f32_e32 v27, v27, v238
	v_mul_f32_e32 v28, v28, v238
	v_mul_f32_e32 v29, v29, v238
	v_mul_f32_e32 v30, v30, v238
	v_mul_f32_e32 v31, v31, v238
	v_mul_f32_e32 v16, v48, v16
	v_mul_f32_e32 v17, v49, v17
	v_mul_f32_e32 v18, v50, v18
	v_mul_f32_e32 v19, v51, v19
	v_mul_f32_e32 v20, v52, v20
	v_mul_f32_e32 v21, v53, v21
	v_mul_f32_e32 v22, v54, v22
	v_mul_f32_e32 v23, v55, v23
	v_mul_f32_e32 v24, v56, v24
	v_mul_f32_e32 v25, v57, v25
	v_mul_f32_e32 v26, v58, v26
	v_mul_f32_e32 v27, v59, v27
	v_mul_f32_e32 v28, v60, v28
	v_mul_f32_e32 v29, v61, v29
	v_mul_f32_e32 v30, v62, v30
	v_mul_f32_e32 v31, v63, v31
	v_fma_f32 v16, v194, v16, v64
	v_fma_f32 v17, v195, v17, v65
	v_fma_f32 v18, v196, v18, v66
	v_fma_f32 v19, v197, v19, v67
	v_fma_f32 v20, v198, v20, v68
	v_fma_f32 v21, v199, v21, v69
	v_fma_f32 v22, v200, v22, v70
	v_fma_f32 v23, v201, v23, v71
	v_fma_f32 v24, v202, v24, v72
	v_fma_f32 v25, v203, v25, v73
	v_fma_f32 v26, v204, v26, v74
	v_fma_f32 v27, v205, v27, v75
	v_fma_f32 v28, v206, v28, v76
	v_fma_f32 v29, v207, v29, v77
	v_fma_f32 v30, v208, v30, v78
	v_fma_f32 v31, v209, v31, v79
	v_cvt_pk_bf16_f32 v248, v16, v17
	v_cvt_pk_bf16_f32 v249, v18, v19
	v_cvt_pk_bf16_f32 v250, v20, v21
	v_cvt_pk_bf16_f32 v251, v22, v23
	v_cvt_pk_bf16_f32 v252, v24, v25
	v_cvt_pk_bf16_f32 v253, v26, v27
	v_cvt_pk_bf16_f32 v254, v28, v29
	v_cvt_pk_bf16_f32 v255, v30, v31
	global_store_dwordx2 v237, v[248:249], s[10:11] offset:0
	global_store_dwordx2 v237, v[250:251], s[10:11] offset:512
	global_store_dwordx2 v237, v[252:253], s[10:11] offset:1024
	global_store_dwordx2 v237, v[254:255], s[10:11] offset:1536
	s_add_u32 s10, s10, 0x880
	s_addc_u32 s11, s11, 0
	global_load_dwordx4 v[16:19], v236, s[8:9] offset:0
	global_load_dwordx4 v[20:23], v236, s[8:9] offset:1024
	global_load_dwordx4 v[24:27], v236, s[8:9] offset:2048
	global_load_dwordx4 v[28:31], v236, s[8:9] offset:3072
	s_add_u32 s8, s8, 0x1000
	s_addc_u32 s9, s9, 0
	s_waitcnt vmcnt(16)
	v_mul_f32_e32 v238, v32, v32
	v_mul_f32_e32 v239, v33, v33
	v_fmac_f32_e32 v238, v34, v34
	v_fmac_f32_e32 v239, v35, v35
	v_fmac_f32_e32 v238, v36, v36
	v_fmac_f32_e32 v239, v37, v37
	v_fmac_f32_e32 v238, v38, v38
	v_fmac_f32_e32 v239, v39, v39
	v_fmac_f32_e32 v238, v40, v40
	v_fmac_f32_e32 v239, v41, v41
	v_fmac_f32_e32 v238, v42, v42
	v_fmac_f32_e32 v239, v43, v43
	v_fmac_f32_e32 v238, v44, v44
	v_fmac_f32_e32 v239, v45, v45
	v_fmac_f32_e32 v238, v46, v46
	v_fmac_f32_e32 v239, v47, v47
	v_add_f32_e32 v238, v238, v239
	s_nop 1
	v_add_f32_dpp v238, v238, v238 quad_perm:[1,0,3,2] row_mask:0xf bank_mask:0xf bound_ctrl:1
	s_nop 1
	v_add_f32_dpp v238, v238, v238 quad_perm:[2,3,0,1] row_mask:0xf bank_mask:0xf bound_ctrl:1
	s_nop 1
	v_add_f32_dpp v238, v238, v238 row_ror:4 row_mask:0xf bank_mask:0xf bound_ctrl:1
	s_nop 1
	v_add_f32_dpp v238, v238, v238 row_ror:8 row_mask:0xf bank_mask:0xf bound_ctrl:1
	s_nop 1
	v_readlane_b32 s1, v238, 0
	v_readlane_b32 s3, v238, 16
	v_readlane_b32 s16, v238, 32
	v_readlane_b32 s17, v238, 48
	s_nop 1
	v_mov_b32_e32 v238, s1
	v_add_f32_e32 v238, s3, v238
	v_add_f32_e32 v238, s16, v238
	v_add_f32_e32 v238, s17, v238
	v_mov_b32_e32 v239, 0x358637bd
	v_fmac_f32_e32 v239, 0x3a800000, v238
	v_rsq_f32_e32 v238, v239
	s_nop 0
	v_mul_f32_e32 v32, v32, v238
	v_mul_f32_e32 v33, v33, v238
	v_mul_f32_e32 v34, v34, v238
	v_mul_f32_e32 v35, v35, v238
	v_mul_f32_e32 v36, v36, v238
	v_mul_f32_e32 v37, v37, v238
	v_mul_f32_e32 v38, v38, v238
	v_mul_f32_e32 v39, v39, v238
	v_mul_f32_e32 v40, v40, v238
	v_mul_f32_e32 v41, v41, v238
	v_mul_f32_e32 v42, v42, v238
	v_mul_f32_e32 v43, v43, v238
	v_mul_f32_e32 v44, v44, v238
	v_mul_f32_e32 v45, v45, v238
	v_mul_f32_e32 v46, v46, v238
	v_mul_f32_e32 v47, v47, v238
	v_mul_f32_e32 v32, v48, v32
	v_mul_f32_e32 v33, v49, v33
	v_mul_f32_e32 v34, v50, v34
	v_mul_f32_e32 v35, v51, v35
	v_mul_f32_e32 v36, v52, v36
	v_mul_f32_e32 v37, v53, v37
	v_mul_f32_e32 v38, v54, v38
	v_mul_f32_e32 v39, v55, v39
	v_mul_f32_e32 v40, v56, v40
	v_mul_f32_e32 v41, v57, v41
	v_mul_f32_e32 v42, v58, v42
	v_mul_f32_e32 v43, v59, v43
	v_mul_f32_e32 v44, v60, v44
	v_mul_f32_e32 v45, v61, v45
	v_mul_f32_e32 v46, v62, v46
	v_mul_f32_e32 v47, v63, v47
	v_fma_f32 v32, v194, v32, v64
	v_fma_f32 v33, v195, v33, v65
	v_fma_f32 v34, v196, v34, v66
	v_fma_f32 v35, v197, v35, v67
	v_fma_f32 v36, v198, v36, v68
	v_fma_f32 v37, v199, v37, v69
	v_fma_f32 v38, v200, v38, v70
	v_fma_f32 v39, v201, v39, v71
	v_fma_f32 v40, v202, v40, v72
	v_fma_f32 v41, v203, v41, v73
	v_fma_f32 v42, v204, v42, v74
	v_fma_f32 v43, v205, v43, v75
	v_fma_f32 v44, v206, v44, v76
	v_fma_f32 v45, v207, v45, v77
	v_fma_f32 v46, v208, v46, v78
	v_fma_f32 v47, v209, v47, v79
	v_cvt_pk_bf16_f32 v240, v32, v33
	v_cvt_pk_bf16_f32 v241, v34, v35
	v_cvt_pk_bf16_f32 v242, v36, v37
	v_cvt_pk_bf16_f32 v243, v38, v39
	v_cvt_pk_bf16_f32 v244, v40, v41
	v_cvt_pk_bf16_f32 v245, v42, v43
	v_cvt_pk_bf16_f32 v246, v44, v45
	v_cvt_pk_bf16_f32 v247, v46, v47
	global_store_dwordx2 v237, v[240:241], s[10:11] offset:0
	global_store_dwordx2 v237, v[242:243], s[10:11] offset:512
	global_store_dwordx2 v237, v[244:245], s[10:11] offset:1024
	global_store_dwordx2 v237, v[246:247], s[10:11] offset:1536
	s_add_u32 s10, s10, 0x880
	s_addc_u32 s11, s11, 0
	global_load_dwordx4 v[32:35], v236, s[8:9] offset:0
	global_load_dwordx4 v[36:39], v236, s[8:9] offset:1024
	global_load_dwordx4 v[40:43], v236, s[8:9] offset:2048
	global_load_dwordx4 v[44:47], v236, s[8:9] offset:3072
	s_add_u32 s8, s8, 0x1000
	s_addc_u32 s9, s9, 0
	s_waitcnt vmcnt(16)
	v_mul_f32_e32 v238, v0, v0
	v_mul_f32_e32 v239, v1, v1
	v_fmac_f32_e32 v238, v2, v2
	v_fmac_f32_e32 v239, v3, v3
	v_fmac_f32_e32 v238, v4, v4
	v_fmac_f32_e32 v239, v5, v5
	v_fmac_f32_e32 v238, v6, v6
	v_fmac_f32_e32 v239, v7, v7
	v_fmac_f32_e32 v238, v8, v8
	v_fmac_f32_e32 v239, v9, v9
	v_fmac_f32_e32 v238, v10, v10
	v_fmac_f32_e32 v239, v11, v11
	v_fmac_f32_e32 v238, v12, v12
	v_fmac_f32_e32 v239, v13, v13
	v_fmac_f32_e32 v238, v14, v14
	v_fmac_f32_e32 v239, v15, v15
	v_add_f32_e32 v238, v238, v239
	s_nop 1
	v_add_f32_dpp v238, v238, v238 quad_perm:[1,0,3,2] row_mask:0xf bank_mask:0xf bound_ctrl:1
	s_nop 1
	v_add_f32_dpp v238, v238, v238 quad_perm:[2,3,0,1] row_mask:0xf bank_mask:0xf bound_ctrl:1
	s_nop 1
	v_add_f32_dpp v238, v238, v238 row_ror:4 row_mask:0xf bank_mask:0xf bound_ctrl:1
	s_nop 1
	v_add_f32_dpp v238, v238, v238 row_ror:8 row_mask:0xf bank_mask:0xf bound_ctrl:1
	s_nop 1
	v_readlane_b32 s1, v238, 0
	v_readlane_b32 s3, v238, 16
	v_readlane_b32 s16, v238, 32
	v_readlane_b32 s17, v238, 48
	s_nop 1
	v_mov_b32_e32 v238, s1
	v_add_f32_e32 v238, s3, v238
	v_add_f32_e32 v238, s16, v238
	v_add_f32_e32 v238, s17, v238
	v_mov_b32_e32 v239, 0x358637bd
	v_fmac_f32_e32 v239, 0x3a800000, v238
	v_rsq_f32_e32 v238, v239
	s_nop 0
	v_mul_f32_e32 v0, v0, v238
	v_mul_f32_e32 v1, v1, v238
	v_mul_f32_e32 v2, v2, v238
	v_mul_f32_e32 v3, v3, v238
	v_mul_f32_e32 v4, v4, v238
	v_mul_f32_e32 v5, v5, v238
	v_mul_f32_e32 v6, v6, v238
	v_mul_f32_e32 v7, v7, v238
	v_mul_f32_e32 v8, v8, v238
	v_mul_f32_e32 v9, v9, v238
	v_mul_f32_e32 v10, v10, v238
	v_mul_f32_e32 v11, v11, v238
	v_mul_f32_e32 v12, v12, v238
	v_mul_f32_e32 v13, v13, v238
	v_mul_f32_e32 v14, v14, v238
	v_mul_f32_e32 v15, v15, v238
	v_mul_f32_e32 v0, v48, v0
	v_mul_f32_e32 v1, v49, v1
	v_mul_f32_e32 v2, v50, v2
	v_mul_f32_e32 v3, v51, v3
	v_mul_f32_e32 v4, v52, v4
	v_mul_f32_e32 v5, v53, v5
	v_mul_f32_e32 v6, v54, v6
	v_mul_f32_e32 v7, v55, v7
	v_mul_f32_e32 v8, v56, v8
	v_mul_f32_e32 v9, v57, v9
	v_mul_f32_e32 v10, v58, v10
	v_mul_f32_e32 v11, v59, v11
	v_mul_f32_e32 v12, v60, v12
	v_mul_f32_e32 v13, v61, v13
	v_mul_f32_e32 v14, v62, v14
	v_mul_f32_e32 v15, v63, v15
	v_fma_f32 v0, v194, v0, v64
	v_fma_f32 v1, v195, v1, v65
	v_fma_f32 v2, v196, v2, v66
	v_fma_f32 v3, v197, v3, v67
	v_fma_f32 v4, v198, v4, v68
	v_fma_f32 v5, v199, v5, v69
	v_fma_f32 v6, v200, v6, v70
	v_fma_f32 v7, v201, v7, v71
	v_fma_f32 v8, v202, v8, v72
	v_fma_f32 v9, v203, v9, v73
	v_fma_f32 v10, v204, v10, v74
	v_fma_f32 v11, v205, v11, v75
	v_fma_f32 v12, v206, v12, v76
	v_fma_f32 v13, v207, v13, v77
	v_fma_f32 v14, v208, v14, v78
	v_fma_f32 v15, v209, v15, v79
	v_cvt_pk_bf16_f32 v248, v0, v1
	v_cvt_pk_bf16_f32 v249, v2, v3
	v_cvt_pk_bf16_f32 v250, v4, v5
	v_cvt_pk_bf16_f32 v251, v6, v7
	v_cvt_pk_bf16_f32 v252, v8, v9
	v_cvt_pk_bf16_f32 v253, v10, v11
	v_cvt_pk_bf16_f32 v254, v12, v13
	v_cvt_pk_bf16_f32 v255, v14, v15
	global_store_dwordx2 v237, v[248:249], s[10:11] offset:0
	global_store_dwordx2 v237, v[250:251], s[10:11] offset:512
	global_store_dwordx2 v237, v[252:253], s[10:11] offset:1024
	global_store_dwordx2 v237, v[254:255], s[10:11] offset:1536
	s_add_u32 s10, s10, 0x880
	s_addc_u32 s11, s11, 0
	global_load_dwordx4 v[0:3], v236, s[8:9] offset:0
	global_load_dwordx4 v[4:7], v236, s[8:9] offset:1024
	global_load_dwordx4 v[8:11], v236, s[8:9] offset:2048
	global_load_dwordx4 v[12:15], v236, s[8:9] offset:3072
	s_add_u32 s8, s8, 0x1000
	s_addc_u32 s9, s9, 0
	s_waitcnt vmcnt(16)
	v_mul_f32_e32 v238, v16, v16
	v_mul_f32_e32 v239, v17, v17
	v_fmac_f32_e32 v238, v18, v18
	v_fmac_f32_e32 v239, v19, v19
	v_fmac_f32_e32 v238, v20, v20
	v_fmac_f32_e32 v239, v21, v21
	v_fmac_f32_e32 v238, v22, v22
	v_fmac_f32_e32 v239, v23, v23
	v_fmac_f32_e32 v238, v24, v24
	v_fmac_f32_e32 v239, v25, v25
	v_fmac_f32_e32 v238, v26, v26
	v_fmac_f32_e32 v239, v27, v27
	v_fmac_f32_e32 v238, v28, v28
	v_fmac_f32_e32 v239, v29, v29
	v_fmac_f32_e32 v238, v30, v30
	v_fmac_f32_e32 v239, v31, v31
	v_add_f32_e32 v238, v238, v239
	s_nop 1
	v_add_f32_dpp v238, v238, v238 quad_perm:[1,0,3,2] row_mask:0xf bank_mask:0xf bound_ctrl:1
	s_nop 1
	v_add_f32_dpp v238, v238, v238 quad_perm:[2,3,0,1] row_mask:0xf bank_mask:0xf bound_ctrl:1
	s_nop 1
	v_add_f32_dpp v238, v238, v238 row_ror:4 row_mask:0xf bank_mask:0xf bound_ctrl:1
	s_nop 1
	v_add_f32_dpp v238, v238, v238 row_ror:8 row_mask:0xf bank_mask:0xf bound_ctrl:1
	s_nop 1
	v_readlane_b32 s1, v238, 0
	v_readlane_b32 s3, v238, 16
	v_readlane_b32 s16, v238, 32
	v_readlane_b32 s17, v238, 48
	s_nop 1
	v_mov_b32_e32 v238, s1
	v_add_f32_e32 v238, s3, v238
	v_add_f32_e32 v238, s16, v238
	v_add_f32_e32 v238, s17, v238
	v_mov_b32_e32 v239, 0x358637bd
	v_fmac_f32_e32 v239, 0x3a800000, v238
	v_rsq_f32_e32 v238, v239
	s_nop 0
	v_mul_f32_e32 v16, v16, v238
	v_mul_f32_e32 v17, v17, v238
	v_mul_f32_e32 v18, v18, v238
	v_mul_f32_e32 v19, v19, v238
	v_mul_f32_e32 v20, v20, v238
	v_mul_f32_e32 v21, v21, v238
	v_mul_f32_e32 v22, v22, v238
	v_mul_f32_e32 v23, v23, v238
	v_mul_f32_e32 v24, v24, v238
	v_mul_f32_e32 v25, v25, v238
	v_mul_f32_e32 v26, v26, v238
	v_mul_f32_e32 v27, v27, v238
	v_mul_f32_e32 v28, v28, v238
	v_mul_f32_e32 v29, v29, v238
	v_mul_f32_e32 v30, v30, v238
	v_mul_f32_e32 v31, v31, v238
	v_mul_f32_e32 v16, v48, v16
	v_mul_f32_e32 v17, v49, v17
	v_mul_f32_e32 v18, v50, v18
	v_mul_f32_e32 v19, v51, v19
	v_mul_f32_e32 v20, v52, v20
	v_mul_f32_e32 v21, v53, v21
	v_mul_f32_e32 v22, v54, v22
	v_mul_f32_e32 v23, v55, v23
	v_mul_f32_e32 v24, v56, v24
	v_mul_f32_e32 v25, v57, v25
	v_mul_f32_e32 v26, v58, v26
	v_mul_f32_e32 v27, v59, v27
	v_mul_f32_e32 v28, v60, v28
	v_mul_f32_e32 v29, v61, v29
	v_mul_f32_e32 v30, v62, v30
	v_mul_f32_e32 v31, v63, v31
	v_fma_f32 v16, v194, v16, v64
	v_fma_f32 v17, v195, v17, v65
	v_fma_f32 v18, v196, v18, v66
	v_fma_f32 v19, v197, v19, v67
	v_fma_f32 v20, v198, v20, v68
	v_fma_f32 v21, v199, v21, v69
	v_fma_f32 v22, v200, v22, v70
	v_fma_f32 v23, v201, v23, v71
	v_fma_f32 v24, v202, v24, v72
	v_fma_f32 v25, v203, v25, v73
	v_fma_f32 v26, v204, v26, v74
	v_fma_f32 v27, v205, v27, v75
	v_fma_f32 v28, v206, v28, v76
	v_fma_f32 v29, v207, v29, v77
	v_fma_f32 v30, v208, v30, v78
	v_fma_f32 v31, v209, v31, v79
	v_cvt_pk_bf16_f32 v240, v16, v17
	v_cvt_pk_bf16_f32 v241, v18, v19
	v_cvt_pk_bf16_f32 v242, v20, v21
	v_cvt_pk_bf16_f32 v243, v22, v23
	v_cvt_pk_bf16_f32 v244, v24, v25
	v_cvt_pk_bf16_f32 v245, v26, v27
	v_cvt_pk_bf16_f32 v246, v28, v29
	v_cvt_pk_bf16_f32 v247, v30, v31
	global_store_dwordx2 v237, v[240:241], s[10:11] offset:0
	global_store_dwordx2 v237, v[242:243], s[10:11] offset:512
	global_store_dwordx2 v237, v[244:245], s[10:11] offset:1024
	global_store_dwordx2 v237, v[246:247], s[10:11] offset:1536
	s_add_u32 s10, s10, 0x880
	s_addc_u32 s11, s11, 0
	global_load_dwordx4 v[16:19], v236, s[8:9] offset:0
	global_load_dwordx4 v[20:23], v236, s[8:9] offset:1024
	global_load_dwordx4 v[24:27], v236, s[8:9] offset:2048
	global_load_dwordx4 v[28:31], v236, s[8:9] offset:3072
	s_add_u32 s8, s8, 0x1000
	s_addc_u32 s9, s9, 0
	s_waitcnt vmcnt(16)
	v_mul_f32_e32 v238, v32, v32
	v_mul_f32_e32 v239, v33, v33
	v_fmac_f32_e32 v238, v34, v34
	v_fmac_f32_e32 v239, v35, v35
	v_fmac_f32_e32 v238, v36, v36
	v_fmac_f32_e32 v239, v37, v37
	v_fmac_f32_e32 v238, v38, v38
	v_fmac_f32_e32 v239, v39, v39
	v_fmac_f32_e32 v238, v40, v40
	v_fmac_f32_e32 v239, v41, v41
	v_fmac_f32_e32 v238, v42, v42
	v_fmac_f32_e32 v239, v43, v43
	v_fmac_f32_e32 v238, v44, v44
	v_fmac_f32_e32 v239, v45, v45
	v_fmac_f32_e32 v238, v46, v46
	v_fmac_f32_e32 v239, v47, v47
	v_add_f32_e32 v238, v238, v239
	s_nop 1
	v_add_f32_dpp v238, v238, v238 quad_perm:[1,0,3,2] row_mask:0xf bank_mask:0xf bound_ctrl:1
	s_nop 1
	v_add_f32_dpp v238, v238, v238 quad_perm:[2,3,0,1] row_mask:0xf bank_mask:0xf bound_ctrl:1
	s_nop 1
	v_add_f32_dpp v238, v238, v238 row_ror:4 row_mask:0xf bank_mask:0xf bound_ctrl:1
	s_nop 1
	v_add_f32_dpp v238, v238, v238 row_ror:8 row_mask:0xf bank_mask:0xf bound_ctrl:1
	s_nop 1
	v_readlane_b32 s1, v238, 0
	v_readlane_b32 s3, v238, 16
	v_readlane_b32 s16, v238, 32
	v_readlane_b32 s17, v238, 48
	s_nop 1
	v_mov_b32_e32 v238, s1
	v_add_f32_e32 v238, s3, v238
	v_add_f32_e32 v238, s16, v238
	v_add_f32_e32 v238, s17, v238
	v_mov_b32_e32 v239, 0x358637bd
	v_fmac_f32_e32 v239, 0x3a800000, v238
	v_rsq_f32_e32 v238, v239
	s_nop 0
	v_mul_f32_e32 v32, v32, v238
	v_mul_f32_e32 v33, v33, v238
	v_mul_f32_e32 v34, v34, v238
	v_mul_f32_e32 v35, v35, v238
	v_mul_f32_e32 v36, v36, v238
	v_mul_f32_e32 v37, v37, v238
	v_mul_f32_e32 v38, v38, v238
	v_mul_f32_e32 v39, v39, v238
	v_mul_f32_e32 v40, v40, v238
	v_mul_f32_e32 v41, v41, v238
	v_mul_f32_e32 v42, v42, v238
	v_mul_f32_e32 v43, v43, v238
	v_mul_f32_e32 v44, v44, v238
	v_mul_f32_e32 v45, v45, v238
	v_mul_f32_e32 v46, v46, v238
	v_mul_f32_e32 v47, v47, v238
	v_mul_f32_e32 v32, v48, v32
	v_mul_f32_e32 v33, v49, v33
	v_mul_f32_e32 v34, v50, v34
	v_mul_f32_e32 v35, v51, v35
	v_mul_f32_e32 v36, v52, v36
	v_mul_f32_e32 v37, v53, v37
	v_mul_f32_e32 v38, v54, v38
	v_mul_f32_e32 v39, v55, v39
	v_mul_f32_e32 v40, v56, v40
	v_mul_f32_e32 v41, v57, v41
	v_mul_f32_e32 v42, v58, v42
	v_mul_f32_e32 v43, v59, v43
	v_mul_f32_e32 v44, v60, v44
	v_mul_f32_e32 v45, v61, v45
	v_mul_f32_e32 v46, v62, v46
	v_mul_f32_e32 v47, v63, v47
	v_fma_f32 v32, v194, v32, v64
	v_fma_f32 v33, v195, v33, v65
	v_fma_f32 v34, v196, v34, v66
	v_fma_f32 v35, v197, v35, v67
	v_fma_f32 v36, v198, v36, v68
	v_fma_f32 v37, v199, v37, v69
	v_fma_f32 v38, v200, v38, v70
	v_fma_f32 v39, v201, v39, v71
	v_fma_f32 v40, v202, v40, v72
	v_fma_f32 v41, v203, v41, v73
	v_fma_f32 v42, v204, v42, v74
	v_fma_f32 v43, v205, v43, v75
	v_fma_f32 v44, v206, v44, v76
	v_fma_f32 v45, v207, v45, v77
	v_fma_f32 v46, v208, v46, v78
	v_fma_f32 v47, v209, v47, v79
	v_cvt_pk_bf16_f32 v248, v32, v33
	v_cvt_pk_bf16_f32 v249, v34, v35
	v_cvt_pk_bf16_f32 v250, v36, v37
	v_cvt_pk_bf16_f32 v251, v38, v39
	v_cvt_pk_bf16_f32 v252, v40, v41
	v_cvt_pk_bf16_f32 v253, v42, v43
	v_cvt_pk_bf16_f32 v254, v44, v45
	v_cvt_pk_bf16_f32 v255, v46, v47
	global_store_dwordx2 v237, v[248:249], s[10:11] offset:0
	global_store_dwordx2 v237, v[250:251], s[10:11] offset:512
	global_store_dwordx2 v237, v[252:253], s[10:11] offset:1024
	global_store_dwordx2 v237, v[254:255], s[10:11] offset:1536
	s_add_u32 s10, s10, 0x880
	s_addc_u32 s11, s11, 0
	s_waitcnt vmcnt(12)
	v_mul_f32_e32 v238, v0, v0
	v_mul_f32_e32 v239, v1, v1
	v_fmac_f32_e32 v238, v2, v2
	v_fmac_f32_e32 v239, v3, v3
	v_fmac_f32_e32 v238, v4, v4
	v_fmac_f32_e32 v239, v5, v5
	v_fmac_f32_e32 v238, v6, v6
	v_fmac_f32_e32 v239, v7, v7
	v_fmac_f32_e32 v238, v8, v8
	v_fmac_f32_e32 v239, v9, v9
	v_fmac_f32_e32 v238, v10, v10
	v_fmac_f32_e32 v239, v11, v11
	v_fmac_f32_e32 v238, v12, v12
	v_fmac_f32_e32 v239, v13, v13
	v_fmac_f32_e32 v238, v14, v14
	v_fmac_f32_e32 v239, v15, v15
	v_add_f32_e32 v238, v238, v239
	s_nop 1
	v_add_f32_dpp v238, v238, v238 quad_perm:[1,0,3,2] row_mask:0xf bank_mask:0xf bound_ctrl:1
	s_nop 1
	v_add_f32_dpp v238, v238, v238 quad_perm:[2,3,0,1] row_mask:0xf bank_mask:0xf bound_ctrl:1
	s_nop 1
	v_add_f32_dpp v238, v238, v238 row_ror:4 row_mask:0xf bank_mask:0xf bound_ctrl:1
	s_nop 1
	v_add_f32_dpp v238, v238, v238 row_ror:8 row_mask:0xf bank_mask:0xf bound_ctrl:1
	s_nop 1
	v_readlane_b32 s1, v238, 0
	v_readlane_b32 s3, v238, 16
	v_readlane_b32 s16, v238, 32
	v_readlane_b32 s17, v238, 48
	s_nop 1
	v_mov_b32_e32 v238, s1
	v_add_f32_e32 v238, s3, v238
	v_add_f32_e32 v238, s16, v238
	v_add_f32_e32 v238, s17, v238
	v_mov_b32_e32 v239, 0x358637bd
	v_fmac_f32_e32 v239, 0x3a800000, v238
	v_rsq_f32_e32 v238, v239
	s_nop 0
	v_mul_f32_e32 v0, v0, v238
	v_mul_f32_e32 v1, v1, v238
	v_mul_f32_e32 v2, v2, v238
	v_mul_f32_e32 v3, v3, v238
	v_mul_f32_e32 v4, v4, v238
	v_mul_f32_e32 v5, v5, v238
	v_mul_f32_e32 v6, v6, v238
	v_mul_f32_e32 v7, v7, v238
	v_mul_f32_e32 v8, v8, v238
	v_mul_f32_e32 v9, v9, v238
	v_mul_f32_e32 v10, v10, v238
	v_mul_f32_e32 v11, v11, v238
	v_mul_f32_e32 v12, v12, v238
	v_mul_f32_e32 v13, v13, v238
	v_mul_f32_e32 v14, v14, v238
	v_mul_f32_e32 v15, v15, v238
	v_mul_f32_e32 v0, v48, v0
	v_mul_f32_e32 v1, v49, v1
	v_mul_f32_e32 v2, v50, v2
	v_mul_f32_e32 v3, v51, v3
	v_mul_f32_e32 v4, v52, v4
	v_mul_f32_e32 v5, v53, v5
	v_mul_f32_e32 v6, v54, v6
	v_mul_f32_e32 v7, v55, v7
	v_mul_f32_e32 v8, v56, v8
	v_mul_f32_e32 v9, v57, v9
	v_mul_f32_e32 v10, v58, v10
	v_mul_f32_e32 v11, v59, v11
	v_mul_f32_e32 v12, v60, v12
	v_mul_f32_e32 v13, v61, v13
	v_mul_f32_e32 v14, v62, v14
	v_mul_f32_e32 v15, v63, v15
	v_fma_f32 v0, v194, v0, v64
	v_fma_f32 v1, v195, v1, v65
	v_fma_f32 v2, v196, v2, v66
	v_fma_f32 v3, v197, v3, v67
	v_fma_f32 v4, v198, v4, v68
	v_fma_f32 v5, v199, v5, v69
	v_fma_f32 v6, v200, v6, v70
	v_fma_f32 v7, v201, v7, v71
	v_fma_f32 v8, v202, v8, v72
	v_fma_f32 v9, v203, v9, v73
	v_fma_f32 v10, v204, v10, v74
	v_fma_f32 v11, v205, v11, v75
	v_fma_f32 v12, v206, v12, v76
	v_fma_f32 v13, v207, v13, v77
	v_fma_f32 v14, v208, v14, v78
	v_fma_f32 v15, v209, v15, v79
	v_cvt_pk_bf16_f32 v240, v0, v1
	v_cvt_pk_bf16_f32 v241, v2, v3
	v_cvt_pk_bf16_f32 v242, v4, v5
	v_cvt_pk_bf16_f32 v243, v6, v7
	v_cvt_pk_bf16_f32 v244, v8, v9
	v_cvt_pk_bf16_f32 v245, v10, v11
	v_cvt_pk_bf16_f32 v246, v12, v13
	v_cvt_pk_bf16_f32 v247, v14, v15
	global_store_dwordx2 v237, v[240:241], s[10:11] offset:0
	global_store_dwordx2 v237, v[242:243], s[10:11] offset:512
	global_store_dwordx2 v237, v[244:245], s[10:11] offset:1024
	global_store_dwordx2 v237, v[246:247], s[10:11] offset:1536
	s_add_u32 s10, s10, 0x880
	s_addc_u32 s11, s11, 0
	s_waitcnt vmcnt(8)
	v_mul_f32_e32 v238, v16, v16
	v_mul_f32_e32 v239, v17, v17
	v_fmac_f32_e32 v238, v18, v18
	v_fmac_f32_e32 v239, v19, v19
	v_fmac_f32_e32 v238, v20, v20
	v_fmac_f32_e32 v239, v21, v21
	v_fmac_f32_e32 v238, v22, v22
	v_fmac_f32_e32 v239, v23, v23
	v_fmac_f32_e32 v238, v24, v24
	v_fmac_f32_e32 v239, v25, v25
	v_fmac_f32_e32 v238, v26, v26
	v_fmac_f32_e32 v239, v27, v27
	v_fmac_f32_e32 v238, v28, v28
	v_fmac_f32_e32 v239, v29, v29
	v_fmac_f32_e32 v238, v30, v30
	v_fmac_f32_e32 v239, v31, v31
	v_add_f32_e32 v238, v238, v239
	s_nop 1
	v_add_f32_dpp v238, v238, v238 quad_perm:[1,0,3,2] row_mask:0xf bank_mask:0xf bound_ctrl:1
	s_nop 1
	v_add_f32_dpp v238, v238, v238 quad_perm:[2,3,0,1] row_mask:0xf bank_mask:0xf bound_ctrl:1
	s_nop 1
	v_add_f32_dpp v238, v238, v238 row_ror:4 row_mask:0xf bank_mask:0xf bound_ctrl:1
	s_nop 1
	v_add_f32_dpp v238, v238, v238 row_ror:8 row_mask:0xf bank_mask:0xf bound_ctrl:1
	s_nop 1
	v_readlane_b32 s1, v238, 0
	v_readlane_b32 s3, v238, 16
	v_readlane_b32 s16, v238, 32
	v_readlane_b32 s17, v238, 48
	s_nop 1
	v_mov_b32_e32 v238, s1
	v_add_f32_e32 v238, s3, v238
	v_add_f32_e32 v238, s16, v238
	v_add_f32_e32 v238, s17, v238
	v_mov_b32_e32 v239, 0x358637bd
	v_fmac_f32_e32 v239, 0x3a800000, v238
	v_rsq_f32_e32 v238, v239
	s_nop 0
	v_mul_f32_e32 v16, v16, v238
	v_mul_f32_e32 v17, v17, v238
	v_mul_f32_e32 v18, v18, v238
	v_mul_f32_e32 v19, v19, v238
	v_mul_f32_e32 v20, v20, v238
	v_mul_f32_e32 v21, v21, v238
	v_mul_f32_e32 v22, v22, v238
	v_mul_f32_e32 v23, v23, v238
	v_mul_f32_e32 v24, v24, v238
	v_mul_f32_e32 v25, v25, v238
	v_mul_f32_e32 v26, v26, v238
	v_mul_f32_e32 v27, v27, v238
	v_mul_f32_e32 v28, v28, v238
	v_mul_f32_e32 v29, v29, v238
	v_mul_f32_e32 v30, v30, v238
	v_mul_f32_e32 v31, v31, v238
	v_mul_f32_e32 v16, v48, v16
	v_mul_f32_e32 v17, v49, v17
	v_mul_f32_e32 v18, v50, v18
	v_mul_f32_e32 v19, v51, v19
	v_mul_f32_e32 v20, v52, v20
	v_mul_f32_e32 v21, v53, v21
	v_mul_f32_e32 v22, v54, v22
	v_mul_f32_e32 v23, v55, v23
	v_mul_f32_e32 v24, v56, v24
	v_mul_f32_e32 v25, v57, v25
	v_mul_f32_e32 v26, v58, v26
	v_mul_f32_e32 v27, v59, v27
	v_mul_f32_e32 v28, v60, v28
	v_mul_f32_e32 v29, v61, v29
	v_mul_f32_e32 v30, v62, v30
	v_mul_f32_e32 v31, v63, v31
	v_fma_f32 v16, v194, v16, v64
	v_fma_f32 v17, v195, v17, v65
	v_fma_f32 v18, v196, v18, v66
	v_fma_f32 v19, v197, v19, v67
	v_fma_f32 v20, v198, v20, v68
	v_fma_f32 v21, v199, v21, v69
	v_fma_f32 v22, v200, v22, v70
	v_fma_f32 v23, v201, v23, v71
	v_fma_f32 v24, v202, v24, v72
	v_fma_f32 v25, v203, v25, v73
	v_fma_f32 v26, v204, v26, v74
	v_fma_f32 v27, v205, v27, v75
	v_fma_f32 v28, v206, v28, v76
	v_fma_f32 v29, v207, v29, v77
	v_fma_f32 v30, v208, v30, v78
	v_fma_f32 v31, v209, v31, v79
	v_cvt_pk_bf16_f32 v248, v16, v17
	v_cvt_pk_bf16_f32 v249, v18, v19
	v_cvt_pk_bf16_f32 v250, v20, v21
	v_cvt_pk_bf16_f32 v251, v22, v23
	v_cvt_pk_bf16_f32 v252, v24, v25
	v_cvt_pk_bf16_f32 v253, v26, v27
	v_cvt_pk_bf16_f32 v254, v28, v29
	v_cvt_pk_bf16_f32 v255, v30, v31
	global_store_dwordx2 v237, v[248:249], s[10:11] offset:0
	global_store_dwordx2 v237, v[250:251], s[10:11] offset:512
	global_store_dwordx2 v237, v[252:253], s[10:11] offset:1024
	global_store_dwordx2 v237, v[254:255], s[10:11] offset:1536
	s_add_u32 s10, s10, 0x880
	s_addc_u32 s11, s11, 0
	s_cmp_lg_u32 s19, 31
	s_cbranch_scc1 .Lnl0_end
	v_lshrrev_b32_e32 v238, 6, v174
	s_nop 0
	v_readfirstlane_b32 s1, v238
	s_lshl_b32 s0, s18, 3
	s_add_i32 s0, s0, s1
	s_lshl_b32 s0, s0, 1
	s_add_i32 s1, s0, 0x4000
	s_lshl_b32 s8, s1, 12
	s_add_u32 s8, s82, s8
	s_addc_u32 s9, s83, 0
	s_mul_i32 s10, s1, 0x880
	s_add_u32 s10, s10, 0x3018000
	s_add_u32 s10, s84, s10
	s_addc_u32 s11, s85, 0
	s_mul_i32 s3, s0, 0x6000
	s_add_u32 s12, s84, 0x52bb880
	s_addc_u32 s13, s85, 0
	s_add_u32 s12, s12, s3
	s_addc_u32 s13, s13, 0
	s_add_u32 s14, s12, 0x1000
	s_addc_u32 s15, s13, 0
	global_load_dwordx4 v[32:35], v236, s[8:9] offset:0
	global_load_dwordx4 v[36:39], v236, s[8:9] offset:1024
	global_load_dwordx4 v[40:43], v236, s[8:9] offset:2048
	global_load_dwordx4 v[44:47], v236, s[8:9] offset:3072
	s_add_u32 s8, s8, 0x1000
	s_addc_u32 s9, s9, 0
	global_load_dwordx4 v[80:83], v236, s[12:13] offset:0
	global_load_dwordx4 v[84:87], v236, s[12:13] offset:1024
	global_load_dwordx4 v[88:91], v236, s[12:13] offset:2048
	global_load_dwordx4 v[92:95], v236, s[12:13] offset:3072
	global_load_dwordx4 v[210:213], v236, s[14:15] offset:0
	global_load_dwordx4 v[214:217], v236, s[14:15] offset:1024
	global_load_dwordx4 v[218:221], v236, s[14:15] offset:2048
	global_load_dwordx4 v[222:225], v236, s[14:15] offset:3072
	s_add_i32 s0, s0, 1
	s_waitcnt vmcnt(8)
	v_mul_f32_e32 v238, v32, v32
	v_mul_f32_e32 v239, v33, v33
	v_fmac_f32_e32 v238, v34, v34
	v_fmac_f32_e32 v239, v35, v35
	v_fmac_f32_e32 v238, v36, v36
	v_fmac_f32_e32 v239, v37, v37
	v_fmac_f32_e32 v238, v38, v38
	v_fmac_f32_e32 v239, v39, v39
	v_fmac_f32_e32 v238, v40, v40
	v_fmac_f32_e32 v239, v41, v41
	v_fmac_f32_e32 v238, v42, v42
	v_fmac_f32_e32 v239, v43, v43
	v_fmac_f32_e32 v238, v44, v44
	v_fmac_f32_e32 v239, v45, v45
	v_fmac_f32_e32 v238, v46, v46
	v_fmac_f32_e32 v239, v47, v47
	v_add_f32_e32 v238, v238, v239
	s_nop 1
	v_add_f32_dpp v238, v238, v238 quad_perm:[1,0,3,2] row_mask:0xf bank_mask:0xf bound_ctrl:1
	s_nop 1
	v_add_f32_dpp v238, v238, v238 quad_perm:[2,3,0,1] row_mask:0xf bank_mask:0xf bound_ctrl:1
	s_nop 1
	v_add_f32_dpp v238, v238, v238 row_ror:4 row_mask:0xf bank_mask:0xf bound_ctrl:1
	s_nop 1
	v_add_f32_dpp v238, v238, v238 row_ror:8 row_mask:0xf bank_mask:0xf bound_ctrl:1
	s_nop 1
	v_readlane_b32 s1, v238, 0
	v_readlane_b32 s3, v238, 16
	v_readlane_b32 s16, v238, 32
	v_readlane_b32 s17, v238, 48
	s_nop 1
	v_mov_b32_e32 v238, s1
	v_add_f32_e32 v238, s3, v238
	v_add_f32_e32 v238, s16, v238
	v_add_f32_e32 v238, s17, v238
	v_mov_b32_e32 v239, 0x358637bd
	v_fmac_f32_e32 v239, 0x3a800000, v238
	v_rsq_f32_e32 v238, v239
	s_nop 0
	s_waitcnt vmcnt(0)
	v_add_f32_e32 v210, 1.0, v210
	v_add_f32_e32 v211, 1.0, v211
	v_add_f32_e32 v212, 1.0, v212
	v_add_f32_e32 v213, 1.0, v213
	v_add_f32_e32 v214, 1.0, v214
	v_add_f32_e32 v215, 1.0, v215
	v_add_f32_e32 v216, 1.0, v216
	v_add_f32_e32 v217, 1.0, v217
	v_add_f32_e32 v218, 1.0, v218
	v_add_f32_e32 v219, 1.0, v219
	v_add_f32_e32 v220, 1.0, v220
	v_add_f32_e32 v221, 1.0, v221
	v_add_f32_e32 v222, 1.0, v222
	v_add_f32_e32 v223, 1.0, v223
	v_add_f32_e32 v224, 1.0, v224
	v_add_f32_e32 v225, 1.0, v225
	v_mul_f32_e32 v32, v32, v238
	v_mul_f32_e32 v33, v33, v238
	v_mul_f32_e32 v34, v34, v238
	v_mul_f32_e32 v35, v35, v238
	v_mul_f32_e32 v36, v36, v238
	v_mul_f32_e32 v37, v37, v238
	v_mul_f32_e32 v38, v38, v238
	v_mul_f32_e32 v39, v39, v238
	v_mul_f32_e32 v40, v40, v238
	v_mul_f32_e32 v41, v41, v238
	v_mul_f32_e32 v42, v42, v238
	v_mul_f32_e32 v43, v43, v238
	v_mul_f32_e32 v44, v44, v238
	v_mul_f32_e32 v45, v45, v238
	v_mul_f32_e32 v46, v46, v238
	v_mul_f32_e32 v47, v47, v238
	v_mul_f32_e32 v32, v48, v32
	v_mul_f32_e32 v33, v49, v33
	v_mul_f32_e32 v34, v50, v34
	v_mul_f32_e32 v35, v51, v35
	v_mul_f32_e32 v36, v52, v36
	v_mul_f32_e32 v37, v53, v37
	v_mul_f32_e32 v38, v54, v38
	v_mul_f32_e32 v39, v55, v39
	v_mul_f32_e32 v40, v56, v40
	v_mul_f32_e32 v41, v57, v41
	v_mul_f32_e32 v42, v58, v42
	v_mul_f32_e32 v43, v59, v43
	v_mul_f32_e32 v44, v60, v44
	v_mul_f32_e32 v45, v61, v45
	v_mul_f32_e32 v46, v62, v46
	v_mul_f32_e32 v47, v63, v47
	v_fma_f32 v32, v210, v32, v80
	v_fma_f32 v33, v211, v33, v81
	v_fma_f32 v34, v212, v34, v82
	v_fma_f32 v35, v213, v35, v83
	v_fma_f32 v36, v214, v36, v84
	v_fma_f32 v37, v215, v37, v85
	v_fma_f32 v38, v216, v38, v86
	v_fma_f32 v39, v217, v39, v87
	v_fma_f32 v40, v218, v40, v88
	v_fma_f32 v41, v219, v41, v89
	v_fma_f32 v42, v220, v42, v90
	v_fma_f32 v43, v221, v43, v91
	v_fma_f32 v44, v222, v44, v92
	v_fma_f32 v45, v223, v45, v93
	v_fma_f32 v46, v224, v46, v94
	v_fma_f32 v47, v225, v47, v95
	v_cvt_pk_bf16_f32 v240, v32, v33
	v_cvt_pk_bf16_f32 v241, v34, v35
	v_cvt_pk_bf16_f32 v242, v36, v37
	v_cvt_pk_bf16_f32 v243, v38, v39
	v_cvt_pk_bf16_f32 v244, v40, v41
	v_cvt_pk_bf16_f32 v245, v42, v43
	v_cvt_pk_bf16_f32 v246, v44, v45
	v_cvt_pk_bf16_f32 v247, v46, v47
	global_store_dwordx2 v237, v[240:241], s[10:11] offset:0
	global_store_dwordx2 v237, v[242:243], s[10:11] offset:512
	global_store_dwordx2 v237, v[244:245], s[10:11] offset:1024
	global_store_dwordx2 v237, v[246:247], s[10:11] offset:1536
	s_add_u32 s10, s10, 0x880
	s_addc_u32 s11, s11, 0
	s_mul_i32 s3, s0, 0x6000
	s_add_u32 s12, s84, 0x52bb880
	s_addc_u32 s13, s85, 0
	s_add_u32 s12, s12, s3
	s_addc_u32 s13, s13, 0
	s_add_u32 s14, s12, 0x1000
	s_addc_u32 s15, s13, 0
	global_load_dwordx4 v[0:3], v236, s[8:9] offset:0
	global_load_dwordx4 v[4:7], v236, s[8:9] offset:1024
	global_load_dwordx4 v[8:11], v236, s[8:9] offset:2048
	global_load_dwordx4 v[12:15], v236, s[8:9] offset:3072
	s_add_u32 s8, s8, 0x1000
	s_addc_u32 s9, s9, 0
	global_load_dwordx4 v[64:67], v236, s[12:13] offset:0
	global_load_dwordx4 v[68:71], v236, s[12:13] offset:1024
	global_load_dwordx4 v[72:75], v236, s[12:13] offset:2048
	global_load_dwordx4 v[76:79], v236, s[12:13] offset:3072
	global_load_dwordx4 v[194:197], v236, s[14:15] offset:0
	global_load_dwordx4 v[198:201], v236, s[14:15] offset:1024
	global_load_dwordx4 v[202:205], v236, s[14:15] offset:2048
	global_load_dwordx4 v[206:209], v236, s[14:15] offset:3072
	s_add_i32 s0, s0, 1
	s_waitcnt vmcnt(8)
	v_mul_f32_e32 v238, v0, v0
	v_mul_f32_e32 v239, v1, v1
	v_fmac_f32_e32 v238, v2, v2
	v_fmac_f32_e32 v239, v3, v3
	v_fmac_f32_e32 v238, v4, v4
	v_fmac_f32_e32 v239, v5, v5
	v_fmac_f32_e32 v238, v6, v6
	v_fmac_f32_e32 v239, v7, v7
	v_fmac_f32_e32 v238, v8, v8
	v_fmac_f32_e32 v239, v9, v9
	v_fmac_f32_e32 v238, v10, v10
	v_fmac_f32_e32 v239, v11, v11
	v_fmac_f32_e32 v238, v12, v12
	v_fmac_f32_e32 v239, v13, v13
	v_fmac_f32_e32 v238, v14, v14
	v_fmac_f32_e32 v239, v15, v15
	v_add_f32_e32 v238, v238, v239
	s_nop 1
	v_add_f32_dpp v238, v238, v238 quad_perm:[1,0,3,2] row_mask:0xf bank_mask:0xf bound_ctrl:1
	s_nop 1
	v_add_f32_dpp v238, v238, v238 quad_perm:[2,3,0,1] row_mask:0xf bank_mask:0xf bound_ctrl:1
	s_nop 1
	v_add_f32_dpp v238, v238, v238 row_ror:4 row_mask:0xf bank_mask:0xf bound_ctrl:1
	s_nop 1
	v_add_f32_dpp v238, v238, v238 row_ror:8 row_mask:0xf bank_mask:0xf bound_ctrl:1
	s_nop 1
	v_readlane_b32 s1, v238, 0
	v_readlane_b32 s3, v238, 16
	v_readlane_b32 s16, v238, 32
	v_readlane_b32 s17, v238, 48
	s_nop 1
	v_mov_b32_e32 v238, s1
	v_add_f32_e32 v238, s3, v238
	v_add_f32_e32 v238, s16, v238
	v_add_f32_e32 v238, s17, v238
	v_mov_b32_e32 v239, 0x358637bd
	v_fmac_f32_e32 v239, 0x3a800000, v238
	v_rsq_f32_e32 v238, v239
	s_nop 0
	s_waitcnt vmcnt(0)
	v_add_f32_e32 v194, 1.0, v194
	v_add_f32_e32 v195, 1.0, v195
	v_add_f32_e32 v196, 1.0, v196
	v_add_f32_e32 v197, 1.0, v197
	v_add_f32_e32 v198, 1.0, v198
	v_add_f32_e32 v199, 1.0, v199
	v_add_f32_e32 v200, 1.0, v200
	v_add_f32_e32 v201, 1.0, v201
	v_add_f32_e32 v202, 1.0, v202
	v_add_f32_e32 v203, 1.0, v203
	v_add_f32_e32 v204, 1.0, v204
	v_add_f32_e32 v205, 1.0, v205
	v_add_f32_e32 v206, 1.0, v206
	v_add_f32_e32 v207, 1.0, v207
	v_add_f32_e32 v208, 1.0, v208
	v_add_f32_e32 v209, 1.0, v209
	v_mul_f32_e32 v0, v0, v238
	v_mul_f32_e32 v1, v1, v238
	v_mul_f32_e32 v2, v2, v238
	v_mul_f32_e32 v3, v3, v238
	v_mul_f32_e32 v4, v4, v238
	v_mul_f32_e32 v5, v5, v238
	v_mul_f32_e32 v6, v6, v238
	v_mul_f32_e32 v7, v7, v238
	v_mul_f32_e32 v8, v8, v238
	v_mul_f32_e32 v9, v9, v238
	v_mul_f32_e32 v10, v10, v238
	v_mul_f32_e32 v11, v11, v238
	v_mul_f32_e32 v12, v12, v238
	v_mul_f32_e32 v13, v13, v238
	v_mul_f32_e32 v14, v14, v238
	v_mul_f32_e32 v15, v15, v238
	v_mul_f32_e32 v0, v48, v0
	v_mul_f32_e32 v1, v49, v1
	v_mul_f32_e32 v2, v50, v2
	v_mul_f32_e32 v3, v51, v3
	v_mul_f32_e32 v4, v52, v4
	v_mul_f32_e32 v5, v53, v5
	v_mul_f32_e32 v6, v54, v6
	v_mul_f32_e32 v7, v55, v7
	v_mul_f32_e32 v8, v56, v8
	v_mul_f32_e32 v9, v57, v9
	v_mul_f32_e32 v10, v58, v10
	v_mul_f32_e32 v11, v59, v11
	v_mul_f32_e32 v12, v60, v12
	v_mul_f32_e32 v13, v61, v13
	v_mul_f32_e32 v14, v62, v14
	v_mul_f32_e32 v15, v63, v15
	v_fma_f32 v0, v194, v0, v64
	v_fma_f32 v1, v195, v1, v65
	v_fma_f32 v2, v196, v2, v66
	v_fma_f32 v3, v197, v3, v67
	v_fma_f32 v4, v198, v4, v68
	v_fma_f32 v5, v199, v5, v69
	v_fma_f32 v6, v200, v6, v70
	v_fma_f32 v7, v201, v7, v71
	v_fma_f32 v8, v202, v8, v72
	v_fma_f32 v9, v203, v9, v73
	v_fma_f32 v10, v204, v10, v74
	v_fma_f32 v11, v205, v11, v75
	v_fma_f32 v12, v206, v12, v76
	v_fma_f32 v13, v207, v13, v77
	v_fma_f32 v14, v208, v14, v78
	v_fma_f32 v15, v209, v15, v79
	v_cvt_pk_bf16_f32 v248, v0, v1
	v_cvt_pk_bf16_f32 v249, v2, v3
	v_cvt_pk_bf16_f32 v250, v4, v5
	v_cvt_pk_bf16_f32 v251, v6, v7
	v_cvt_pk_bf16_f32 v252, v8, v9
	v_cvt_pk_bf16_f32 v253, v10, v11
	v_cvt_pk_bf16_f32 v254, v12, v13
	v_cvt_pk_bf16_f32 v255, v14, v15
	global_store_dwordx2 v237, v[248:249], s[10:11] offset:0
	global_store_dwordx2 v237, v[250:251], s[10:11] offset:512
	global_store_dwordx2 v237, v[252:253], s[10:11] offset:1024
	global_store_dwordx2 v237, v[254:255], s[10:11] offset:1536
	s_add_u32 s10, s10, 0x880
	s_addc_u32 s11, s11, 0
.Lnl0_end:
	s_branch .LBB0_1525
.Lnl0_orig:
	v_lshlrev_b32_e32 v0, 2, v32
	v_ashrrev_i32_e32 v55, 31, v54
	v_and_b32_e32 v34, 0xfc, v0
	s_waitcnt vmcnt(2)
	v_lshlrev_b64 v[16:17], 12, v[54:55]
	v_mov_b32_e32 v49, 0
	v_lshlrev_b32_e32 v48, 2, v34
	v_readlane_b32 s8, v192, 11
	v_lshl_add_u64 v[16:17], s[82:83], 0, v[16:17]
	v_readlane_b32 s10, v192, 13
	v_readlane_b32 s11, v192, 14
	v_lshl_add_u64 v[16:17], v[16:17], 0, v[48:49]
	s_nop 3
	global_load_dwordx4 v[0:3], v48, s[10:11]
	global_load_dwordx4 v[4:7], v48, s[10:11] offset:1024
	global_load_dwordx4 v[8:11], v48, s[10:11] offset:2048
	global_load_dwordx4 v[12:15], v48, s[10:11] offset:3072
	global_load_dwordx4 v[28:31], v[16:17], off
	global_load_dwordx4 v[24:27], v[16:17], off offset:1024
	global_load_dwordx4 v[20:23], v[16:17], off offset:2048
	s_nop 0
	global_load_dwordx4 v[16:19], v[16:17], off offset:3072
	v_mbcnt_hi_u32_b32 v33, -1, v175
	v_and_b32_e32 v35, 64, v33
	v_add_u32_e32 v35, 64, v35
	v_xor_b32_e32 v36, 32, v33
	v_cmp_lt_i32_e32 vcc, v36, v35
	s_movk_i32 s0, 0x880
	v_readlane_b32 s9, v192, 12
	v_cndmask_b32_e32 v36, v33, v36, vcc
	v_lshlrev_b32_e32 v55, 2, v36
	v_xor_b32_e32 v36, 16, v33
	v_cmp_lt_i32_e32 vcc, v36, v35
	v_readlane_b32 s12, v192, 15
	v_readlane_b32 s13, v192, 16
	v_cndmask_b32_e32 v36, v33, v36, vcc
	v_lshlrev_b32_e32 v56, 2, v36
	v_xor_b32_e32 v36, 8, v33
	v_cmp_lt_i32_e32 vcc, v36, v35
	v_readlane_b32 s14, v192, 17
	v_readlane_b32 s15, v192, 18
	v_cndmask_b32_e32 v36, v33, v36, vcc
	v_lshlrev_b32_e32 v57, 2, v36
	v_xor_b32_e32 v36, 4, v33
	v_cmp_lt_i32_e32 vcc, v36, v35
	v_readlane_b32 s18, v192, 21
	v_readlane_b32 s19, v192, 22
	v_cndmask_b32_e32 v36, v33, v36, vcc
	v_lshlrev_b32_e32 v58, 2, v36
	v_xor_b32_e32 v36, 2, v33
	v_cmp_lt_i32_e32 vcc, v36, v35
	v_readlane_b32 s20, v192, 23
	v_readlane_b32 s21, v192, 24
	v_cndmask_b32_e32 v36, v33, v36, vcc
	v_lshlrev_b32_e32 v59, 2, v36
	v_xor_b32_e32 v36, 1, v33
	v_cmp_lt_i32_e32 vcc, v36, v35
	v_and_b32_e32 v35, 63, v32
	v_lshlrev_b32_e32 v48, 3, v35
	v_cndmask_b32_e32 v33, v33, v36, vcc
	v_lshlrev_b32_e32 v60, 2, v33
	v_mad_i64_i32 v[32:33], s[0:1], v54, s0, v[48:49]
	v_lshl_add_u64 v[32:33], s[84:85], 0, v[32:33]
	s_mov_b64 s[0:1], 0x3018000
	v_lshl_add_u64 v[50:51], v[32:33], 0, s[0:1]
	v_add_u32_e32 v32, s74, v54
	v_ashrrev_i32_e32 v33, 31, v32
	v_lshlrev_b64 v[32:33], 12, v[32:33]
	s_ashr_i32 s75, s74, 31
	v_lshl_or_b32 v32, v35, 4, v32
	v_lshl_add_u64 v[52:53], s[82:83], 0, v[32:33]
	s_lshl_b64 s[8:9], s[74:75], 12
	s_mov_b64 s[10:11], 0
	s_movk_i32 s18, 0x407f
	s_movk_i32 s19, 0x4000
	s_movk_i32 s20, 0x6000
	v_lshlrev_b32_e32 v48, 2, v34
	s_mov_b64 s[12:13], 0x3000
	s_mov_b64 s[14:15], 0x4000
	v_mov_b32_e32 v61, 0x358637bd
	s_mov_b32 s21, 0x800000
	v_readlane_b32 s16, v192, 19
	v_readlane_b32 s17, v192, 20
	v_readlane_b32 s22, v192, 25
	v_readlane_b32 s23, v192, 26
	s_branch .LBB0_1523

.LBB0_1853:
	s_or_b64 exec, exec, s[0:1]
	v_mov_b32_e32 v32, v174
	s_waitcnt lgkmcnt(0)
	s_barrier
	s_movk_i32 s3, 0x4080
	v_ashrrev_i32_e32 v0, 6, v32
	v_add_u32_e32 v54, s94, v0
	v_cmp_gt_i32_e32 vcc, s3, v54
	s_and_saveexec_b64 s[4:5], vcc
	s_cbranch_execz .LBB0_1858
	s_cmpk_lg_i32 s86, 0x100
	s_cbranch_scc1 .Lnl1_orig
	s_waitcnt vmcnt(0)
	v_readlane_b32 s20, v192, 11
	v_readlane_b32 s21, v192, 12
	v_lshrrev_b32_e32 v238, 6, v174
	s_nop 1
	v_readfirstlane_b32 s1, v238
	v_and_b32_e32 v236, 63, v174
	v_lshlrev_b32_e32 v237, 3, v236
	v_lshlrev_b32_e32 v236, 4, v236
	s_lshr_b32 s3, s94, 3
	s_and_b32 s18, s3, 7
	s_lshr_b32 s19, s3, 3
	s_lshl_b32 s0, s18, 11
	s_lshl_b32 s3, s19, 6
	s_add_i32 s0, s0, s3
	s_lshl_b32 s3, s1, 3
	s_add_i32 s0, s0, s3
	s_add_u32 s20, s20, 0x1000
	s_addc_u32 s21, s21, 0
	global_load_dwordx4 v[48:51], v236, s[20:21] offset:0
	global_load_dwordx4 v[52:55], v236, s[20:21] offset:1024
	global_load_dwordx4 v[56:59], v236, s[20:21] offset:2048
	global_load_dwordx4 v[60:63], v236, s[20:21] offset:3072
	s_lshl_b32 s8, s0, 12
	s_add_u32 s8, s82, s8
	s_addc_u32 s9, s83, 0
	s_mul_i32 s10, s0, 0x880
	s_add_u32 s10, s10, 0x3018000
	s_add_u32 s10, s84, s10
	s_addc_u32 s11, s85, 0
	s_lshr_b32 s1, s0, 12
	s_mul_i32 s3, s1, 0x6000
	s_add_u32 s12, s84, 0x55b8880
	s_addc_u32 s13, s85, 0
	s_add_u32 s12, s12, s3
	s_addc_u32 s13, s13, 0
	s_add_u32 s14, s12, 0x1000
	s_addc_u32 s15, s13, 0
	global_load_dwordx4 v[0:3], v236, s[8:9] offset:0
	global_load_dwordx4 v[4:7], v236, s[8:9] offset:1024
	global_load_dwordx4 v[8:11], v236, s[8:9] offset:2048
	global_load_dwordx4 v[12:15], v236, s[8:9] offset:3072
	s_add_u32 s8, s8, 0x1000
	s_addc_u32 s9, s9, 0
	global_load_dwordx4 v[64:67], v236, s[12:13] offset:0
	global_load_dwordx4 v[68:71], v236, s[12:13] offset:1024
	global_load_dwordx4 v[72:75], v236, s[12:13] offset:2048
	global_load_dwordx4 v[76:79], v236, s[12:13] offset:3072
	global_load_dwordx4 v[194:197], v236, s[14:15] offset:0
	global_load_dwordx4 v[198:201], v236, s[14:15] offset:1024
	global_load_dwordx4 v[202:205], v236, s[14:15] offset:2048
	global_load_dwordx4 v[206:209], v236, s[14:15] offset:3072
	global_load_dwordx4 v[16:19], v236, s[8:9] offset:0
	global_load_dwordx4 v[20:23], v236, s[8:9] offset:1024
	global_load_dwordx4 v[24:27], v236, s[8:9] offset:2048
	global_load_dwordx4 v[28:31], v236, s[8:9] offset:3072
	s_add_u32 s8, s8, 0x1000
	s_addc_u32 s9, s9, 0
	global_load_dwordx4 v[32:35], v236, s[8:9] offset:0
	global_load_dwordx4 v[36:39], v236, s[8:9] offset:1024
	global_load_dwordx4 v[40:43], v236, s[8:9] offset:2048
	global_load_dwordx4 v[44:47], v236, s[8:9] offset:3072
	s_add_u32 s8, s8, 0x1000
	s_addc_u32 s9, s9, 0
	s_waitcnt vmcnt(16)
	v_mul_f32_e32 v238, v0, v0
	v_mul_f32_e32 v239, v1, v1
	v_fmac_f32_e32 v238, v2, v2
	v_fmac_f32_e32 v239, v3, v3
	v_fmac_f32_e32 v238, v4, v4
	v_fmac_f32_e32 v239, v5, v5
	v_fmac_f32_e32 v238, v6, v6
	v_fmac_f32_e32 v239, v7, v7
	v_fmac_f32_e32 v238, v8, v8
	v_fmac_f32_e32 v239, v9, v9
	v_fmac_f32_e32 v238, v10, v10
	v_fmac_f32_e32 v239, v11, v11
	v_fmac_f32_e32 v238, v12, v12
	v_fmac_f32_e32 v239, v13, v13
	v_fmac_f32_e32 v238, v14, v14
	v_fmac_f32_e32 v239, v15, v15
	v_add_f32_e32 v238, v238, v239
	s_nop 1
	v_add_f32_dpp v238, v238, v238 quad_perm:[1,0,3,2] row_mask:0xf bank_mask:0xf bound_ctrl:1
	s_nop 1
	v_add_f32_dpp v238, v238, v238 quad_perm:[2,3,0,1] row_mask:0xf bank_mask:0xf bound_ctrl:1
	s_nop 1
	v_add_f32_dpp v238, v238, v238 row_ror:4 row_mask:0xf bank_mask:0xf bound_ctrl:1
	s_nop 1
	v_add_f32_dpp v238, v238, v238 row_ror:8 row_mask:0xf bank_mask:0xf bound_ctrl:1
	s_nop 1
	v_readlane_b32 s1, v238, 0
	v_readlane_b32 s3, v238, 16
	v_readlane_b32 s16, v238, 32
	v_readlane_b32 s17, v238, 48
	s_nop 1
	v_mov_b32_e32 v238, s1
	v_add_f32_e32 v238, s3, v238
	v_add_f32_e32 v238, s16, v238
	v_add_f32_e32 v238, s17, v238
	v_mov_b32_e32 v239, 0x358637bd
	v_fmac_f32_e32 v239, 0x3a800000, v238
	v_rsq_f32_e32 v238, v239
	s_nop 0
	s_waitcnt vmcnt(8)
	v_add_f32_e32 v194, 1.0, v194
	v_add_f32_e32 v195, 1.0, v195
	v_add_f32_e32 v196, 1.0, v196
	v_add_f32_e32 v197, 1.0, v197
	v_add_f32_e32 v198, 1.0, v198
	v_add_f32_e32 v199, 1.0, v199
	v_add_f32_e32 v200, 1.0, v200
	v_add_f32_e32 v201, 1.0, v201
	v_add_f32_e32 v202, 1.0, v202
	v_add_f32_e32 v203, 1.0, v203
	v_add_f32_e32 v204, 1.0, v204
	v_add_f32_e32 v205, 1.0, v205
	v_add_f32_e32 v206, 1.0, v206
	v_add_f32_e32 v207, 1.0, v207
	v_add_f32_e32 v208, 1.0, v208
	v_add_f32_e32 v209, 1.0, v209
	v_mul_f32_e32 v0, v0, v238
	v_mul_f32_e32 v1, v1, v238
	v_mul_f32_e32 v2, v2, v238
	v_mul_f32_e32 v3, v3, v238
	v_mul_f32_e32 v4, v4, v238
	v_mul_f32_e32 v5, v5, v238
	v_mul_f32_e32 v6, v6, v238
	v_mul_f32_e32 v7, v7, v238
	v_mul_f32_e32 v8, v8, v238
	v_mul_f32_e32 v9, v9, v238
	v_mul_f32_e32 v10, v10, v238
	v_mul_f32_e32 v11, v11, v238
	v_mul_f32_e32 v12, v12, v238
	v_mul_f32_e32 v13, v13, v238
	v_mul_f32_e32 v14, v14, v238
	v_mul_f32_e32 v15, v15, v238
	v_mul_f32_e32 v0, v48, v0
	v_mul_f32_e32 v1, v49, v1
	v_mul_f32_e32 v2, v50, v2
	v_mul_f32_e32 v3, v51, v3
	v_mul_f32_e32 v4, v52, v4
	v_mul_f32_e32 v5, v53, v5
	v_mul_f32_e32 v6, v54, v6
	v_mul_f32_e32 v7, v55, v7
	v_mul_f32_e32 v8, v56, v8
	v_mul_f32_e32 v9, v57, v9
	v_mul_f32_e32 v10, v58, v10
	v_mul_f32_e32 v11, v59, v11
	v_mul_f32_e32 v12, v60, v12
	v_mul_f32_e32 v13, v61, v13
	v_mul_f32_e32 v14, v62, v14
	v_mul_f32_e32 v15, v63, v15
	v_fma_f32 v0, v194, v0, v64
	v_fma_f32 v1, v195, v1, v65
	v_fma_f32 v2, v196, v2, v66
	v_fma_f32 v3, v197, v3, v67
	v_fma_f32 v4, v198, v4, v68
	v_fma_f32 v5, v199, v5, v69
	v_fma_f32 v6, v200, v6, v70
	v_fma_f32 v7, v201, v7, v71
	v_fma_f32 v8, v202, v8, v72
	v_fma_f32 v9, v203, v9, v73
	v_fma_f32 v10, v204, v10, v74
	v_fma_f32 v11, v205, v11, v75
	v_fma_f32 v12, v206, v12, v76
	v_fma_f32 v13, v207, v13, v77
	v_fma_f32 v14, v208, v14, v78
	v_fma_f32 v15, v209, v15, v79
	v_cvt_pk_bf16_f32 v240, v0, v1
	v_cvt_pk_bf16_f32 v241, v2, v3
	v_cvt_pk_bf16_f32 v242, v4, v5
	v_cvt_pk_bf16_f32 v243, v6, v7
	v_cvt_pk_bf16_f32 v244, v8, v9
	v_cvt_pk_bf16_f32 v245, v10, v11
	v_cvt_pk_bf16_f32 v246, v12, v13
	v_cvt_pk_bf16_f32 v247, v14, v15
	global_store_dwordx2 v237, v[240:241], s[10:11] offset:0
	global_store_dwordx2 v237, v[242:243], s[10:11] offset:512
	global_store_dwordx2 v237, v[244:245], s[10:11] offset:1024
	global_store_dwordx2 v237, v[246:247], s[10:11] offset:1536
	s_add_u32 s10, s10, 0x880
	s_addc_u32 s11, s11, 0
	global_load_dwordx4 v[0:3], v236, s[8:9] offset:0
	global_load_dwordx4 v[4:7], v236, s[8:9] offset:1024
	global_load_dwordx4 v[8:11], v236, s[8:9] offset:2048
	global_load_dwordx4 v[12:15], v236, s[8:9] offset:3072
	s_add_u32 s8, s8, 0x1000
	s_addc_u32 s9, s9, 0
	s_waitcnt vmcnt(12)
	v_mul_f32_e32 v238, v16, v16
	v_mul_f32_e32 v239, v17, v17
	v_fmac_f32_e32 v238, v18, v18
	v_fmac_f32_e32 v239, v19, v19
	v_fmac_f32_e32 v238, v20, v20
	v_fmac_f32_e32 v239, v21, v21
	v_fmac_f32_e32 v238, v22, v22
	v_fmac_f32_e32 v239, v23, v23
	v_fmac_f32_e32 v238, v24, v24
	v_fmac_f32_e32 v239, v25, v25
	v_fmac_f32_e32 v238, v26, v26
	v_fmac_f32_e32 v239, v27, v27
	v_fmac_f32_e32 v238, v28, v28
	v_fmac_f32_e32 v239, v29, v29
	v_fmac_f32_e32 v238, v30, v30
	v_fmac_f32_e32 v239, v31, v31
	v_add_f32_e32 v238, v238, v239
	s_nop 1
	v_add_f32_dpp v238, v238, v238 quad_perm:[1,0,3,2] row_mask:0xf bank_mask:0xf bound_ctrl:1
	s_nop 1
	v_add_f32_dpp v238, v238, v238 quad_perm:[2,3,0,1] row_mask:0xf bank_mask:0xf bound_ctrl:1
	s_nop 1
	v_add_f32_dpp v238, v238, v238 row_ror:4 row_mask:0xf bank_mask:0xf bound_ctrl:1
	s_nop 1
	v_add_f32_dpp v238, v238, v238 row_ror:8 row_mask:0xf bank_mask:0xf bound_ctrl:1
	s_nop 1
	v_readlane_b32 s1, v238, 0
	v_readlane_b32 s3, v238, 16
	v_readlane_b32 s16, v238, 32
	v_readlane_b32 s17, v238, 48
	s_nop 1
	v_mov_b32_e32 v238, s1
	v_add_f32_e32 v238, s3, v238
	v_add_f32_e32 v238, s16, v238
	v_add_f32_e32 v238, s17, v238
	v_mov_b32_e32 v239, 0x358637bd
	v_fmac_f32_e32 v239, 0x3a800000, v238
	v_rsq_f32_e32 v238, v239
	s_nop 0
	v_mul_f32_e32 v16, v16, v238
	v_mul_f32_e32 v17, v17, v238
	v_mul_f32_e32 v18, v18, v238
	v_mul_f32_e32 v19, v19, v238
	v_mul_f32_e32 v20, v20, v238
	v_mul_f32_e32 v21, v21, v238
	v_mul_f32_e32 v22, v22, v238
	v_mul_f32_e32 v23, v23, v238
	v_mul_f32_e32 v24, v24, v238
	v_mul_f32_e32 v25, v25, v238
	v_mul_f32_e32 v26, v26, v238
	v_mul_f32_e32 v27, v27, v238
	v_mul_f32_e32 v28, v28, v238
	v_mul_f32_e32 v29, v29, v238
	v_mul_f32_e32 v30, v30, v238
	v_mul_f32_e32 v31, v31, v238
	v_mul_f32_e32 v16, v48, v16
	v_mul_f32_e32 v17, v49, v17
	v_mul_f32_e32 v18, v50, v18
	v_mul_f32_e32 v19, v51, v19
	v_mul_f32_e32 v20, v52, v20
	v_mul_f32_e32 v21, v53, v21
	v_mul_f32_e32 v22, v54, v22
	v_mul_f32_e32 v23, v55, v23
	v_mul_f32_e32 v24, v56, v24
	v_mul_f32_e32 v25, v57, v25
	v_mul_f32_e32 v26, v58, v26
	v_mul_f32_e32 v27, v59, v27
	v_mul_f32_e32 v28, v60, v28
	v_mul_f32_e32 v29, v61, v29
	v_mul_f32_e32 v30, v62, v30
	v_mul_f32_e32 v31, v63, v31
	v_fma_f32 v16, v194, v16, v64
	v_fma_f32 v17, v195, v17, v65
	v_fma_f32 v18, v196, v18, v66
	v_fma_f32 v19, v197, v19, v67
	v_fma_f32 v20, v198, v20, v68
	v_fma_f32 v21, v199, v21, v69
	v_fma_f32 v22, v200, v22, v70
	v_fma_f32 v23, v201, v23, v71
	v_fma_f32 v24, v202, v24, v72
	v_fma_f32 v25, v203, v25, v73
	v_fma_f32 v26, v204, v26, v74
	v_fma_f32 v27, v205, v27, v75
	v_fma_f32 v28, v206, v28, v76
	v_fma_f32 v29, v207, v29, v77
	v_fma_f32 v30, v208, v30, v78
	v_fma_f32 v31, v209, v31, v79
	v_cvt_pk_bf16_f32 v248, v16, v17
	v_cvt_pk_bf16_f32 v249, v18, v19
	v_cvt_pk_bf16_f32 v250, v20, v21
	v_cvt_pk_bf16_f32 v251, v22, v23
	v_cvt_pk_bf16_f32 v252, v24, v25
	v_cvt_pk_bf16_f32 v253, v26, v27
	v_cvt_pk_bf16_f32 v254, v28, v29
	v_cvt_pk_bf16_f32 v255, v30, v31
	global_store_dwordx2 v237, v[248:249], s[10:11] offset:0
	global_store_dwordx2 v237, v[250:251], s[10:11] offset:512
	global_store_dwordx2 v237, v[252:253], s[10:11] offset:1024
	global_store_dwordx2 v237, v[254:255], s[10:11] offset:1536
	s_add_u32 s10, s10, 0x880
	s_addc_u32 s11, s11, 0
	global_load_dwordx4 v[16:19], v236, s[8:9] offset:0
	global_load_dwordx4 v[20:23], v236, s[8:9] offset:1024
	global_load_dwordx4 v[24:27], v236, s[8:9] offset:2048
	global_load_dwordx4 v[28:31], v236, s[8:9] offset:3072
	s_add_u32 s8, s8, 0x1000
	s_addc_u32 s9, s9, 0
	s_waitcnt vmcnt(16)
	v_mul_f32_e32 v238, v32, v32
	v_mul_f32_e32 v239, v33, v33
	v_fmac_f32_e32 v238, v34, v34
	v_fmac_f32_e32 v239, v35, v35
	v_fmac_f32_e32 v238, v36, v36
	v_fmac_f32_e32 v239, v37, v37
	v_fmac_f32_e32 v238, v38, v38
	v_fmac_f32_e32 v239, v39, v39
	v_fmac_f32_e32 v238, v40, v40
	v_fmac_f32_e32 v239, v41, v41
	v_fmac_f32_e32 v238, v42, v42
	v_fmac_f32_e32 v239, v43, v43
	v_fmac_f32_e32 v238, v44, v44
	v_fmac_f32_e32 v239, v45, v45
	v_fmac_f32_e32 v238, v46, v46
	v_fmac_f32_e32 v239, v47, v47
	v_add_f32_e32 v238, v238, v239
	s_nop 1
	v_add_f32_dpp v238, v238, v238 quad_perm:[1,0,3,2] row_mask:0xf bank_mask:0xf bound_ctrl:1
	s_nop 1
	v_add_f32_dpp v238, v238, v238 quad_perm:[2,3,0,1] row_mask:0xf bank_mask:0xf bound_ctrl:1
	s_nop 1
	v_add_f32_dpp v238, v238, v238 row_ror:4 row_mask:0xf bank_mask:0xf bound_ctrl:1
	s_nop 1
	v_add_f32_dpp v238, v238, v238 row_ror:8 row_mask:0xf bank_mask:0xf bound_ctrl:1
	s_nop 1
	v_readlane_b32 s1, v238, 0
	v_readlane_b32 s3, v238, 16
	v_readlane_b32 s16, v238, 32
	v_readlane_b32 s17, v238, 48
	s_nop 1
	v_mov_b32_e32 v238, s1
	v_add_f32_e32 v238, s3, v238
	v_add_f32_e32 v238, s16, v238
	v_add_f32_e32 v238, s17, v238
	v_mov_b32_e32 v239, 0x358637bd
	v_fmac_f32_e32 v239, 0x3a800000, v238
	v_rsq_f32_e32 v238, v239
	s_nop 0
	v_mul_f32_e32 v32, v32, v238
	v_mul_f32_e32 v33, v33, v238
	v_mul_f32_e32 v34, v34, v238
	v_mul_f32_e32 v35, v35, v238
	v_mul_f32_e32 v36, v36, v238
	v_mul_f32_e32 v37, v37, v238
	v_mul_f32_e32 v38, v38, v238
	v_mul_f32_e32 v39, v39, v238
	v_mul_f32_e32 v40, v40, v238
	v_mul_f32_e32 v41, v41, v238
	v_mul_f32_e32 v42, v42, v238
	v_mul_f32_e32 v43, v43, v238
	v_mul_f32_e32 v44, v44, v238
	v_mul_f32_e32 v45, v45, v238
	v_mul_f32_e32 v46, v46, v238
	v_mul_f32_e32 v47, v47, v238
	v_mul_f32_e32 v32, v48, v32
	v_mul_f32_e32 v33, v49, v33
	v_mul_f32_e32 v34, v50, v34
	v_mul_f32_e32 v35, v51, v35
	v_mul_f32_e32 v36, v52, v36
	v_mul_f32_e32 v37, v53, v37
	v_mul_f32_e32 v38, v54, v38
	v_mul_f32_e32 v39, v55, v39
	v_mul_f32_e32 v40, v56, v40
	v_mul_f32_e32 v41, v57, v41
	v_mul_f32_e32 v42, v58, v42
	v_mul_f32_e32 v43, v59, v43
	v_mul_f32_e32 v44, v60, v44
	v_mul_f32_e32 v45, v61, v45
	v_mul_f32_e32 v46, v62, v46
	v_mul_f32_e32 v47, v63, v47
	v_fma_f32 v32, v194, v32, v64
	v_fma_f32 v33, v195, v33, v65
	v_fma_f32 v34, v196, v34, v66
	v_fma_f32 v35, v197, v35, v67
	v_fma_f32 v36, v198, v36, v68
	v_fma_f32 v37, v199, v37, v69
	v_fma_f32 v38, v200, v38, v70
	v_fma_f32 v39, v201, v39, v71
	v_fma_f32 v40, v202, v40, v72
	v_fma_f32 v41, v203, v41, v73
	v_fma_f32 v42, v204, v42, v74
	v_fma_f32 v43, v205, v43, v75
	v_fma_f32 v44, v206, v44, v76
	v_fma_f32 v45, v207, v45, v77
	v_fma_f32 v46, v208, v46, v78
	v_fma_f32 v47, v209, v47, v79
	v_cvt_pk_bf16_f32 v240, v32, v33
	v_cvt_pk_bf16_f32 v241, v34, v35
	v_cvt_pk_bf16_f32 v242, v36, v37
	v_cvt_pk_bf16_f32 v243, v38, v39
	v_cvt_pk_bf16_f32 v244, v40, v41
	v_cvt_pk_bf16_f32 v245, v42, v43
	v_cvt_pk_bf16_f32 v246, v44, v45
	v_cvt_pk_bf16_f32 v247, v46, v47
	global_store_dwordx2 v237, v[240:241], s[10:11] offset:0
	global_store_dwordx2 v237, v[242:243], s[10:11] offset:512
	global_store_dwordx2 v237, v[244:245], s[10:11] offset:1024
	global_store_dwordx2 v237, v[246:247], s[10:11] offset:1536
	s_add_u32 s10, s10, 0x880
	s_addc_u32 s11, s11, 0
	global_load_dwordx4 v[32:35], v236, s[8:9] offset:0
	global_load_dwordx4 v[36:39], v236, s[8:9] offset:1024
	global_load_dwordx4 v[40:43], v236, s[8:9] offset:2048
	global_load_dwordx4 v[44:47], v236, s[8:9] offset:3072
	s_add_u32 s8, s8, 0x1000
	s_addc_u32 s9, s9, 0
	s_waitcnt vmcnt(16)
	v_mul_f32_e32 v238, v0, v0
	v_mul_f32_e32 v239, v1, v1
	v_fmac_f32_e32 v238, v2, v2
	v_fmac_f32_e32 v239, v3, v3
	v_fmac_f32_e32 v238, v4, v4
	v_fmac_f32_e32 v239, v5, v5
	v_fmac_f32_e32 v238, v6, v6
	v_fmac_f32_e32 v239, v7, v7
	v_fmac_f32_e32 v238, v8, v8
	v_fmac_f32_e32 v239, v9, v9
	v_fmac_f32_e32 v238, v10, v10
	v_fmac_f32_e32 v239, v11, v11
	v_fmac_f32_e32 v238, v12, v12
	v_fmac_f32_e32 v239, v13, v13
	v_fmac_f32_e32 v238, v14, v14
	v_fmac_f32_e32 v239, v15, v15
	v_add_f32_e32 v238, v238, v239
	s_nop 1
	v_add_f32_dpp v238, v238, v238 quad_perm:[1,0,3,2] row_mask:0xf bank_mask:0xf bound_ctrl:1
	s_nop 1
	v_add_f32_dpp v238, v238, v238 quad_perm:[2,3,0,1] row_mask:0xf bank_mask:0xf bound_ctrl:1
	s_nop 1
	v_add_f32_dpp v238, v238, v238 row_ror:4 row_mask:0xf bank_mask:0xf bound_ctrl:1
	s_nop 1
	v_add_f32_dpp v238, v238, v238 row_ror:8 row_mask:0xf bank_mask:0xf bound_ctrl:1
	s_nop 1
	v_readlane_b32 s1, v238, 0
	v_readlane_b32 s3, v238, 16
	v_readlane_b32 s16, v238, 32
	v_readlane_b32 s17, v238, 48
	s_nop 1
	v_mov_b32_e32 v238, s1
	v_add_f32_e32 v238, s3, v238
	v_add_f32_e32 v238, s16, v238
	v_add_f32_e32 v238, s17, v238
	v_mov_b32_e32 v239, 0x358637bd
	v_fmac_f32_e32 v239, 0x3a800000, v238
	v_rsq_f32_e32 v238, v239
	s_nop 0
	v_mul_f32_e32 v0, v0, v238
	v_mul_f32_e32 v1, v1, v238
	v_mul_f32_e32 v2, v2, v238
	v_mul_f32_e32 v3, v3, v238
	v_mul_f32_e32 v4, v4, v238
	v_mul_f32_e32 v5, v5, v238
	v_mul_f32_e32 v6, v6, v238
	v_mul_f32_e32 v7, v7, v238
	v_mul_f32_e32 v8, v8, v238
	v_mul_f32_e32 v9, v9, v238
	v_mul_f32_e32 v10, v10, v238
	v_mul_f32_e32 v11, v11, v238
	v_mul_f32_e32 v12, v12, v238
	v_mul_f32_e32 v13, v13, v238
	v_mul_f32_e32 v14, v14, v238
	v_mul_f32_e32 v15, v15, v238
	v_mul_f32_e32 v0, v48, v0
	v_mul_f32_e32 v1, v49, v1
	v_mul_f32_e32 v2, v50, v2
	v_mul_f32_e32 v3, v51, v3
	v_mul_f32_e32 v4, v52, v4
	v_mul_f32_e32 v5, v53, v5
	v_mul_f32_e32 v6, v54, v6
	v_mul_f32_e32 v7, v55, v7
	v_mul_f32_e32 v8, v56, v8
	v_mul_f32_e32 v9, v57, v9
	v_mul_f32_e32 v10, v58, v10
	v_mul_f32_e32 v11, v59, v11
	v_mul_f32_e32 v12, v60, v12
	v_mul_f32_e32 v13, v61, v13
	v_mul_f32_e32 v14, v62, v14
	v_mul_f32_e32 v15, v63, v15
	v_fma_f32 v0, v194, v0, v64
	v_fma_f32 v1, v195, v1, v65
	v_fma_f32 v2, v196, v2, v66
	v_fma_f32 v3, v197, v3, v67
	v_fma_f32 v4, v198, v4, v68
	v_fma_f32 v5, v199, v5, v69
	v_fma_f32 v6, v200, v6, v70
	v_fma_f32 v7, v201, v7, v71
	v_fma_f32 v8, v202, v8, v72
	v_fma_f32 v9, v203, v9, v73
	v_fma_f32 v10, v204, v10, v74
	v_fma_f32 v11, v205, v11, v75
	v_fma_f32 v12, v206, v12, v76
	v_fma_f32 v13, v207, v13, v77
	v_fma_f32 v14, v208, v14, v78
	v_fma_f32 v15, v209, v15, v79
	v_cvt_pk_bf16_f32 v248, v0, v1
	v_cvt_pk_bf16_f32 v249, v2, v3
	v_cvt_pk_bf16_f32 v250, v4, v5
	v_cvt_pk_bf16_f32 v251, v6, v7
	v_cvt_pk_bf16_f32 v252, v8, v9
	v_cvt_pk_bf16_f32 v253, v10, v11
	v_cvt_pk_bf16_f32 v254, v12, v13
	v_cvt_pk_bf16_f32 v255, v14, v15
	global_store_dwordx2 v237, v[248:249], s[10:11] offset:0
	global_store_dwordx2 v237, v[250:251], s[10:11] offset:512
	global_store_dwordx2 v237, v[252:253], s[10:11] offset:1024
	global_store_dwordx2 v237, v[254:255], s[10:11] offset:1536
	s_add_u32 s10, s10, 0x880
	s_addc_u32 s11, s11, 0
	global_load_dwordx4 v[0:3], v236, s[8:9] offset:0
	global_load_dwordx4 v[4:7], v236, s[8:9] offset:1024
	global_load_dwordx4 v[8:11], v236, s[8:9] offset:2048
	global_load_dwordx4 v[12:15], v236, s[8:9] offset:3072
	s_add_u32 s8, s8, 0x1000
	s_addc_u32 s9, s9, 0
	s_waitcnt vmcnt(16)
	v_mul_f32_e32 v238, v16, v16
	v_mul_f32_e32 v239, v17, v17
	v_fmac_f32_e32 v238, v18, v18
	v_fmac_f32_e32 v239, v19, v19
	v_fmac_f32_e32 v238, v20, v20
	v_fmac_f32_e32 v239, v21, v21
	v_fmac_f32_e32 v238, v22, v22
	v_fmac_f32_e32 v239, v23, v23
	v_fmac_f32_e32 v238, v24, v24
	v_fmac_f32_e32 v239, v25, v25
	v_fmac_f32_e32 v238, v26, v26
	v_fmac_f32_e32 v239, v27, v27
	v_fmac_f32_e32 v238, v28, v28
	v_fmac_f32_e32 v239, v29, v29
	v_fmac_f32_e32 v238, v30, v30
	v_fmac_f32_e32 v239, v31, v31
	v_add_f32_e32 v238, v238, v239
	s_nop 1
	v_add_f32_dpp v238, v238, v238 quad_perm:[1,0,3,2] row_mask:0xf bank_mask:0xf bound_ctrl:1
	s_nop 1
	v_add_f32_dpp v238, v238, v238 quad_perm:[2,3,0,1] row_mask:0xf bank_mask:0xf bound_ctrl:1
	s_nop 1
	v_add_f32_dpp v238, v238, v238 row_ror:4 row_mask:0xf bank_mask:0xf bound_ctrl:1
	s_nop 1
	v_add_f32_dpp v238, v238, v238 row_ror:8 row_mask:0xf bank_mask:0xf bound_ctrl:1
	s_nop 1
	v_readlane_b32 s1, v238, 0
	v_readlane_b32 s3, v238, 16
	v_readlane_b32 s16, v238, 32
	v_readlane_b32 s17, v238, 48
	s_nop 1
	v_mov_b32_e32 v238, s1
	v_add_f32_e32 v238, s3, v238
	v_add_f32_e32 v238, s16, v238
	v_add_f32_e32 v238, s17, v238
	v_mov_b32_e32 v239, 0x358637bd
	v_fmac_f32_e32 v239, 0x3a800000, v238
	v_rsq_f32_e32 v238, v239
	s_nop 0
	v_mul_f32_e32 v16, v16, v238
	v_mul_f32_e32 v17, v17, v238
	v_mul_f32_e32 v18, v18, v238
	v_mul_f32_e32 v19, v19, v238
	v_mul_f32_e32 v20, v20, v238
	v_mul_f32_e32 v21, v21, v238
	v_mul_f32_e32 v22, v22, v238
	v_mul_f32_e32 v23, v23, v238
	v_mul_f32_e32 v24, v24, v238
	v_mul_f32_e32 v25, v25, v238
	v_mul_f32_e32 v26, v26, v238
	v_mul_f32_e32 v27, v27, v238
	v_mul_f32_e32 v28, v28, v238
	v_mul_f32_e32 v29, v29, v238
	v_mul_f32_e32 v30, v30, v238
	v_mul_f32_e32 v31, v31, v238
	v_mul_f32_e32 v16, v48, v16
	v_mul_f32_e32 v17, v49, v17
	v_mul_f32_e32 v18, v50, v18
	v_mul_f32_e32 v19, v51, v19
	v_mul_f32_e32 v20, v52, v20
	v_mul_f32_e32 v21, v53, v21
	v_mul_f32_e32 v22, v54, v22
	v_mul_f32_e32 v23, v55, v23
	v_mul_f32_e32 v24, v56, v24
	v_mul_f32_e32 v25, v57, v25
	v_mul_f32_e32 v26, v58, v26
	v_mul_f32_e32 v27, v59, v27
	v_mul_f32_e32 v28, v60, v28
	v_mul_f32_e32 v29, v61, v29
	v_mul_f32_e32 v30, v62, v30
	v_mul_f32_e32 v31, v63, v31
	v_fma_f32 v16, v194, v16, v64
	v_fma_f32 v17, v195, v17, v65
	v_fma_f32 v18, v196, v18, v66
	v_fma_f32 v19, v197, v19, v67
	v_fma_f32 v20, v198, v20, v68
	v_fma_f32 v21, v199, v21, v69
	v_fma_f32 v22, v200, v22, v70
	v_fma_f32 v23, v201, v23, v71
	v_fma_f32 v24, v202, v24, v72
	v_fma_f32 v25, v203, v25, v73
	v_fma_f32 v26, v204, v26, v74
	v_fma_f32 v27, v205, v27, v75
	v_fma_f32 v28, v206, v28, v76
	v_fma_f32 v29, v207, v29, v77
	v_fma_f32 v30, v208, v30, v78
	v_fma_f32 v31, v209, v31, v79
	v_cvt_pk_bf16_f32 v240, v16, v17
	v_cvt_pk_bf16_f32 v241, v18, v19
	v_cvt_pk_bf16_f32 v242, v20, v21
	v_cvt_pk_bf16_f32 v243, v22, v23
	v_cvt_pk_bf16_f32 v244, v24, v25
	v_cvt_pk_bf16_f32 v245, v26, v27
	v_cvt_pk_bf16_f32 v246, v28, v29
	v_cvt_pk_bf16_f32 v247, v30, v31
	global_store_dwordx2 v237, v[240:241], s[10:11] offset:0
	global_store_dwordx2 v237, v[242:243], s[10:11] offset:512
	global_store_dwordx2 v237, v[244:245], s[10:11] offset:1024
	global_store_dwordx2 v237, v[246:247], s[10:11] offset:1536
	s_add_u32 s10, s10, 0x880
	s_addc_u32 s11, s11, 0
	global_load_dwordx4 v[16:19], v236, s[8:9] offset:0
	global_load_dwordx4 v[20:23], v236, s[8:9] offset:1024
	global_load_dwordx4 v[24:27], v236, s[8:9] offset:2048
	global_load_dwordx4 v[28:31], v236, s[8:9] offset:3072
	s_add_u32 s8, s8, 0x1000
	s_addc_u32 s9, s9, 0
	s_waitcnt vmcnt(16)
	v_mul_f32_e32 v238, v32, v32
	v_mul_f32_e32 v239, v33, v33
	v_fmac_f32_e32 v238, v34, v34
	v_fmac_f32_e32 v239, v35, v35
	v_fmac_f32_e32 v238, v36, v36
	v_fmac_f32_e32 v239, v37, v37
	v_fmac_f32_e32 v238, v38, v38
	v_fmac_f32_e32 v239, v39, v39
	v_fmac_f32_e32 v238, v40, v40
	v_fmac_f32_e32 v239, v41, v41
	v_fmac_f32_e32 v238, v42, v42
	v_fmac_f32_e32 v239, v43, v43
	v_fmac_f32_e32 v238, v44, v44
	v_fmac_f32_e32 v239, v45, v45
	v_fmac_f32_e32 v238, v46, v46
	v_fmac_f32_e32 v239, v47, v47
	v_add_f32_e32 v238, v238, v239
	s_nop 1
	v_add_f32_dpp v238, v238, v238 quad_perm:[1,0,3,2] row_mask:0xf bank_mask:0xf bound_ctrl:1
	s_nop 1
	v_add_f32_dpp v238, v238, v238 quad_perm:[2,3,0,1] row_mask:0xf bank_mask:0xf bound_ctrl:1
	s_nop 1
	v_add_f32_dpp v238, v238, v238 row_ror:4 row_mask:0xf bank_mask:0xf bound_ctrl:1
	s_nop 1
	v_add_f32_dpp v238, v238, v238 row_ror:8 row_mask:0xf bank_mask:0xf bound_ctrl:1
	s_nop 1
	v_readlane_b32 s1, v238, 0
	v_readlane_b32 s3, v238, 16
	v_readlane_b32 s16, v238, 32
	v_readlane_b32 s17, v238, 48
	s_nop 1
	v_mov_b32_e32 v238, s1
	v_add_f32_e32 v238, s3, v238
	v_add_f32_e32 v238, s16, v238
	v_add_f32_e32 v238, s17, v238
	v_mov_b32_e32 v239, 0x358637bd
	v_fmac_f32_e32 v239, 0x3a800000, v238
	v_rsq_f32_e32 v238, v239
	s_nop 0
	v_mul_f32_e32 v32, v32, v238
	v_mul_f32_e32 v33, v33, v238
	v_mul_f32_e32 v34, v34, v238
	v_mul_f32_e32 v35, v35, v238
	v_mul_f32_e32 v36, v36, v238
	v_mul_f32_e32 v37, v37, v238
	v_mul_f32_e32 v38, v38, v238
	v_mul_f32_e32 v39, v39, v238
	v_mul_f32_e32 v40, v40, v238
	v_mul_f32_e32 v41, v41, v238
	v_mul_f32_e32 v42, v42, v238
	v_mul_f32_e32 v43, v43, v238
	v_mul_f32_e32 v44, v44, v238
	v_mul_f32_e32 v45, v45, v238
	v_mul_f32_e32 v46, v46, v238
	v_mul_f32_e32 v47, v47, v238
	v_mul_f32_e32 v32, v48, v32
	v_mul_f32_e32 v33, v49, v33
	v_mul_f32_e32 v34, v50, v34
	v_mul_f32_e32 v35, v51, v35
	v_mul_f32_e32 v36, v52, v36
	v_mul_f32_e32 v37, v53, v37
	v_mul_f32_e32 v38, v54, v38
	v_mul_f32_e32 v39, v55, v39
	v_mul_f32_e32 v40, v56, v40
	v_mul_f32_e32 v41, v57, v41
	v_mul_f32_e32 v42, v58, v42
	v_mul_f32_e32 v43, v59, v43
	v_mul_f32_e32 v44, v60, v44
	v_mul_f32_e32 v45, v61, v45
	v_mul_f32_e32 v46, v62, v46
	v_mul_f32_e32 v47, v63, v47
	v_fma_f32 v32, v194, v32, v64
	v_fma_f32 v33, v195, v33, v65
	v_fma_f32 v34, v196, v34, v66
	v_fma_f32 v35, v197, v35, v67
	v_fma_f32 v36, v198, v36, v68
	v_fma_f32 v37, v199, v37, v69
	v_fma_f32 v38, v200, v38, v70
	v_fma_f32 v39, v201, v39, v71
	v_fma_f32 v40, v202, v40, v72
	v_fma_f32 v41, v203, v41, v73
	v_fma_f32 v42, v204, v42, v74
	v_fma_f32 v43, v205, v43, v75
	v_fma_f32 v44, v206, v44, v76
	v_fma_f32 v45, v207, v45, v77
	v_fma_f32 v46, v208, v46, v78
	v_fma_f32 v47, v209, v47, v79
	v_cvt_pk_bf16_f32 v248, v32, v33
	v_cvt_pk_bf16_f32 v249, v34, v35
	v_cvt_pk_bf16_f32 v250, v36, v37
	v_cvt_pk_bf16_f32 v251, v38, v39
	v_cvt_pk_bf16_f32 v252, v40, v41
	v_cvt_pk_bf16_f32 v253, v42, v43
	v_cvt_pk_bf16_f32 v254, v44, v45
	v_cvt_pk_bf16_f32 v255, v46, v47
	global_store_dwordx2 v237, v[248:249], s[10:11] offset:0
	global_store_dwordx2 v237, v[250:251], s[10:11] offset:512
	global_store_dwordx2 v237, v[252:253], s[10:11] offset:1024
	global_store_dwordx2 v237, v[254:255], s[10:11] offset:1536
	s_add_u32 s10, s10, 0x880
	s_addc_u32 s11, s11, 0
	s_waitcnt vmcnt(12)
	v_mul_f32_e32 v238, v0, v0
	v_mul_f32_e32 v239, v1, v1
	v_fmac_f32_e32 v238, v2, v2
	v_fmac_f32_e32 v239, v3, v3
	v_fmac_f32_e32 v238, v4, v4
	v_fmac_f32_e32 v239, v5, v5
	v_fmac_f32_e32 v238, v6, v6
	v_fmac_f32_e32 v239, v7, v7
	v_fmac_f32_e32 v238, v8, v8
	v_fmac_f32_e32 v239, v9, v9
	v_fmac_f32_e32 v238, v10, v10
	v_fmac_f32_e32 v239, v11, v11
	v_fmac_f32_e32 v238, v12, v12
	v_fmac_f32_e32 v239, v13, v13
	v_fmac_f32_e32 v238, v14, v14
	v_fmac_f32_e32 v239, v15, v15
	v_add_f32_e32 v238, v238, v239
	s_nop 1
	v_add_f32_dpp v238, v238, v238 quad_perm:[1,0,3,2] row_mask:0xf bank_mask:0xf bound_ctrl:1
	s_nop 1
	v_add_f32_dpp v238, v238, v238 quad_perm:[2,3,0,1] row_mask:0xf bank_mask:0xf bound_ctrl:1
	s_nop 1
	v_add_f32_dpp v238, v238, v238 row_ror:4 row_mask:0xf bank_mask:0xf bound_ctrl:1
	s_nop 1
	v_add_f32_dpp v238, v238, v238 row_ror:8 row_mask:0xf bank_mask:0xf bound_ctrl:1
	s_nop 1
	v_readlane_b32 s1, v238, 0
	v_readlane_b32 s3, v238, 16
	v_readlane_b32 s16, v238, 32
	v_readlane_b32 s17, v238, 48
	s_nop 1
	v_mov_b32_e32 v238, s1
	v_add_f32_e32 v238, s3, v238
	v_add_f32_e32 v238, s16, v238
	v_add_f32_e32 v238, s17, v238
	v_mov_b32_e32 v239, 0x358637bd
	v_fmac_f32_e32 v239, 0x3a800000, v238
	v_rsq_f32_e32 v238, v239
	s_nop 0
	v_mul_f32_e32 v0, v0, v238
	v_mul_f32_e32 v1, v1, v238
	v_mul_f32_e32 v2, v2, v238
	v_mul_f32_e32 v3, v3, v238
	v_mul_f32_e32 v4, v4, v238
	v_mul_f32_e32 v5, v5, v238
	v_mul_f32_e32 v6, v6, v238
	v_mul_f32_e32 v7, v7, v238
	v_mul_f32_e32 v8, v8, v238
	v_mul_f32_e32 v9, v9, v238
	v_mul_f32_e32 v10, v10, v238
	v_mul_f32_e32 v11, v11, v238
	v_mul_f32_e32 v12, v12, v238
	v_mul_f32_e32 v13, v13, v238
	v_mul_f32_e32 v14, v14, v238
	v_mul_f32_e32 v15, v15, v238
	v_mul_f32_e32 v0, v48, v0
	v_mul_f32_e32 v1, v49, v1
	v_mul_f32_e32 v2, v50, v2
	v_mul_f32_e32 v3, v51, v3
	v_mul_f32_e32 v4, v52, v4
	v_mul_f32_e32 v5, v53, v5
	v_mul_f32_e32 v6, v54, v6
	v_mul_f32_e32 v7, v55, v7
	v_mul_f32_e32 v8, v56, v8
	v_mul_f32_e32 v9, v57, v9
	v_mul_f32_e32 v10, v58, v10
	v_mul_f32_e32 v11, v59, v11
	v_mul_f32_e32 v12, v60, v12
	v_mul_f32_e32 v13, v61, v13
	v_mul_f32_e32 v14, v62, v14
	v_mul_f32_e32 v15, v63, v15
	v_fma_f32 v0, v194, v0, v64
	v_fma_f32 v1, v195, v1, v65
	v_fma_f32 v2, v196, v2, v66
	v_fma_f32 v3, v197, v3, v67
	v_fma_f32 v4, v198, v4, v68
	v_fma_f32 v5, v199, v5, v69
	v_fma_f32 v6, v200, v6, v70
	v_fma_f32 v7, v201, v7, v71
	v_fma_f32 v8, v202, v8, v72
	v_fma_f32 v9, v203, v9, v73
	v_fma_f32 v10, v204, v10, v74
	v_fma_f32 v11, v205, v11, v75
	v_fma_f32 v12, v206, v12, v76
	v_fma_f32 v13, v207, v13, v77
	v_fma_f32 v14, v208, v14, v78
	v_fma_f32 v15, v209, v15, v79
	v_cvt_pk_bf16_f32 v240, v0, v1
	v_cvt_pk_bf16_f32 v241, v2, v3
	v_cvt_pk_bf16_f32 v242, v4, v5
	v_cvt_pk_bf16_f32 v243, v6, v7
	v_cvt_pk_bf16_f32 v244, v8, v9
	v_cvt_pk_bf16_f32 v245, v10, v11
	v_cvt_pk_bf16_f32 v246, v12, v13
	v_cvt_pk_bf16_f32 v247, v14, v15
	global_store_dwordx2 v237, v[240:241], s[10:11] offset:0
	global_store_dwordx2 v237, v[242:243], s[10:11] offset:512
	global_store_dwordx2 v237, v[244:245], s[10:11] offset:1024
	global_store_dwordx2 v237, v[246:247], s[10:11] offset:1536
	s_add_u32 s10, s10, 0x880
	s_addc_u32 s11, s11, 0
	s_waitcnt vmcnt(8)
	v_mul_f32_e32 v238, v16, v16
	v_mul_f32_e32 v239, v17, v17
	v_fmac_f32_e32 v238, v18, v18
	v_fmac_f32_e32 v239, v19, v19
	v_fmac_f32_e32 v238, v20, v20
	v_fmac_f32_e32 v239, v21, v21
	v_fmac_f32_e32 v238, v22, v22
	v_fmac_f32_e32 v239, v23, v23
	v_fmac_f32_e32 v238, v24, v24
	v_fmac_f32_e32 v239, v25, v25
	v_fmac_f32_e32 v238, v26, v26
	v_fmac_f32_e32 v239, v27, v27
	v_fmac_f32_e32 v238, v28, v28
	v_fmac_f32_e32 v239, v29, v29
	v_fmac_f32_e32 v238, v30, v30
	v_fmac_f32_e32 v239, v31, v31
	v_add_f32_e32 v238, v238, v239
	s_nop 1
	v_add_f32_dpp v238, v238, v238 quad_perm:[1,0,3,2] row_mask:0xf bank_mask:0xf bound_ctrl:1
	s_nop 1
	v_add_f32_dpp v238, v238, v238 quad_perm:[2,3,0,1] row_mask:0xf bank_mask:0xf bound_ctrl:1
	s_nop 1
	v_add_f32_dpp v238, v238, v238 row_ror:4 row_mask:0xf bank_mask:0xf bound_ctrl:1
	s_nop 1
	v_add_f32_dpp v238, v238, v238 row_ror:8 row_mask:0xf bank_mask:0xf bound_ctrl:1
	s_nop 1
	v_readlane_b32 s1, v238, 0
	v_readlane_b32 s3, v238, 16
	v_readlane_b32 s16, v238, 32
	v_readlane_b32 s17, v238, 48
	s_nop 1
	v_mov_b32_e32 v238, s1
	v_add_f32_e32 v238, s3, v238
	v_add_f32_e32 v238, s16, v238
	v_add_f32_e32 v238, s17, v238
	v_mov_b32_e32 v239, 0x358637bd
	v_fmac_f32_e32 v239, 0x3a800000, v238
	v_rsq_f32_e32 v238, v239
	s_nop 0
	v_mul_f32_e32 v16, v16, v238
	v_mul_f32_e32 v17, v17, v238
	v_mul_f32_e32 v18, v18, v238
	v_mul_f32_e32 v19, v19, v238
	v_mul_f32_e32 v20, v20, v238
	v_mul_f32_e32 v21, v21, v238
	v_mul_f32_e32 v22, v22, v238
	v_mul_f32_e32 v23, v23, v238
	v_mul_f32_e32 v24, v24, v238
	v_mul_f32_e32 v25, v25, v238
	v_mul_f32_e32 v26, v26, v238
	v_mul_f32_e32 v27, v27, v238
	v_mul_f32_e32 v28, v28, v238
	v_mul_f32_e32 v29, v29, v238
	v_mul_f32_e32 v30, v30, v238
	v_mul_f32_e32 v31, v31, v238
	v_mul_f32_e32 v16, v48, v16
	v_mul_f32_e32 v17, v49, v17
	v_mul_f32_e32 v18, v50, v18
	v_mul_f32_e32 v19, v51, v19
	v_mul_f32_e32 v20, v52, v20
	v_mul_f32_e32 v21, v53, v21
	v_mul_f32_e32 v22, v54, v22
	v_mul_f32_e32 v23, v55, v23
	v_mul_f32_e32 v24, v56, v24
	v_mul_f32_e32 v25, v57, v25
	v_mul_f32_e32 v26, v58, v26
	v_mul_f32_e32 v27, v59, v27
	v_mul_f32_e32 v28, v60, v28
	v_mul_f32_e32 v29, v61, v29
	v_mul_f32_e32 v30, v62, v30
	v_mul_f32_e32 v31, v63, v31
	v_fma_f32 v16, v194, v16, v64
	v_fma_f32 v17, v195, v17, v65
	v_fma_f32 v18, v196, v18, v66
	v_fma_f32 v19, v197, v19, v67
	v_fma_f32 v20, v198, v20, v68
	v_fma_f32 v21, v199, v21, v69
	v_fma_f32 v22, v200, v22, v70
	v_fma_f32 v23, v201, v23, v71
	v_fma_f32 v24, v202, v24, v72
	v_fma_f32 v25, v203, v25, v73
	v_fma_f32 v26, v204, v26, v74
	v_fma_f32 v27, v205, v27, v75
	v_fma_f32 v28, v206, v28, v76
	v_fma_f32 v29, v207, v29, v77
	v_fma_f32 v30, v208, v30, v78
	v_fma_f32 v31, v209, v31, v79
	v_cvt_pk_bf16_f32 v248, v16, v17
	v_cvt_pk_bf16_f32 v249, v18, v19
	v_cvt_pk_bf16_f32 v250, v20, v21
	v_cvt_pk_bf16_f32 v251, v22, v23
	v_cvt_pk_bf16_f32 v252, v24, v25
	v_cvt_pk_bf16_f32 v253, v26, v27
	v_cvt_pk_bf16_f32 v254, v28, v29
	v_cvt_pk_bf16_f32 v255, v30, v31
	global_store_dwordx2 v237, v[248:249], s[10:11] offset:0
	global_store_dwordx2 v237, v[250:251], s[10:11] offset:512
	global_store_dwordx2 v237, v[252:253], s[10:11] offset:1024
	global_store_dwordx2 v237, v[254:255], s[10:11] offset:1536
	s_add_u32 s10, s10, 0x880
	s_addc_u32 s11, s11, 0
	s_cmp_lg_u32 s19, 31
	s_cbranch_scc1 .Lnl1_end
	v_lshrrev_b32_e32 v238, 6, v174
	s_nop 0
	v_readfirstlane_b32 s1, v238
	s_lshl_b32 s0, s18, 3
	s_add_i32 s0, s0, s1
	s_lshl_b32 s0, s0, 1
	s_add_i32 s1, s0, 0x4000
	s_lshl_b32 s8, s1, 12
	s_add_u32 s8, s82, s8
	s_addc_u32 s9, s83, 0
	s_mul_i32 s10, s1, 0x880
	s_add_u32 s10, s10, 0x3018000
	s_add_u32 s10, s84, s10
	s_addc_u32 s11, s85, 0
	s_mul_i32 s3, s0, 0x6000
	s_add_u32 s12, s84, 0x55d0880
	s_addc_u32 s13, s85, 0
	s_add_u32 s12, s12, s3
	s_addc_u32 s13, s13, 0
	s_add_u32 s14, s12, 0x1000
	s_addc_u32 s15, s13, 0
	global_load_dwordx4 v[32:35], v236, s[8:9] offset:0
	global_load_dwordx4 v[36:39], v236, s[8:9] offset:1024
	global_load_dwordx4 v[40:43], v236, s[8:9] offset:2048
	global_load_dwordx4 v[44:47], v236, s[8:9] offset:3072
	s_add_u32 s8, s8, 0x1000
	s_addc_u32 s9, s9, 0
	global_load_dwordx4 v[80:83], v236, s[12:13] offset:0
	global_load_dwordx4 v[84:87], v236, s[12:13] offset:1024
	global_load_dwordx4 v[88:91], v236, s[12:13] offset:2048
	global_load_dwordx4 v[92:95], v236, s[12:13] offset:3072
	global_load_dwordx4 v[210:213], v236, s[14:15] offset:0
	global_load_dwordx4 v[214:217], v236, s[14:15] offset:1024
	global_load_dwordx4 v[218:221], v236, s[14:15] offset:2048
	global_load_dwordx4 v[222:225], v236, s[14:15] offset:3072
	s_add_i32 s0, s0, 1
	s_waitcnt vmcnt(8)
	v_mul_f32_e32 v238, v32, v32
	v_mul_f32_e32 v239, v33, v33
	v_fmac_f32_e32 v238, v34, v34
	v_fmac_f32_e32 v239, v35, v35
	v_fmac_f32_e32 v238, v36, v36
	v_fmac_f32_e32 v239, v37, v37
	v_fmac_f32_e32 v238, v38, v38
	v_fmac_f32_e32 v239, v39, v39
	v_fmac_f32_e32 v238, v40, v40
	v_fmac_f32_e32 v239, v41, v41
	v_fmac_f32_e32 v238, v42, v42
	v_fmac_f32_e32 v239, v43, v43
	v_fmac_f32_e32 v238, v44, v44
	v_fmac_f32_e32 v239, v45, v45
	v_fmac_f32_e32 v238, v46, v46
	v_fmac_f32_e32 v239, v47, v47
	v_add_f32_e32 v238, v238, v239
	s_nop 1
	v_add_f32_dpp v238, v238, v238 quad_perm:[1,0,3,2] row_mask:0xf bank_mask:0xf bound_ctrl:1
	s_nop 1
	v_add_f32_dpp v238, v238, v238 quad_perm:[2,3,0,1] row_mask:0xf bank_mask:0xf bound_ctrl:1
	s_nop 1
	v_add_f32_dpp v238, v238, v238 row_ror:4 row_mask:0xf bank_mask:0xf bound_ctrl:1
	s_nop 1
	v_add_f32_dpp v238, v238, v238 row_ror:8 row_mask:0xf bank_mask:0xf bound_ctrl:1
	s_nop 1
	v_readlane_b32 s1, v238, 0
	v_readlane_b32 s3, v238, 16
	v_readlane_b32 s16, v238, 32
	v_readlane_b32 s17, v238, 48
	s_nop 1
	v_mov_b32_e32 v238, s1
	v_add_f32_e32 v238, s3, v238
	v_add_f32_e32 v238, s16, v238
	v_add_f32_e32 v238, s17, v238
	v_mov_b32_e32 v239, 0x358637bd
	v_fmac_f32_e32 v239, 0x3a800000, v238
	v_rsq_f32_e32 v238, v239
	s_nop 0
	s_waitcnt vmcnt(0)
	v_add_f32_e32 v210, 1.0, v210
	v_add_f32_e32 v211, 1.0, v211
	v_add_f32_e32 v212, 1.0, v212
	v_add_f32_e32 v213, 1.0, v213
	v_add_f32_e32 v214, 1.0, v214
	v_add_f32_e32 v215, 1.0, v215
	v_add_f32_e32 v216, 1.0, v216
	v_add_f32_e32 v217, 1.0, v217
	v_add_f32_e32 v218, 1.0, v218
	v_add_f32_e32 v219, 1.0, v219
	v_add_f32_e32 v220, 1.0, v220
	v_add_f32_e32 v221, 1.0, v221
	v_add_f32_e32 v222, 1.0, v222
	v_add_f32_e32 v223, 1.0, v223
	v_add_f32_e32 v224, 1.0, v224
	v_add_f32_e32 v225, 1.0, v225
	v_mul_f32_e32 v32, v32, v238
	v_mul_f32_e32 v33, v33, v238
	v_mul_f32_e32 v34, v34, v238
	v_mul_f32_e32 v35, v35, v238
	v_mul_f32_e32 v36, v36, v238
	v_mul_f32_e32 v37, v37, v238
	v_mul_f32_e32 v38, v38, v238
	v_mul_f32_e32 v39, v39, v238
	v_mul_f32_e32 v40, v40, v238
	v_mul_f32_e32 v41, v41, v238
	v_mul_f32_e32 v42, v42, v238
	v_mul_f32_e32 v43, v43, v238
	v_mul_f32_e32 v44, v44, v238
	v_mul_f32_e32 v45, v45, v238
	v_mul_f32_e32 v46, v46, v238
	v_mul_f32_e32 v47, v47, v238
	v_mul_f32_e32 v32, v48, v32
	v_mul_f32_e32 v33, v49, v33
	v_mul_f32_e32 v34, v50, v34
	v_mul_f32_e32 v35, v51, v35
	v_mul_f32_e32 v36, v52, v36
	v_mul_f32_e32 v37, v53, v37
	v_mul_f32_e32 v38, v54, v38
	v_mul_f32_e32 v39, v55, v39
	v_mul_f32_e32 v40, v56, v40
	v_mul_f32_e32 v41, v57, v41
	v_mul_f32_e32 v42, v58, v42
	v_mul_f32_e32 v43, v59, v43
	v_mul_f32_e32 v44, v60, v44
	v_mul_f32_e32 v45, v61, v45
	v_mul_f32_e32 v46, v62, v46
	v_mul_f32_e32 v47, v63, v47
	v_fma_f32 v32, v210, v32, v80
	v_fma_f32 v33, v211, v33, v81
	v_fma_f32 v34, v212, v34, v82
	v_fma_f32 v35, v213, v35, v83
	v_fma_f32 v36, v214, v36, v84
	v_fma_f32 v37, v215, v37, v85
	v_fma_f32 v38, v216, v38, v86
	v_fma_f32 v39, v217, v39, v87
	v_fma_f32 v40, v218, v40, v88
	v_fma_f32 v41, v219, v41, v89
	v_fma_f32 v42, v220, v42, v90
	v_fma_f32 v43, v221, v43, v91
	v_fma_f32 v44, v222, v44, v92
	v_fma_f32 v45, v223, v45, v93
	v_fma_f32 v46, v224, v46, v94
	v_fma_f32 v47, v225, v47, v95
	v_cvt_pk_bf16_f32 v240, v32, v33
	v_cvt_pk_bf16_f32 v241, v34, v35
	v_cvt_pk_bf16_f32 v242, v36, v37
	v_cvt_pk_bf16_f32 v243, v38, v39
	v_cvt_pk_bf16_f32 v244, v40, v41
	v_cvt_pk_bf16_f32 v245, v42, v43
	v_cvt_pk_bf16_f32 v246, v44, v45
	v_cvt_pk_bf16_f32 v247, v46, v47
	global_store_dwordx2 v237, v[240:241], s[10:11] offset:0
	global_store_dwordx2 v237, v[242:243], s[10:11] offset:512
	global_store_dwordx2 v237, v[244:245], s[10:11] offset:1024
	global_store_dwordx2 v237, v[246:247], s[10:11] offset:1536
	s_add_u32 s10, s10, 0x880
	s_addc_u32 s11, s11, 0
	s_mul_i32 s3, s0, 0x6000
	s_add_u32 s12, s84, 0x55d0880
	s_addc_u32 s13, s85, 0
	s_add_u32 s12, s12, s3
	s_addc_u32 s13, s13, 0
	s_add_u32 s14, s12, 0x1000
	s_addc_u32 s15, s13, 0
	global_load_dwordx4 v[0:3], v236, s[8:9] offset:0
	global_load_dwordx4 v[4:7], v236, s[8:9] offset:1024
	global_load_dwordx4 v[8:11], v236, s[8:9] offset:2048
	global_load_dwordx4 v[12:15], v236, s[8:9] offset:3072
	s_add_u32 s8, s8, 0x1000
	s_addc_u32 s9, s9, 0
	global_load_dwordx4 v[64:67], v236, s[12:13] offset:0
	global_load_dwordx4 v[68:71], v236, s[12:13] offset:1024
	global_load_dwordx4 v[72:75], v236, s[12:13] offset:2048
	global_load_dwordx4 v[76:79], v236, s[12:13] offset:3072
	global_load_dwordx4 v[194:197], v236, s[14:15] offset:0
	global_load_dwordx4 v[198:201], v236, s[14:15] offset:1024
	global_load_dwordx4 v[202:205], v236, s[14:15] offset:2048
	global_load_dwordx4 v[206:209], v236, s[14:15] offset:3072
	s_add_i32 s0, s0, 1
	s_waitcnt vmcnt(8)
	v_mul_f32_e32 v238, v0, v0
	v_mul_f32_e32 v239, v1, v1
	v_fmac_f32_e32 v238, v2, v2
	v_fmac_f32_e32 v239, v3, v3
	v_fmac_f32_e32 v238, v4, v4
	v_fmac_f32_e32 v239, v5, v5
	v_fmac_f32_e32 v238, v6, v6
	v_fmac_f32_e32 v239, v7, v7
	v_fmac_f32_e32 v238, v8, v8
	v_fmac_f32_e32 v239, v9, v9
	v_fmac_f32_e32 v238, v10, v10
	v_fmac_f32_e32 v239, v11, v11
	v_fmac_f32_e32 v238, v12, v12
	v_fmac_f32_e32 v239, v13, v13
	v_fmac_f32_e32 v238, v14, v14
	v_fmac_f32_e32 v239, v15, v15
	v_add_f32_e32 v238, v238, v239
	s_nop 1
	v_add_f32_dpp v238, v238, v238 quad_perm:[1,0,3,2] row_mask:0xf bank_mask:0xf bound_ctrl:1
	s_nop 1
	v_add_f32_dpp v238, v238, v238 quad_perm:[2,3,0,1] row_mask:0xf bank_mask:0xf bound_ctrl:1
	s_nop 1
	v_add_f32_dpp v238, v238, v238 row_ror:4 row_mask:0xf bank_mask:0xf bound_ctrl:1
	s_nop 1
	v_add_f32_dpp v238, v238, v238 row_ror:8 row_mask:0xf bank_mask:0xf bound_ctrl:1
	s_nop 1
	v_readlane_b32 s1, v238, 0
	v_readlane_b32 s3, v238, 16
	v_readlane_b32 s16, v238, 32
	v_readlane_b32 s17, v238, 48
	s_nop 1
	v_mov_b32_e32 v238, s1
	v_add_f32_e32 v238, s3, v238
	v_add_f32_e32 v238, s16, v238
	v_add_f32_e32 v238, s17, v238
	v_mov_b32_e32 v239, 0x358637bd
	v_fmac_f32_e32 v239, 0x3a800000, v238
	v_rsq_f32_e32 v238, v239
	s_nop 0
	s_waitcnt vmcnt(0)
	v_add_f32_e32 v194, 1.0, v194
	v_add_f32_e32 v195, 1.0, v195
	v_add_f32_e32 v196, 1.0, v196
	v_add_f32_e32 v197, 1.0, v197
	v_add_f32_e32 v198, 1.0, v198
	v_add_f32_e32 v199, 1.0, v199
	v_add_f32_e32 v200, 1.0, v200
	v_add_f32_e32 v201, 1.0, v201
	v_add_f32_e32 v202, 1.0, v202
	v_add_f32_e32 v203, 1.0, v203
	v_add_f32_e32 v204, 1.0, v204
	v_add_f32_e32 v205, 1.0, v205
	v_add_f32_e32 v206, 1.0, v206
	v_add_f32_e32 v207, 1.0, v207
	v_add_f32_e32 v208, 1.0, v208
	v_add_f32_e32 v209, 1.0, v209
	v_mul_f32_e32 v0, v0, v238
	v_mul_f32_e32 v1, v1, v238
	v_mul_f32_e32 v2, v2, v238
	v_mul_f32_e32 v3, v3, v238
	v_mul_f32_e32 v4, v4, v238
	v_mul_f32_e32 v5, v5, v238
	v_mul_f32_e32 v6, v6, v238
	v_mul_f32_e32 v7, v7, v238
	v_mul_f32_e32 v8, v8, v238
	v_mul_f32_e32 v9, v9, v238
	v_mul_f32_e32 v10, v10, v238
	v_mul_f32_e32 v11, v11, v238
	v_mul_f32_e32 v12, v12, v238
	v_mul_f32_e32 v13, v13, v238
	v_mul_f32_e32 v14, v14, v238
	v_mul_f32_e32 v15, v15, v238
	v_mul_f32_e32 v0, v48, v0
	v_mul_f32_e32 v1, v49, v1
	v_mul_f32_e32 v2, v50, v2
	v_mul_f32_e32 v3, v51, v3
	v_mul_f32_e32 v4, v52, v4
	v_mul_f32_e32 v5, v53, v5
	v_mul_f32_e32 v6, v54, v6
	v_mul_f32_e32 v7, v55, v7
	v_mul_f32_e32 v8, v56, v8
	v_mul_f32_e32 v9, v57, v9
	v_mul_f32_e32 v10, v58, v10
	v_mul_f32_e32 v11, v59, v11
	v_mul_f32_e32 v12, v60, v12
	v_mul_f32_e32 v13, v61, v13
	v_mul_f32_e32 v14, v62, v14
	v_mul_f32_e32 v15, v63, v15
	v_fma_f32 v0, v194, v0, v64
	v_fma_f32 v1, v195, v1, v65
	v_fma_f32 v2, v196, v2, v66
	v_fma_f32 v3, v197, v3, v67
	v_fma_f32 v4, v198, v4, v68
	v_fma_f32 v5, v199, v5, v69
	v_fma_f32 v6, v200, v6, v70
	v_fma_f32 v7, v201, v7, v71
	v_fma_f32 v8, v202, v8, v72
	v_fma_f32 v9, v203, v9, v73
	v_fma_f32 v10, v204, v10, v74
	v_fma_f32 v11, v205, v11, v75
	v_fma_f32 v12, v206, v12, v76
	v_fma_f32 v13, v207, v13, v77
	v_fma_f32 v14, v208, v14, v78
	v_fma_f32 v15, v209, v15, v79
	v_cvt_pk_bf16_f32 v248, v0, v1
	v_cvt_pk_bf16_f32 v249, v2, v3
	v_cvt_pk_bf16_f32 v250, v4, v5
	v_cvt_pk_bf16_f32 v251, v6, v7
	v_cvt_pk_bf16_f32 v252, v8, v9
	v_cvt_pk_bf16_f32 v253, v10, v11
	v_cvt_pk_bf16_f32 v254, v12, v13
	v_cvt_pk_bf16_f32 v255, v14, v15
	global_store_dwordx2 v237, v[248:249], s[10:11] offset:0
	global_store_dwordx2 v237, v[250:251], s[10:11] offset:512
	global_store_dwordx2 v237, v[252:253], s[10:11] offset:1024
	global_store_dwordx2 v237, v[254:255], s[10:11] offset:1536
	s_add_u32 s10, s10, 0x880
	s_addc_u32 s11, s11, 0

.Lnl1_orig:
	v_lshlrev_b32_e32 v0, 2, v32
	v_and_b32_e32 v34, 0xfc, v0
	v_readlane_b32 s8, v192, 11
	v_mov_b32_e32 v49, 0
	v_lshlrev_b32_e32 v48, 2, v34
	v_readlane_b32 s9, v192, 12
	v_ashrrev_i32_e32 v55, 31, v54
	s_waitcnt vmcnt(2)
	v_lshlrev_b64 v[16:17], 12, v[54:55]
	v_lshl_add_u64 v[0:1], s[8:9], 0, v[48:49]
	s_mov_b64 s[6:7], 0x1000
	s_waitcnt vmcnt(0)
	v_add_co_u32_e32 v8, vcc, 0x1000, v0
	v_lshl_add_u64 v[16:17], s[82:83], 0, v[16:17]
	v_lshl_add_u64 v[12:13], v[0:1], 0, s[6:7]
	v_addc_co_u32_e32 v9, vcc, 0, v1, vcc
	v_lshl_add_u64 v[16:17], v[16:17], 0, v[48:49]
	global_load_dwordx4 v[0:3], v[12:13], off offset:1024
	global_load_dwordx4 v[4:7], v[12:13], off offset:2048
	s_nop 0
	global_load_dwordx4 v[8:11], v[8:9], off
	s_nop 0
	global_load_dwordx4 v[12:15], v[12:13], off offset:3072
	s_nop 0
	global_load_dwordx4 v[28:31], v[16:17], off
	global_load_dwordx4 v[24:27], v[16:17], off offset:1024
	global_load_dwordx4 v[20:23], v[16:17], off offset:2048
	s_nop 0
	global_load_dwordx4 v[16:19], v[16:17], off offset:3072
	v_mbcnt_hi_u32_b32 v33, -1, v175
	v_and_b32_e32 v35, 64, v33
	v_add_u32_e32 v35, 64, v35
	v_xor_b32_e32 v36, 32, v33
	v_cmp_lt_i32_e32 vcc, v36, v35
	s_movk_i32 s0, 0x880
	v_readlane_b32 s10, v192, 13
	v_cndmask_b32_e32 v36, v33, v36, vcc
	v_lshlrev_b32_e32 v55, 2, v36
	v_xor_b32_e32 v36, 16, v33
	v_cmp_lt_i32_e32 vcc, v36, v35
	v_readlane_b32 s11, v192, 14
	v_readlane_b32 s14, v192, 17
	v_cndmask_b32_e32 v36, v33, v36, vcc
	v_lshlrev_b32_e32 v56, 2, v36
	v_xor_b32_e32 v36, 8, v33
	v_cmp_lt_i32_e32 vcc, v36, v35
	v_readlane_b32 s15, v192, 18
	v_readlane_b32 s16, v192, 19
	v_cndmask_b32_e32 v36, v33, v36, vcc
	v_lshlrev_b32_e32 v57, 2, v36
	v_xor_b32_e32 v36, 4, v33
	v_cmp_lt_i32_e32 vcc, v36, v35
	v_readlane_b32 s17, v192, 20
	v_readlane_b32 s18, v192, 21
	v_cndmask_b32_e32 v36, v33, v36, vcc
	v_lshlrev_b32_e32 v58, 2, v36
	v_xor_b32_e32 v36, 2, v33
	v_cmp_lt_i32_e32 vcc, v36, v35
	s_ashr_i32 s75, s74, 31
	s_movk_i32 s14, 0x1000
	v_cndmask_b32_e32 v36, v33, v36, vcc
	v_lshlrev_b32_e32 v59, 2, v36
	v_xor_b32_e32 v36, 1, v33
	v_cmp_lt_i32_e32 vcc, v36, v35
	v_and_b32_e32 v35, 63, v32
	v_lshlrev_b32_e32 v48, 3, v35
	v_cndmask_b32_e32 v33, v33, v36, vcc
	v_lshlrev_b32_e32 v60, 2, v33
	v_mad_i64_i32 v[32:33], s[0:1], v54, s0, v[48:49]
	v_lshl_add_u64 v[32:33], s[84:85], 0, v[32:33]
	s_mov_b64 s[0:1], 0x3018000
	v_lshl_add_u64 v[50:51], v[32:33], 0, s[0:1]
	v_add_u32_e32 v32, s74, v54
	v_ashrrev_i32_e32 v33, 31, v32
	v_lshlrev_b64 v[32:33], 12, v[32:33]
	v_lshl_or_b32 v32, v35, 4, v32
	v_lshl_add_u64 v[52:53], s[82:83], 0, v[32:33]
	s_lshl_b64 s[8:9], s[74:75], 12
	s_mov_b64 s[10:11], 0
	s_movk_i32 s15, 0x407f
	s_movk_i32 s16, 0x4000
	s_movk_i32 s17, 0x6000
	v_lshlrev_b32_e32 v48, 2, v34
	v_mov_b32_e32 v61, 0x358637bd
	s_mov_b32 s18, 0x800000
	v_readlane_b32 s12, v192, 15
	v_readlane_b32 s13, v192, 16
	v_readlane_b32 s19, v192, 22
	v_readlane_b32 s20, v192, 23
	v_readlane_b32 s21, v192, 24
	v_readlane_b32 s22, v192, 25
	v_readlane_b32 s23, v192, 26
	s_branch .LBB0_1856

.LBB0_2945:
	s_or_b64 exec, exec, s[0:1]
	v_mov_b32_e32 v32, v174
	s_waitcnt lgkmcnt(0)
	s_barrier
	s_movk_i32 s3, 0x4080
	v_ashrrev_i32_e32 v0, 6, v32
	v_add_u32_e32 v54, s94, v0
	v_cmp_gt_i32_e32 vcc, s3, v54
	s_and_saveexec_b64 s[4:5], vcc
	s_cbranch_execz .LBB0_2950
	s_cmpk_lg_i32 s86, 0x100
	s_cbranch_scc1 .Lnl2_orig
	s_waitcnt vmcnt(0)
	v_readlane_b32 s20, v192, 13
	v_readlane_b32 s21, v192, 14
	v_lshrrev_b32_e32 v238, 6, v174
	s_nop 1
	v_readfirstlane_b32 s1, v238
	v_and_b32_e32 v236, 63, v174
	v_lshlrev_b32_e32 v237, 3, v236
	v_lshlrev_b32_e32 v236, 4, v236
	s_lshr_b32 s3, s94, 3
	s_and_b32 s18, s3, 7
	s_lshr_b32 s19, s3, 3
	s_lshl_b32 s0, s18, 11
	s_lshl_b32 s3, s19, 6
	s_add_i32 s0, s0, s3
	s_lshl_b32 s3, s1, 3
	s_add_i32 s0, s0, s3
	s_add_u32 s20, s20, 0x1000
	s_addc_u32 s21, s21, 0
	global_load_dwordx4 v[48:51], v236, s[20:21] offset:0
	global_load_dwordx4 v[52:55], v236, s[20:21] offset:1024
	global_load_dwordx4 v[56:59], v236, s[20:21] offset:2048
	global_load_dwordx4 v[60:63], v236, s[20:21] offset:3072
	s_lshl_b32 s8, s0, 12
	s_add_u32 s8, s82, s8
	s_addc_u32 s9, s83, 0
	s_mul_i32 s10, s0, 0x880
	s_add_u32 s10, s10, 0x3018000
	s_add_u32 s10, s84, s10
	s_addc_u32 s11, s85, 0
	s_lshr_b32 s1, s0, 12
	s_mul_i32 s3, s1, 0x6000
	s_add_u32 s12, s84, 0x55bb880
	s_addc_u32 s13, s85, 0
	s_add_u32 s12, s12, s3
	s_addc_u32 s13, s13, 0
	s_add_u32 s14, s12, 0x1000
	s_addc_u32 s15, s13, 0
	global_load_dwordx4 v[0:3], v236, s[8:9] offset:0
	global_load_dwordx4 v[4:7], v236, s[8:9] offset:1024
	global_load_dwordx4 v[8:11], v236, s[8:9] offset:2048
	global_load_dwordx4 v[12:15], v236, s[8:9] offset:3072
	s_add_u32 s8, s8, 0x1000
	s_addc_u32 s9, s9, 0
	global_load_dwordx4 v[64:67], v236, s[12:13] offset:0
	global_load_dwordx4 v[68:71], v236, s[12:13] offset:1024
	global_load_dwordx4 v[72:75], v236, s[12:13] offset:2048
	global_load_dwordx4 v[76:79], v236, s[12:13] offset:3072
	global_load_dwordx4 v[194:197], v236, s[14:15] offset:0
	global_load_dwordx4 v[198:201], v236, s[14:15] offset:1024
	global_load_dwordx4 v[202:205], v236, s[14:15] offset:2048
	global_load_dwordx4 v[206:209], v236, s[14:15] offset:3072
	global_load_dwordx4 v[16:19], v236, s[8:9] offset:0
	global_load_dwordx4 v[20:23], v236, s[8:9] offset:1024
	global_load_dwordx4 v[24:27], v236, s[8:9] offset:2048
	global_load_dwordx4 v[28:31], v236, s[8:9] offset:3072
	s_add_u32 s8, s8, 0x1000
	s_addc_u32 s9, s9, 0
	global_load_dwordx4 v[32:35], v236, s[8:9] offset:0
	global_load_dwordx4 v[36:39], v236, s[8:9] offset:1024
	global_load_dwordx4 v[40:43], v236, s[8:9] offset:2048
	global_load_dwordx4 v[44:47], v236, s[8:9] offset:3072
	s_add_u32 s8, s8, 0x1000
	s_addc_u32 s9, s9, 0
	s_waitcnt vmcnt(16)
	v_mul_f32_e32 v238, v0, v0
	v_mul_f32_e32 v239, v1, v1
	v_fmac_f32_e32 v238, v2, v2
	v_fmac_f32_e32 v239, v3, v3
	v_fmac_f32_e32 v238, v4, v4
	v_fmac_f32_e32 v239, v5, v5
	v_fmac_f32_e32 v238, v6, v6
	v_fmac_f32_e32 v239, v7, v7
	v_fmac_f32_e32 v238, v8, v8
	v_fmac_f32_e32 v239, v9, v9
	v_fmac_f32_e32 v238, v10, v10
	v_fmac_f32_e32 v239, v11, v11
	v_fmac_f32_e32 v238, v12, v12
	v_fmac_f32_e32 v239, v13, v13
	v_fmac_f32_e32 v238, v14, v14
	v_fmac_f32_e32 v239, v15, v15
	v_add_f32_e32 v238, v238, v239
	s_nop 1
	v_add_f32_dpp v238, v238, v238 quad_perm:[1,0,3,2] row_mask:0xf bank_mask:0xf bound_ctrl:1
	s_nop 1
	v_add_f32_dpp v238, v238, v238 quad_perm:[2,3,0,1] row_mask:0xf bank_mask:0xf bound_ctrl:1
	s_nop 1
	v_add_f32_dpp v238, v238, v238 row_ror:4 row_mask:0xf bank_mask:0xf bound_ctrl:1
	s_nop 1
	v_add_f32_dpp v238, v238, v238 row_ror:8 row_mask:0xf bank_mask:0xf bound_ctrl:1
	s_nop 1
	v_readlane_b32 s1, v238, 0
	v_readlane_b32 s3, v238, 16
	v_readlane_b32 s16, v238, 32
	v_readlane_b32 s17, v238, 48
	s_nop 1
	v_mov_b32_e32 v238, s1
	v_add_f32_e32 v238, s3, v238
	v_add_f32_e32 v238, s16, v238
	v_add_f32_e32 v238, s17, v238
	v_mov_b32_e32 v239, 0x358637bd
	v_fmac_f32_e32 v239, 0x3a800000, v238
	v_rsq_f32_e32 v238, v239
	s_nop 0
	s_waitcnt vmcnt(8)
	v_add_f32_e32 v194, 1.0, v194
	v_add_f32_e32 v195, 1.0, v195
	v_add_f32_e32 v196, 1.0, v196
	v_add_f32_e32 v197, 1.0, v197
	v_add_f32_e32 v198, 1.0, v198
	v_add_f32_e32 v199, 1.0, v199
	v_add_f32_e32 v200, 1.0, v200
	v_add_f32_e32 v201, 1.0, v201
	v_add_f32_e32 v202, 1.0, v202
	v_add_f32_e32 v203, 1.0, v203
	v_add_f32_e32 v204, 1.0, v204
	v_add_f32_e32 v205, 1.0, v205
	v_add_f32_e32 v206, 1.0, v206
	v_add_f32_e32 v207, 1.0, v207
	v_add_f32_e32 v208, 1.0, v208
	v_add_f32_e32 v209, 1.0, v209
	v_mul_f32_e32 v0, v0, v238
	v_mul_f32_e32 v1, v1, v238
	v_mul_f32_e32 v2, v2, v238
	v_mul_f32_e32 v3, v3, v238
	v_mul_f32_e32 v4, v4, v238
	v_mul_f32_e32 v5, v5, v238
	v_mul_f32_e32 v6, v6, v238
	v_mul_f32_e32 v7, v7, v238
	v_mul_f32_e32 v8, v8, v238
	v_mul_f32_e32 v9, v9, v238
	v_mul_f32_e32 v10, v10, v238
	v_mul_f32_e32 v11, v11, v238
	v_mul_f32_e32 v12, v12, v238
	v_mul_f32_e32 v13, v13, v238
	v_mul_f32_e32 v14, v14, v238
	v_mul_f32_e32 v15, v15, v238
	v_mul_f32_e32 v0, v48, v0
	v_mul_f32_e32 v1, v49, v1
	v_mul_f32_e32 v2, v50, v2
	v_mul_f32_e32 v3, v51, v3
	v_mul_f32_e32 v4, v52, v4
	v_mul_f32_e32 v5, v53, v5
	v_mul_f32_e32 v6, v54, v6
	v_mul_f32_e32 v7, v55, v7
	v_mul_f32_e32 v8, v56, v8
	v_mul_f32_e32 v9, v57, v9
	v_mul_f32_e32 v10, v58, v10
	v_mul_f32_e32 v11, v59, v11
	v_mul_f32_e32 v12, v60, v12
	v_mul_f32_e32 v13, v61, v13
	v_mul_f32_e32 v14, v62, v14
	v_mul_f32_e32 v15, v63, v15
	v_fma_f32 v0, v194, v0, v64
	v_fma_f32 v1, v195, v1, v65
	v_fma_f32 v2, v196, v2, v66
	v_fma_f32 v3, v197, v3, v67
	v_fma_f32 v4, v198, v4, v68
	v_fma_f32 v5, v199, v5, v69
	v_fma_f32 v6, v200, v6, v70
	v_fma_f32 v7, v201, v7, v71
	v_fma_f32 v8, v202, v8, v72
	v_fma_f32 v9, v203, v9, v73
	v_fma_f32 v10, v204, v10, v74
	v_fma_f32 v11, v205, v11, v75
	v_fma_f32 v12, v206, v12, v76
	v_fma_f32 v13, v207, v13, v77
	v_fma_f32 v14, v208, v14, v78
	v_fma_f32 v15, v209, v15, v79
	v_cvt_pk_bf16_f32 v240, v0, v1
	v_cvt_pk_bf16_f32 v241, v2, v3
	v_cvt_pk_bf16_f32 v242, v4, v5
	v_cvt_pk_bf16_f32 v243, v6, v7
	v_cvt_pk_bf16_f32 v244, v8, v9
	v_cvt_pk_bf16_f32 v245, v10, v11
	v_cvt_pk_bf16_f32 v246, v12, v13
	v_cvt_pk_bf16_f32 v247, v14, v15
	global_store_dwordx2 v237, v[240:241], s[10:11] offset:0
	global_store_dwordx2 v237, v[242:243], s[10:11] offset:512
	global_store_dwordx2 v237, v[244:245], s[10:11] offset:1024
	global_store_dwordx2 v237, v[246:247], s[10:11] offset:1536
	s_add_u32 s10, s10, 0x880
	s_addc_u32 s11, s11, 0
	global_load_dwordx4 v[0:3], v236, s[8:9] offset:0
	global_load_dwordx4 v[4:7], v236, s[8:9] offset:1024
	global_load_dwordx4 v[8:11], v236, s[8:9] offset:2048
	global_load_dwordx4 v[12:15], v236, s[8:9] offset:3072
	s_add_u32 s8, s8, 0x1000
	s_addc_u32 s9, s9, 0
	s_waitcnt vmcnt(12)
	v_mul_f32_e32 v238, v16, v16
	v_mul_f32_e32 v239, v17, v17
	v_fmac_f32_e32 v238, v18, v18
	v_fmac_f32_e32 v239, v19, v19
	v_fmac_f32_e32 v238, v20, v20
	v_fmac_f32_e32 v239, v21, v21
	v_fmac_f32_e32 v238, v22, v22
	v_fmac_f32_e32 v239, v23, v23
	v_fmac_f32_e32 v238, v24, v24
	v_fmac_f32_e32 v239, v25, v25
	v_fmac_f32_e32 v238, v26, v26
	v_fmac_f32_e32 v239, v27, v27
	v_fmac_f32_e32 v238, v28, v28
	v_fmac_f32_e32 v239, v29, v29
	v_fmac_f32_e32 v238, v30, v30
	v_fmac_f32_e32 v239, v31, v31
	v_add_f32_e32 v238, v238, v239
	s_nop 1
	v_add_f32_dpp v238, v238, v238 quad_perm:[1,0,3,2] row_mask:0xf bank_mask:0xf bound_ctrl:1
	s_nop 1
	v_add_f32_dpp v238, v238, v238 quad_perm:[2,3,0,1] row_mask:0xf bank_mask:0xf bound_ctrl:1
	s_nop 1
	v_add_f32_dpp v238, v238, v238 row_ror:4 row_mask:0xf bank_mask:0xf bound_ctrl:1
	s_nop 1
	v_add_f32_dpp v238, v238, v238 row_ror:8 row_mask:0xf bank_mask:0xf bound_ctrl:1
	s_nop 1
	v_readlane_b32 s1, v238, 0
	v_readlane_b32 s3, v238, 16
	v_readlane_b32 s16, v238, 32
	v_readlane_b32 s17, v238, 48
	s_nop 1
	v_mov_b32_e32 v238, s1
	v_add_f32_e32 v238, s3, v238
	v_add_f32_e32 v238, s16, v238
	v_add_f32_e32 v238, s17, v238
	v_mov_b32_e32 v239, 0x358637bd
	v_fmac_f32_e32 v239, 0x3a800000, v238
	v_rsq_f32_e32 v238, v239
	s_nop 0
	v_mul_f32_e32 v16, v16, v238
	v_mul_f32_e32 v17, v17, v238
	v_mul_f32_e32 v18, v18, v238
	v_mul_f32_e32 v19, v19, v238
	v_mul_f32_e32 v20, v20, v238
	v_mul_f32_e32 v21, v21, v238
	v_mul_f32_e32 v22, v22, v238
	v_mul_f32_e32 v23, v23, v238
	v_mul_f32_e32 v24, v24, v238
	v_mul_f32_e32 v25, v25, v238
	v_mul_f32_e32 v26, v26, v238
	v_mul_f32_e32 v27, v27, v238
	v_mul_f32_e32 v28, v28, v238
	v_mul_f32_e32 v29, v29, v238
	v_mul_f32_e32 v30, v30, v238
	v_mul_f32_e32 v31, v31, v238
	v_mul_f32_e32 v16, v48, v16
	v_mul_f32_e32 v17, v49, v17
	v_mul_f32_e32 v18, v50, v18
	v_mul_f32_e32 v19, v51, v19
	v_mul_f32_e32 v20, v52, v20
	v_mul_f32_e32 v21, v53, v21
	v_mul_f32_e32 v22, v54, v22
	v_mul_f32_e32 v23, v55, v23
	v_mul_f32_e32 v24, v56, v24
	v_mul_f32_e32 v25, v57, v25
	v_mul_f32_e32 v26, v58, v26
	v_mul_f32_e32 v27, v59, v27
	v_mul_f32_e32 v28, v60, v28
	v_mul_f32_e32 v29, v61, v29
	v_mul_f32_e32 v30, v62, v30
	v_mul_f32_e32 v31, v63, v31
	v_fma_f32 v16, v194, v16, v64
	v_fma_f32 v17, v195, v17, v65
	v_fma_f32 v18, v196, v18, v66
	v_fma_f32 v19, v197, v19, v67
	v_fma_f32 v20, v198, v20, v68
	v_fma_f32 v21, v199, v21, v69
	v_fma_f32 v22, v200, v22, v70
	v_fma_f32 v23, v201, v23, v71
	v_fma_f32 v24, v202, v24, v72
	v_fma_f32 v25, v203, v25, v73
	v_fma_f32 v26, v204, v26, v74
	v_fma_f32 v27, v205, v27, v75
	v_fma_f32 v28, v206, v28, v76
	v_fma_f32 v29, v207, v29, v77
	v_fma_f32 v30, v208, v30, v78
	v_fma_f32 v31, v209, v31, v79
	v_cvt_pk_bf16_f32 v248, v16, v17
	v_cvt_pk_bf16_f32 v249, v18, v19
	v_cvt_pk_bf16_f32 v250, v20, v21
	v_cvt_pk_bf16_f32 v251, v22, v23
	v_cvt_pk_bf16_f32 v252, v24, v25
	v_cvt_pk_bf16_f32 v253, v26, v27
	v_cvt_pk_bf16_f32 v254, v28, v29
	v_cvt_pk_bf16_f32 v255, v30, v31
	global_store_dwordx2 v237, v[248:249], s[10:11] offset:0
	global_store_dwordx2 v237, v[250:251], s[10:11] offset:512
	global_store_dwordx2 v237, v[252:253], s[10:11] offset:1024
	global_store_dwordx2 v237, v[254:255], s[10:11] offset:1536
	s_add_u32 s10, s10, 0x880
	s_addc_u32 s11, s11, 0
	global_load_dwordx4 v[16:19], v236, s[8:9] offset:0
	global_load_dwordx4 v[20:23], v236, s[8:9] offset:1024
	global_load_dwordx4 v[24:27], v236, s[8:9] offset:2048
	global_load_dwordx4 v[28:31], v236, s[8:9] offset:3072
	s_add_u32 s8, s8, 0x1000
	s_addc_u32 s9, s9, 0
	s_waitcnt vmcnt(16)
	v_mul_f32_e32 v238, v32, v32
	v_mul_f32_e32 v239, v33, v33
	v_fmac_f32_e32 v238, v34, v34
	v_fmac_f32_e32 v239, v35, v35
	v_fmac_f32_e32 v238, v36, v36
	v_fmac_f32_e32 v239, v37, v37
	v_fmac_f32_e32 v238, v38, v38
	v_fmac_f32_e32 v239, v39, v39
	v_fmac_f32_e32 v238, v40, v40
	v_fmac_f32_e32 v239, v41, v41
	v_fmac_f32_e32 v238, v42, v42
	v_fmac_f32_e32 v239, v43, v43
	v_fmac_f32_e32 v238, v44, v44
	v_fmac_f32_e32 v239, v45, v45
	v_fmac_f32_e32 v238, v46, v46
	v_fmac_f32_e32 v239, v47, v47
	v_add_f32_e32 v238, v238, v239
	s_nop 1
	v_add_f32_dpp v238, v238, v238 quad_perm:[1,0,3,2] row_mask:0xf bank_mask:0xf bound_ctrl:1
	s_nop 1
	v_add_f32_dpp v238, v238, v238 quad_perm:[2,3,0,1] row_mask:0xf bank_mask:0xf bound_ctrl:1
	s_nop 1
	v_add_f32_dpp v238, v238, v238 row_ror:4 row_mask:0xf bank_mask:0xf bound_ctrl:1
	s_nop 1
	v_add_f32_dpp v238, v238, v238 row_ror:8 row_mask:0xf bank_mask:0xf bound_ctrl:1
	s_nop 1
	v_readlane_b32 s1, v238, 0
	v_readlane_b32 s3, v238, 16
	v_readlane_b32 s16, v238, 32
	v_readlane_b32 s17, v238, 48
	s_nop 1
	v_mov_b32_e32 v238, s1
	v_add_f32_e32 v238, s3, v238
	v_add_f32_e32 v238, s16, v238
	v_add_f32_e32 v238, s17, v238
	v_mov_b32_e32 v239, 0x358637bd
	v_fmac_f32_e32 v239, 0x3a800000, v238
	v_rsq_f32_e32 v238, v239
	s_nop 0
	v_mul_f32_e32 v32, v32, v238
	v_mul_f32_e32 v33, v33, v238
	v_mul_f32_e32 v34, v34, v238
	v_mul_f32_e32 v35, v35, v238
	v_mul_f32_e32 v36, v36, v238
	v_mul_f32_e32 v37, v37, v238
	v_mul_f32_e32 v38, v38, v238
	v_mul_f32_e32 v39, v39, v238
	v_mul_f32_e32 v40, v40, v238
	v_mul_f32_e32 v41, v41, v238
	v_mul_f32_e32 v42, v42, v238
	v_mul_f32_e32 v43, v43, v238
	v_mul_f32_e32 v44, v44, v238
	v_mul_f32_e32 v45, v45, v238
	v_mul_f32_e32 v46, v46, v238
	v_mul_f32_e32 v47, v47, v238
	v_mul_f32_e32 v32, v48, v32
	v_mul_f32_e32 v33, v49, v33
	v_mul_f32_e32 v34, v50, v34
	v_mul_f32_e32 v35, v51, v35
	v_mul_f32_e32 v36, v52, v36
	v_mul_f32_e32 v37, v53, v37
	v_mul_f32_e32 v38, v54, v38
	v_mul_f32_e32 v39, v55, v39
	v_mul_f32_e32 v40, v56, v40
	v_mul_f32_e32 v41, v57, v41
	v_mul_f32_e32 v42, v58, v42
	v_mul_f32_e32 v43, v59, v43
	v_mul_f32_e32 v44, v60, v44
	v_mul_f32_e32 v45, v61, v45
	v_mul_f32_e32 v46, v62, v46
	v_mul_f32_e32 v47, v63, v47
	v_fma_f32 v32, v194, v32, v64
	v_fma_f32 v33, v195, v33, v65
	v_fma_f32 v34, v196, v34, v66
	v_fma_f32 v35, v197, v35, v67
	v_fma_f32 v36, v198, v36, v68
	v_fma_f32 v37, v199, v37, v69
	v_fma_f32 v38, v200, v38, v70
	v_fma_f32 v39, v201, v39, v71
	v_fma_f32 v40, v202, v40, v72
	v_fma_f32 v41, v203, v41, v73
	v_fma_f32 v42, v204, v42, v74
	v_fma_f32 v43, v205, v43, v75
	v_fma_f32 v44, v206, v44, v76
	v_fma_f32 v45, v207, v45, v77
	v_fma_f32 v46, v208, v46, v78
	v_fma_f32 v47, v209, v47, v79
	v_cvt_pk_bf16_f32 v240, v32, v33
	v_cvt_pk_bf16_f32 v241, v34, v35
	v_cvt_pk_bf16_f32 v242, v36, v37
	v_cvt_pk_bf16_f32 v243, v38, v39
	v_cvt_pk_bf16_f32 v244, v40, v41
	v_cvt_pk_bf16_f32 v245, v42, v43
	v_cvt_pk_bf16_f32 v246, v44, v45
	v_cvt_pk_bf16_f32 v247, v46, v47
	global_store_dwordx2 v237, v[240:241], s[10:11] offset:0
	global_store_dwordx2 v237, v[242:243], s[10:11] offset:512
	global_store_dwordx2 v237, v[244:245], s[10:11] offset:1024
	global_store_dwordx2 v237, v[246:247], s[10:11] offset:1536
	s_add_u32 s10, s10, 0x880
	s_addc_u32 s11, s11, 0
	global_load_dwordx4 v[32:35], v236, s[8:9] offset:0
	global_load_dwordx4 v[36:39], v236, s[8:9] offset:1024
	global_load_dwordx4 v[40:43], v236, s[8:9] offset:2048
	global_load_dwordx4 v[44:47], v236, s[8:9] offset:3072
	s_add_u32 s8, s8, 0x1000
	s_addc_u32 s9, s9, 0
	s_waitcnt vmcnt(16)
	v_mul_f32_e32 v238, v0, v0
	v_mul_f32_e32 v239, v1, v1
	v_fmac_f32_e32 v238, v2, v2
	v_fmac_f32_e32 v239, v3, v3
	v_fmac_f32_e32 v238, v4, v4
	v_fmac_f32_e32 v239, v5, v5
	v_fmac_f32_e32 v238, v6, v6
	v_fmac_f32_e32 v239, v7, v7
	v_fmac_f32_e32 v238, v8, v8
	v_fmac_f32_e32 v239, v9, v9
	v_fmac_f32_e32 v238, v10, v10
	v_fmac_f32_e32 v239, v11, v11
	v_fmac_f32_e32 v238, v12, v12
	v_fmac_f32_e32 v239, v13, v13
	v_fmac_f32_e32 v238, v14, v14
	v_fmac_f32_e32 v239, v15, v15
	v_add_f32_e32 v238, v238, v239
	s_nop 1
	v_add_f32_dpp v238, v238, v238 quad_perm:[1,0,3,2] row_mask:0xf bank_mask:0xf bound_ctrl:1
	s_nop 1
	v_add_f32_dpp v238, v238, v238 quad_perm:[2,3,0,1] row_mask:0xf bank_mask:0xf bound_ctrl:1
	s_nop 1
	v_add_f32_dpp v238, v238, v238 row_ror:4 row_mask:0xf bank_mask:0xf bound_ctrl:1
	s_nop 1
	v_add_f32_dpp v238, v238, v238 row_ror:8 row_mask:0xf bank_mask:0xf bound_ctrl:1
	s_nop 1
	v_readlane_b32 s1, v238, 0
	v_readlane_b32 s3, v238, 16
	v_readlane_b32 s16, v238, 32
	v_readlane_b32 s17, v238, 48
	s_nop 1
	v_mov_b32_e32 v238, s1
	v_add_f32_e32 v238, s3, v238
	v_add_f32_e32 v238, s16, v238
	v_add_f32_e32 v238, s17, v238
	v_mov_b32_e32 v239, 0x358637bd
	v_fmac_f32_e32 v239, 0x3a800000, v238
	v_rsq_f32_e32 v238, v239
	s_nop 0
	v_mul_f32_e32 v0, v0, v238
	v_mul_f32_e32 v1, v1, v238
	v_mul_f32_e32 v2, v2, v238
	v_mul_f32_e32 v3, v3, v238
	v_mul_f32_e32 v4, v4, v238
	v_mul_f32_e32 v5, v5, v238
	v_mul_f32_e32 v6, v6, v238
	v_mul_f32_e32 v7, v7, v238
	v_mul_f32_e32 v8, v8, v238
	v_mul_f32_e32 v9, v9, v238
	v_mul_f32_e32 v10, v10, v238
	v_mul_f32_e32 v11, v11, v238
	v_mul_f32_e32 v12, v12, v238
	v_mul_f32_e32 v13, v13, v238
	v_mul_f32_e32 v14, v14, v238
	v_mul_f32_e32 v15, v15, v238
	v_mul_f32_e32 v0, v48, v0
	v_mul_f32_e32 v1, v49, v1
	v_mul_f32_e32 v2, v50, v2
	v_mul_f32_e32 v3, v51, v3
	v_mul_f32_e32 v4, v52, v4
	v_mul_f32_e32 v5, v53, v5
	v_mul_f32_e32 v6, v54, v6
	v_mul_f32_e32 v7, v55, v7
	v_mul_f32_e32 v8, v56, v8
	v_mul_f32_e32 v9, v57, v9
	v_mul_f32_e32 v10, v58, v10
	v_mul_f32_e32 v11, v59, v11
	v_mul_f32_e32 v12, v60, v12
	v_mul_f32_e32 v13, v61, v13
	v_mul_f32_e32 v14, v62, v14
	v_mul_f32_e32 v15, v63, v15
	v_fma_f32 v0, v194, v0, v64
	v_fma_f32 v1, v195, v1, v65
	v_fma_f32 v2, v196, v2, v66
	v_fma_f32 v3, v197, v3, v67
	v_fma_f32 v4, v198, v4, v68
	v_fma_f32 v5, v199, v5, v69
	v_fma_f32 v6, v200, v6, v70
	v_fma_f32 v7, v201, v7, v71
	v_fma_f32 v8, v202, v8, v72
	v_fma_f32 v9, v203, v9, v73
	v_fma_f32 v10, v204, v10, v74
	v_fma_f32 v11, v205, v11, v75
	v_fma_f32 v12, v206, v12, v76
	v_fma_f32 v13, v207, v13, v77
	v_fma_f32 v14, v208, v14, v78
	v_fma_f32 v15, v209, v15, v79
	v_cvt_pk_bf16_f32 v248, v0, v1
	v_cvt_pk_bf16_f32 v249, v2, v3
	v_cvt_pk_bf16_f32 v250, v4, v5
	v_cvt_pk_bf16_f32 v251, v6, v7
	v_cvt_pk_bf16_f32 v252, v8, v9
	v_cvt_pk_bf16_f32 v253, v10, v11
	v_cvt_pk_bf16_f32 v254, v12, v13
	v_cvt_pk_bf16_f32 v255, v14, v15
	global_store_dwordx2 v237, v[248:249], s[10:11] offset:0
	global_store_dwordx2 v237, v[250:251], s[10:11] offset:512
	global_store_dwordx2 v237, v[252:253], s[10:11] offset:1024
	global_store_dwordx2 v237, v[254:255], s[10:11] offset:1536
	s_add_u32 s10, s10, 0x880
	s_addc_u32 s11, s11, 0
	global_load_dwordx4 v[0:3], v236, s[8:9] offset:0
	global_load_dwordx4 v[4:7], v236, s[8:9] offset:1024
	global_load_dwordx4 v[8:11], v236, s[8:9] offset:2048
	global_load_dwordx4 v[12:15], v236, s[8:9] offset:3072
	s_add_u32 s8, s8, 0x1000
	s_addc_u32 s9, s9, 0
	s_waitcnt vmcnt(16)
	v_mul_f32_e32 v238, v16, v16
	v_mul_f32_e32 v239, v17, v17
	v_fmac_f32_e32 v238, v18, v18
	v_fmac_f32_e32 v239, v19, v19
	v_fmac_f32_e32 v238, v20, v20
	v_fmac_f32_e32 v239, v21, v21
	v_fmac_f32_e32 v238, v22, v22
	v_fmac_f32_e32 v239, v23, v23
	v_fmac_f32_e32 v238, v24, v24
	v_fmac_f32_e32 v239, v25, v25
	v_fmac_f32_e32 v238, v26, v26
	v_fmac_f32_e32 v239, v27, v27
	v_fmac_f32_e32 v238, v28, v28
	v_fmac_f32_e32 v239, v29, v29
	v_fmac_f32_e32 v238, v30, v30
	v_fmac_f32_e32 v239, v31, v31
	v_add_f32_e32 v238, v238, v239
	s_nop 1
	v_add_f32_dpp v238, v238, v238 quad_perm:[1,0,3,2] row_mask:0xf bank_mask:0xf bound_ctrl:1
	s_nop 1
	v_add_f32_dpp v238, v238, v238 quad_perm:[2,3,0,1] row_mask:0xf bank_mask:0xf bound_ctrl:1
	s_nop 1
	v_add_f32_dpp v238, v238, v238 row_ror:4 row_mask:0xf bank_mask:0xf bound_ctrl:1
	s_nop 1
	v_add_f32_dpp v238, v238, v238 row_ror:8 row_mask:0xf bank_mask:0xf bound_ctrl:1
	s_nop 1
	v_readlane_b32 s1, v238, 0
	v_readlane_b32 s3, v238, 16
	v_readlane_b32 s16, v238, 32
	v_readlane_b32 s17, v238, 48
	s_nop 1
	v_mov_b32_e32 v238, s1
	v_add_f32_e32 v238, s3, v238
	v_add_f32_e32 v238, s16, v238
	v_add_f32_e32 v238, s17, v238
	v_mov_b32_e32 v239, 0x358637bd
	v_fmac_f32_e32 v239, 0x3a800000, v238
	v_rsq_f32_e32 v238, v239
	s_nop 0
	v_mul_f32_e32 v16, v16, v238
	v_mul_f32_e32 v17, v17, v238
	v_mul_f32_e32 v18, v18, v238
	v_mul_f32_e32 v19, v19, v238
	v_mul_f32_e32 v20, v20, v238
	v_mul_f32_e32 v21, v21, v238
	v_mul_f32_e32 v22, v22, v238
	v_mul_f32_e32 v23, v23, v238
	v_mul_f32_e32 v24, v24, v238
	v_mul_f32_e32 v25, v25, v238
	v_mul_f32_e32 v26, v26, v238
	v_mul_f32_e32 v27, v27, v238
	v_mul_f32_e32 v28, v28, v238
	v_mul_f32_e32 v29, v29, v238
	v_mul_f32_e32 v30, v30, v238
	v_mul_f32_e32 v31, v31, v238
	v_mul_f32_e32 v16, v48, v16
	v_mul_f32_e32 v17, v49, v17
	v_mul_f32_e32 v18, v50, v18
	v_mul_f32_e32 v19, v51, v19
	v_mul_f32_e32 v20, v52, v20
	v_mul_f32_e32 v21, v53, v21
	v_mul_f32_e32 v22, v54, v22
	v_mul_f32_e32 v23, v55, v23
	v_mul_f32_e32 v24, v56, v24
	v_mul_f32_e32 v25, v57, v25
	v_mul_f32_e32 v26, v58, v26
	v_mul_f32_e32 v27, v59, v27
	v_mul_f32_e32 v28, v60, v28
	v_mul_f32_e32 v29, v61, v29
	v_mul_f32_e32 v30, v62, v30
	v_mul_f32_e32 v31, v63, v31
	v_fma_f32 v16, v194, v16, v64
	v_fma_f32 v17, v195, v17, v65
	v_fma_f32 v18, v196, v18, v66
	v_fma_f32 v19, v197, v19, v67
	v_fma_f32 v20, v198, v20, v68
	v_fma_f32 v21, v199, v21, v69
	v_fma_f32 v22, v200, v22, v70
	v_fma_f32 v23, v201, v23, v71
	v_fma_f32 v24, v202, v24, v72
	v_fma_f32 v25, v203, v25, v73
	v_fma_f32 v26, v204, v26, v74
	v_fma_f32 v27, v205, v27, v75
	v_fma_f32 v28, v206, v28, v76
	v_fma_f32 v29, v207, v29, v77
	v_fma_f32 v30, v208, v30, v78
	v_fma_f32 v31, v209, v31, v79
	v_cvt_pk_bf16_f32 v240, v16, v17
	v_cvt_pk_bf16_f32 v241, v18, v19
	v_cvt_pk_bf16_f32 v242, v20, v21
	v_cvt_pk_bf16_f32 v243, v22, v23
	v_cvt_pk_bf16_f32 v244, v24, v25
	v_cvt_pk_bf16_f32 v245, v26, v27
	v_cvt_pk_bf16_f32 v246, v28, v29
	v_cvt_pk_bf16_f32 v247, v30, v31
	global_store_dwordx2 v237, v[240:241], s[10:11] offset:0
	global_store_dwordx2 v237, v[242:243], s[10:11] offset:512
	global_store_dwordx2 v237, v[244:245], s[10:11] offset:1024
	global_store_dwordx2 v237, v[246:247], s[10:11] offset:1536
	s_add_u32 s10, s10, 0x880
	s_addc_u32 s11, s11, 0
	global_load_dwordx4 v[16:19], v236, s[8:9] offset:0
	global_load_dwordx4 v[20:23], v236, s[8:9] offset:1024
	global_load_dwordx4 v[24:27], v236, s[8:9] offset:2048
	global_load_dwordx4 v[28:31], v236, s[8:9] offset:3072
	s_add_u32 s8, s8, 0x1000
	s_addc_u32 s9, s9, 0
	s_waitcnt vmcnt(16)
	v_mul_f32_e32 v238, v32, v32
	v_mul_f32_e32 v239, v33, v33
	v_fmac_f32_e32 v238, v34, v34
	v_fmac_f32_e32 v239, v35, v35
	v_fmac_f32_e32 v238, v36, v36
	v_fmac_f32_e32 v239, v37, v37
	v_fmac_f32_e32 v238, v38, v38
	v_fmac_f32_e32 v239, v39, v39
	v_fmac_f32_e32 v238, v40, v40
	v_fmac_f32_e32 v239, v41, v41
	v_fmac_f32_e32 v238, v42, v42
	v_fmac_f32_e32 v239, v43, v43
	v_fmac_f32_e32 v238, v44, v44
	v_fmac_f32_e32 v239, v45, v45
	v_fmac_f32_e32 v238, v46, v46
	v_fmac_f32_e32 v239, v47, v47
	v_add_f32_e32 v238, v238, v239
	s_nop 1
	v_add_f32_dpp v238, v238, v238 quad_perm:[1,0,3,2] row_mask:0xf bank_mask:0xf bound_ctrl:1
	s_nop 1
	v_add_f32_dpp v238, v238, v238 quad_perm:[2,3,0,1] row_mask:0xf bank_mask:0xf bound_ctrl:1
	s_nop 1
	v_add_f32_dpp v238, v238, v238 row_ror:4 row_mask:0xf bank_mask:0xf bound_ctrl:1
	s_nop 1
	v_add_f32_dpp v238, v238, v238 row_ror:8 row_mask:0xf bank_mask:0xf bound_ctrl:1
	s_nop 1
	v_readlane_b32 s1, v238, 0
	v_readlane_b32 s3, v238, 16
	v_readlane_b32 s16, v238, 32
	v_readlane_b32 s17, v238, 48
	s_nop 1
	v_mov_b32_e32 v238, s1
	v_add_f32_e32 v238, s3, v238
	v_add_f32_e32 v238, s16, v238
	v_add_f32_e32 v238, s17, v238
	v_mov_b32_e32 v239, 0x358637bd
	v_fmac_f32_e32 v239, 0x3a800000, v238
	v_rsq_f32_e32 v238, v239
	s_nop 0
	v_mul_f32_e32 v32, v32, v238
	v_mul_f32_e32 v33, v33, v238
	v_mul_f32_e32 v34, v34, v238
	v_mul_f32_e32 v35, v35, v238
	v_mul_f32_e32 v36, v36, v238
	v_mul_f32_e32 v37, v37, v238
	v_mul_f32_e32 v38, v38, v238
	v_mul_f32_e32 v39, v39, v238
	v_mul_f32_e32 v40, v40, v238
	v_mul_f32_e32 v41, v41, v238
	v_mul_f32_e32 v42, v42, v238
	v_mul_f32_e32 v43, v43, v238
	v_mul_f32_e32 v44, v44, v238
	v_mul_f32_e32 v45, v45, v238
	v_mul_f32_e32 v46, v46, v238
	v_mul_f32_e32 v47, v47, v238
	v_mul_f32_e32 v32, v48, v32
	v_mul_f32_e32 v33, v49, v33
	v_mul_f32_e32 v34, v50, v34
	v_mul_f32_e32 v35, v51, v35
	v_mul_f32_e32 v36, v52, v36
	v_mul_f32_e32 v37, v53, v37
	v_mul_f32_e32 v38, v54, v38
	v_mul_f32_e32 v39, v55, v39
	v_mul_f32_e32 v40, v56, v40
	v_mul_f32_e32 v41, v57, v41
	v_mul_f32_e32 v42, v58, v42
	v_mul_f32_e32 v43, v59, v43
	v_mul_f32_e32 v44, v60, v44
	v_mul_f32_e32 v45, v61, v45
	v_mul_f32_e32 v46, v62, v46
	v_mul_f32_e32 v47, v63, v47
	v_fma_f32 v32, v194, v32, v64
	v_fma_f32 v33, v195, v33, v65
	v_fma_f32 v34, v196, v34, v66
	v_fma_f32 v35, v197, v35, v67
	v_fma_f32 v36, v198, v36, v68
	v_fma_f32 v37, v199, v37, v69
	v_fma_f32 v38, v200, v38, v70
	v_fma_f32 v39, v201, v39, v71
	v_fma_f32 v40, v202, v40, v72
	v_fma_f32 v41, v203, v41, v73
	v_fma_f32 v42, v204, v42, v74
	v_fma_f32 v43, v205, v43, v75
	v_fma_f32 v44, v206, v44, v76
	v_fma_f32 v45, v207, v45, v77
	v_fma_f32 v46, v208, v46, v78
	v_fma_f32 v47, v209, v47, v79
	v_cvt_pk_bf16_f32 v248, v32, v33
	v_cvt_pk_bf16_f32 v249, v34, v35
	v_cvt_pk_bf16_f32 v250, v36, v37
	v_cvt_pk_bf16_f32 v251, v38, v39
	v_cvt_pk_bf16_f32 v252, v40, v41
	v_cvt_pk_bf16_f32 v253, v42, v43
	v_cvt_pk_bf16_f32 v254, v44, v45
	v_cvt_pk_bf16_f32 v255, v46, v47
	global_store_dwordx2 v237, v[248:249], s[10:11] offset:0
	global_store_dwordx2 v237, v[250:251], s[10:11] offset:512
	global_store_dwordx2 v237, v[252:253], s[10:11] offset:1024
	global_store_dwordx2 v237, v[254:255], s[10:11] offset:1536
	s_add_u32 s10, s10, 0x880
	s_addc_u32 s11, s11, 0
	s_waitcnt vmcnt(12)
	v_mul_f32_e32 v238, v0, v0
	v_mul_f32_e32 v239, v1, v1
	v_fmac_f32_e32 v238, v2, v2
	v_fmac_f32_e32 v239, v3, v3
	v_fmac_f32_e32 v238, v4, v4
	v_fmac_f32_e32 v239, v5, v5
	v_fmac_f32_e32 v238, v6, v6
	v_fmac_f32_e32 v239, v7, v7
	v_fmac_f32_e32 v238, v8, v8
	v_fmac_f32_e32 v239, v9, v9
	v_fmac_f32_e32 v238, v10, v10
	v_fmac_f32_e32 v239, v11, v11
	v_fmac_f32_e32 v238, v12, v12
	v_fmac_f32_e32 v239, v13, v13
	v_fmac_f32_e32 v238, v14, v14
	v_fmac_f32_e32 v239, v15, v15
	v_add_f32_e32 v238, v238, v239
	s_nop 1
	v_add_f32_dpp v238, v238, v238 quad_perm:[1,0,3,2] row_mask:0xf bank_mask:0xf bound_ctrl:1
	s_nop 1
	v_add_f32_dpp v238, v238, v238 quad_perm:[2,3,0,1] row_mask:0xf bank_mask:0xf bound_ctrl:1
	s_nop 1
	v_add_f32_dpp v238, v238, v238 row_ror:4 row_mask:0xf bank_mask:0xf bound_ctrl:1
	s_nop 1
	v_add_f32_dpp v238, v238, v238 row_ror:8 row_mask:0xf bank_mask:0xf bound_ctrl:1
	s_nop 1
	v_readlane_b32 s1, v238, 0
	v_readlane_b32 s3, v238, 16
	v_readlane_b32 s16, v238, 32
	v_readlane_b32 s17, v238, 48
	s_nop 1
	v_mov_b32_e32 v238, s1
	v_add_f32_e32 v238, s3, v238
	v_add_f32_e32 v238, s16, v238
	v_add_f32_e32 v238, s17, v238
	v_mov_b32_e32 v239, 0x358637bd
	v_fmac_f32_e32 v239, 0x3a800000, v238
	v_rsq_f32_e32 v238, v239
	s_nop 0
	v_mul_f32_e32 v0, v0, v238
	v_mul_f32_e32 v1, v1, v238
	v_mul_f32_e32 v2, v2, v238
	v_mul_f32_e32 v3, v3, v238
	v_mul_f32_e32 v4, v4, v238
	v_mul_f32_e32 v5, v5, v238
	v_mul_f32_e32 v6, v6, v238
	v_mul_f32_e32 v7, v7, v238
	v_mul_f32_e32 v8, v8, v238
	v_mul_f32_e32 v9, v9, v238
	v_mul_f32_e32 v10, v10, v238
	v_mul_f32_e32 v11, v11, v238
	v_mul_f32_e32 v12, v12, v238
	v_mul_f32_e32 v13, v13, v238
	v_mul_f32_e32 v14, v14, v238
	v_mul_f32_e32 v15, v15, v238
	v_mul_f32_e32 v0, v48, v0
	v_mul_f32_e32 v1, v49, v1
	v_mul_f32_e32 v2, v50, v2
	v_mul_f32_e32 v3, v51, v3
	v_mul_f32_e32 v4, v52, v4
	v_mul_f32_e32 v5, v53, v5
	v_mul_f32_e32 v6, v54, v6
	v_mul_f32_e32 v7, v55, v7
	v_mul_f32_e32 v8, v56, v8
	v_mul_f32_e32 v9, v57, v9
	v_mul_f32_e32 v10, v58, v10
	v_mul_f32_e32 v11, v59, v11
	v_mul_f32_e32 v12, v60, v12
	v_mul_f32_e32 v13, v61, v13
	v_mul_f32_e32 v14, v62, v14
	v_mul_f32_e32 v15, v63, v15
	v_fma_f32 v0, v194, v0, v64
	v_fma_f32 v1, v195, v1, v65
	v_fma_f32 v2, v196, v2, v66
	v_fma_f32 v3, v197, v3, v67
	v_fma_f32 v4, v198, v4, v68
	v_fma_f32 v5, v199, v5, v69
	v_fma_f32 v6, v200, v6, v70
	v_fma_f32 v7, v201, v7, v71
	v_fma_f32 v8, v202, v8, v72
	v_fma_f32 v9, v203, v9, v73
	v_fma_f32 v10, v204, v10, v74
	v_fma_f32 v11, v205, v11, v75
	v_fma_f32 v12, v206, v12, v76
	v_fma_f32 v13, v207, v13, v77
	v_fma_f32 v14, v208, v14, v78
	v_fma_f32 v15, v209, v15, v79
	v_cvt_pk_bf16_f32 v240, v0, v1
	v_cvt_pk_bf16_f32 v241, v2, v3
	v_cvt_pk_bf16_f32 v242, v4, v5
	v_cvt_pk_bf16_f32 v243, v6, v7
	v_cvt_pk_bf16_f32 v244, v8, v9
	v_cvt_pk_bf16_f32 v245, v10, v11
	v_cvt_pk_bf16_f32 v246, v12, v13
	v_cvt_pk_bf16_f32 v247, v14, v15
	global_store_dwordx2 v237, v[240:241], s[10:11] offset:0
	global_store_dwordx2 v237, v[242:243], s[10:11] offset:512
	global_store_dwordx2 v237, v[244:245], s[10:11] offset:1024
	global_store_dwordx2 v237, v[246:247], s[10:11] offset:1536
	s_add_u32 s10, s10, 0x880
	s_addc_u32 s11, s11, 0
	s_waitcnt vmcnt(8)
	v_mul_f32_e32 v238, v16, v16
	v_mul_f32_e32 v239, v17, v17
	v_fmac_f32_e32 v238, v18, v18
	v_fmac_f32_e32 v239, v19, v19
	v_fmac_f32_e32 v238, v20, v20
	v_fmac_f32_e32 v239, v21, v21
	v_fmac_f32_e32 v238, v22, v22
	v_fmac_f32_e32 v239, v23, v23
	v_fmac_f32_e32 v238, v24, v24
	v_fmac_f32_e32 v239, v25, v25
	v_fmac_f32_e32 v238, v26, v26
	v_fmac_f32_e32 v239, v27, v27
	v_fmac_f32_e32 v238, v28, v28
	v_fmac_f32_e32 v239, v29, v29
	v_fmac_f32_e32 v238, v30, v30
	v_fmac_f32_e32 v239, v31, v31
	v_add_f32_e32 v238, v238, v239
	s_nop 1
	v_add_f32_dpp v238, v238, v238 quad_perm:[1,0,3,2] row_mask:0xf bank_mask:0xf bound_ctrl:1
	s_nop 1
	v_add_f32_dpp v238, v238, v238 quad_perm:[2,3,0,1] row_mask:0xf bank_mask:0xf bound_ctrl:1
	s_nop 1
	v_add_f32_dpp v238, v238, v238 row_ror:4 row_mask:0xf bank_mask:0xf bound_ctrl:1
	s_nop 1
	v_add_f32_dpp v238, v238, v238 row_ror:8 row_mask:0xf bank_mask:0xf bound_ctrl:1
	s_nop 1
	v_readlane_b32 s1, v238, 0
	v_readlane_b32 s3, v238, 16
	v_readlane_b32 s16, v238, 32
	v_readlane_b32 s17, v238, 48
	s_nop 1
	v_mov_b32_e32 v238, s1
	v_add_f32_e32 v238, s3, v238
	v_add_f32_e32 v238, s16, v238
	v_add_f32_e32 v238, s17, v238
	v_mov_b32_e32 v239, 0x358637bd
	v_fmac_f32_e32 v239, 0x3a800000, v238
	v_rsq_f32_e32 v238, v239
	s_nop 0
	v_mul_f32_e32 v16, v16, v238
	v_mul_f32_e32 v17, v17, v238
	v_mul_f32_e32 v18, v18, v238
	v_mul_f32_e32 v19, v19, v238
	v_mul_f32_e32 v20, v20, v238
	v_mul_f32_e32 v21, v21, v238
	v_mul_f32_e32 v22, v22, v238
	v_mul_f32_e32 v23, v23, v238
	v_mul_f32_e32 v24, v24, v238
	v_mul_f32_e32 v25, v25, v238
	v_mul_f32_e32 v26, v26, v238
	v_mul_f32_e32 v27, v27, v238
	v_mul_f32_e32 v28, v28, v238
	v_mul_f32_e32 v29, v29, v238
	v_mul_f32_e32 v30, v30, v238
	v_mul_f32_e32 v31, v31, v238
	v_mul_f32_e32 v16, v48, v16
	v_mul_f32_e32 v17, v49, v17
	v_mul_f32_e32 v18, v50, v18
	v_mul_f32_e32 v19, v51, v19
	v_mul_f32_e32 v20, v52, v20
	v_mul_f32_e32 v21, v53, v21
	v_mul_f32_e32 v22, v54, v22
	v_mul_f32_e32 v23, v55, v23
	v_mul_f32_e32 v24, v56, v24
	v_mul_f32_e32 v25, v57, v25
	v_mul_f32_e32 v26, v58, v26
	v_mul_f32_e32 v27, v59, v27
	v_mul_f32_e32 v28, v60, v28
	v_mul_f32_e32 v29, v61, v29
	v_mul_f32_e32 v30, v62, v30
	v_mul_f32_e32 v31, v63, v31
	v_fma_f32 v16, v194, v16, v64
	v_fma_f32 v17, v195, v17, v65
	v_fma_f32 v18, v196, v18, v66
	v_fma_f32 v19, v197, v19, v67
	v_fma_f32 v20, v198, v20, v68
	v_fma_f32 v21, v199, v21, v69
	v_fma_f32 v22, v200, v22, v70
	v_fma_f32 v23, v201, v23, v71
	v_fma_f32 v24, v202, v24, v72
	v_fma_f32 v25, v203, v25, v73
	v_fma_f32 v26, v204, v26, v74
	v_fma_f32 v27, v205, v27, v75
	v_fma_f32 v28, v206, v28, v76
	v_fma_f32 v29, v207, v29, v77
	v_fma_f32 v30, v208, v30, v78
	v_fma_f32 v31, v209, v31, v79
	v_cvt_pk_bf16_f32 v248, v16, v17
	v_cvt_pk_bf16_f32 v249, v18, v19
	v_cvt_pk_bf16_f32 v250, v20, v21
	v_cvt_pk_bf16_f32 v251, v22, v23
	v_cvt_pk_bf16_f32 v252, v24, v25
	v_cvt_pk_bf16_f32 v253, v26, v27
	v_cvt_pk_bf16_f32 v254, v28, v29
	v_cvt_pk_bf16_f32 v255, v30, v31
	global_store_dwordx2 v237, v[248:249], s[10:11] offset:0
	global_store_dwordx2 v237, v[250:251], s[10:11] offset:512
	global_store_dwordx2 v237, v[252:253], s[10:11] offset:1024
	global_store_dwordx2 v237, v[254:255], s[10:11] offset:1536
	s_add_u32 s10, s10, 0x880
	s_addc_u32 s11, s11, 0
	s_cmp_lg_u32 s19, 31
	s_cbranch_scc1 .Lnl2_end
	v_lshrrev_b32_e32 v238, 6, v174
	s_nop 0
	v_readfirstlane_b32 s1, v238
	s_lshl_b32 s0, s18, 3
	s_add_i32 s0, s0, s1
	s_lshl_b32 s0, s0, 1
	s_add_i32 s1, s0, 0x4000
	s_lshl_b32 s8, s1, 12
	s_add_u32 s8, s82, s8
	s_addc_u32 s9, s83, 0
	s_mul_i32 s10, s1, 0x880
	s_add_u32 s10, s10, 0x3018000
	s_add_u32 s10, s84, s10
	s_addc_u32 s11, s85, 0
	s_mul_i32 s3, s0, 0x6000
	s_add_u32 s12, s84, 0x55d3880
	s_addc_u32 s13, s85, 0
	s_add_u32 s12, s12, s3
	s_addc_u32 s13, s13, 0
	s_add_u32 s14, s12, 0x1000
	s_addc_u32 s15, s13, 0
	global_load_dwordx4 v[32:35], v236, s[8:9] offset:0
	global_load_dwordx4 v[36:39], v236, s[8:9] offset:1024
	global_load_dwordx4 v[40:43], v236, s[8:9] offset:2048
	global_load_dwordx4 v[44:47], v236, s[8:9] offset:3072
	s_add_u32 s8, s8, 0x1000
	s_addc_u32 s9, s9, 0
	global_load_dwordx4 v[80:83], v236, s[12:13] offset:0
	global_load_dwordx4 v[84:87], v236, s[12:13] offset:1024
	global_load_dwordx4 v[88:91], v236, s[12:13] offset:2048
	global_load_dwordx4 v[92:95], v236, s[12:13] offset:3072
	global_load_dwordx4 v[210:213], v236, s[14:15] offset:0
	global_load_dwordx4 v[214:217], v236, s[14:15] offset:1024
	global_load_dwordx4 v[218:221], v236, s[14:15] offset:2048
	global_load_dwordx4 v[222:225], v236, s[14:15] offset:3072
	s_add_i32 s0, s0, 1
	s_waitcnt vmcnt(8)
	v_mul_f32_e32 v238, v32, v32
	v_mul_f32_e32 v239, v33, v33
	v_fmac_f32_e32 v238, v34, v34
	v_fmac_f32_e32 v239, v35, v35
	v_fmac_f32_e32 v238, v36, v36
	v_fmac_f32_e32 v239, v37, v37
	v_fmac_f32_e32 v238, v38, v38
	v_fmac_f32_e32 v239, v39, v39
	v_fmac_f32_e32 v238, v40, v40
	v_fmac_f32_e32 v239, v41, v41
	v_fmac_f32_e32 v238, v42, v42
	v_fmac_f32_e32 v239, v43, v43
	v_fmac_f32_e32 v238, v44, v44
	v_fmac_f32_e32 v239, v45, v45
	v_fmac_f32_e32 v238, v46, v46
	v_fmac_f32_e32 v239, v47, v47
	v_add_f32_e32 v238, v238, v239
	s_nop 1
	v_add_f32_dpp v238, v238, v238 quad_perm:[1,0,3,2] row_mask:0xf bank_mask:0xf bound_ctrl:1
	s_nop 1
	v_add_f32_dpp v238, v238, v238 quad_perm:[2,3,0,1] row_mask:0xf bank_mask:0xf bound_ctrl:1
	s_nop 1
	v_add_f32_dpp v238, v238, v238 row_ror:4 row_mask:0xf bank_mask:0xf bound_ctrl:1
	s_nop 1
	v_add_f32_dpp v238, v238, v238 row_ror:8 row_mask:0xf bank_mask:0xf bound_ctrl:1
	s_nop 1
	v_readlane_b32 s1, v238, 0
	v_readlane_b32 s3, v238, 16
	v_readlane_b32 s16, v238, 32
	v_readlane_b32 s17, v238, 48
	s_nop 1
	v_mov_b32_e32 v238, s1
	v_add_f32_e32 v238, s3, v238
	v_add_f32_e32 v238, s16, v238
	v_add_f32_e32 v238, s17, v238
	v_mov_b32_e32 v239, 0x358637bd
	v_fmac_f32_e32 v239, 0x3a800000, v238
	v_rsq_f32_e32 v238, v239
	s_nop 0
	s_waitcnt vmcnt(0)
	v_add_f32_e32 v210, 1.0, v210
	v_add_f32_e32 v211, 1.0, v211
	v_add_f32_e32 v212, 1.0, v212
	v_add_f32_e32 v213, 1.0, v213
	v_add_f32_e32 v214, 1.0, v214
	v_add_f32_e32 v215, 1.0, v215
	v_add_f32_e32 v216, 1.0, v216
	v_add_f32_e32 v217, 1.0, v217
	v_add_f32_e32 v218, 1.0, v218
	v_add_f32_e32 v219, 1.0, v219
	v_add_f32_e32 v220, 1.0, v220
	v_add_f32_e32 v221, 1.0, v221
	v_add_f32_e32 v222, 1.0, v222
	v_add_f32_e32 v223, 1.0, v223
	v_add_f32_e32 v224, 1.0, v224
	v_add_f32_e32 v225, 1.0, v225
	v_mul_f32_e32 v32, v32, v238
	v_mul_f32_e32 v33, v33, v238
	v_mul_f32_e32 v34, v34, v238
	v_mul_f32_e32 v35, v35, v238
	v_mul_f32_e32 v36, v36, v238
	v_mul_f32_e32 v37, v37, v238
	v_mul_f32_e32 v38, v38, v238
	v_mul_f32_e32 v39, v39, v238
	v_mul_f32_e32 v40, v40, v238
	v_mul_f32_e32 v41, v41, v238
	v_mul_f32_e32 v42, v42, v238
	v_mul_f32_e32 v43, v43, v238
	v_mul_f32_e32 v44, v44, v238
	v_mul_f32_e32 v45, v45, v238
	v_mul_f32_e32 v46, v46, v238
	v_mul_f32_e32 v47, v47, v238
	v_mul_f32_e32 v32, v48, v32
	v_mul_f32_e32 v33, v49, v33
	v_mul_f32_e32 v34, v50, v34
	v_mul_f32_e32 v35, v51, v35
	v_mul_f32_e32 v36, v52, v36
	v_mul_f32_e32 v37, v53, v37
	v_mul_f32_e32 v38, v54, v38
	v_mul_f32_e32 v39, v55, v39
	v_mul_f32_e32 v40, v56, v40
	v_mul_f32_e32 v41, v57, v41
	v_mul_f32_e32 v42, v58, v42
	v_mul_f32_e32 v43, v59, v43
	v_mul_f32_e32 v44, v60, v44
	v_mul_f32_e32 v45, v61, v45
	v_mul_f32_e32 v46, v62, v46
	v_mul_f32_e32 v47, v63, v47
	v_fma_f32 v32, v210, v32, v80
	v_fma_f32 v33, v211, v33, v81
	v_fma_f32 v34, v212, v34, v82
	v_fma_f32 v35, v213, v35, v83
	v_fma_f32 v36, v214, v36, v84
	v_fma_f32 v37, v215, v37, v85
	v_fma_f32 v38, v216, v38, v86
	v_fma_f32 v39, v217, v39, v87
	v_fma_f32 v40, v218, v40, v88
	v_fma_f32 v41, v219, v41, v89
	v_fma_f32 v42, v220, v42, v90
	v_fma_f32 v43, v221, v43, v91
	v_fma_f32 v44, v222, v44, v92
	v_fma_f32 v45, v223, v45, v93
	v_fma_f32 v46, v224, v46, v94
	v_fma_f32 v47, v225, v47, v95
	v_cvt_pk_bf16_f32 v240, v32, v33
	v_cvt_pk_bf16_f32 v241, v34, v35
	v_cvt_pk_bf16_f32 v242, v36, v37
	v_cvt_pk_bf16_f32 v243, v38, v39
	v_cvt_pk_bf16_f32 v244, v40, v41
	v_cvt_pk_bf16_f32 v245, v42, v43
	v_cvt_pk_bf16_f32 v246, v44, v45
	v_cvt_pk_bf16_f32 v247, v46, v47
	global_store_dwordx2 v237, v[240:241], s[10:11] offset:0
	global_store_dwordx2 v237, v[242:243], s[10:11] offset:512
	global_store_dwordx2 v237, v[244:245], s[10:11] offset:1024
	global_store_dwordx2 v237, v[246:247], s[10:11] offset:1536
	s_add_u32 s10, s10, 0x880
	s_addc_u32 s11, s11, 0
	s_mul_i32 s3, s0, 0x6000
	s_add_u32 s12, s84, 0x55d3880
	s_addc_u32 s13, s85, 0
	s_add_u32 s12, s12, s3
	s_addc_u32 s13, s13, 0
	s_add_u32 s14, s12, 0x1000
	s_addc_u32 s15, s13, 0
	global_load_dwordx4 v[0:3], v236, s[8:9] offset:0
	global_load_dwordx4 v[4:7], v236, s[8:9] offset:1024
	global_load_dwordx4 v[8:11], v236, s[8:9] offset:2048
	global_load_dwordx4 v[12:15], v236, s[8:9] offset:3072
	s_add_u32 s8, s8, 0x1000
	s_addc_u32 s9, s9, 0
	global_load_dwordx4 v[64:67], v236, s[12:13] offset:0
	global_load_dwordx4 v[68:71], v236, s[12:13] offset:1024
	global_load_dwordx4 v[72:75], v236, s[12:13] offset:2048
	global_load_dwordx4 v[76:79], v236, s[12:13] offset:3072
	global_load_dwordx4 v[194:197], v236, s[14:15] offset:0
	global_load_dwordx4 v[198:201], v236, s[14:15] offset:1024
	global_load_dwordx4 v[202:205], v236, s[14:15] offset:2048
	global_load_dwordx4 v[206:209], v236, s[14:15] offset:3072
	s_add_i32 s0, s0, 1
	s_waitcnt vmcnt(8)
	v_mul_f32_e32 v238, v0, v0
	v_mul_f32_e32 v239, v1, v1
	v_fmac_f32_e32 v238, v2, v2
	v_fmac_f32_e32 v239, v3, v3
	v_fmac_f32_e32 v238, v4, v4
	v_fmac_f32_e32 v239, v5, v5
	v_fmac_f32_e32 v238, v6, v6
	v_fmac_f32_e32 v239, v7, v7
	v_fmac_f32_e32 v238, v8, v8
	v_fmac_f32_e32 v239, v9, v9
	v_fmac_f32_e32 v238, v10, v10
	v_fmac_f32_e32 v239, v11, v11
	v_fmac_f32_e32 v238, v12, v12
	v_fmac_f32_e32 v239, v13, v13
	v_fmac_f32_e32 v238, v14, v14
	v_fmac_f32_e32 v239, v15, v15
	v_add_f32_e32 v238, v238, v239
	s_nop 1
	v_add_f32_dpp v238, v238, v238 quad_perm:[1,0,3,2] row_mask:0xf bank_mask:0xf bound_ctrl:1
	s_nop 1
	v_add_f32_dpp v238, v238, v238 quad_perm:[2,3,0,1] row_mask:0xf bank_mask:0xf bound_ctrl:1
	s_nop 1
	v_add_f32_dpp v238, v238, v238 row_ror:4 row_mask:0xf bank_mask:0xf bound_ctrl:1
	s_nop 1
	v_add_f32_dpp v238, v238, v238 row_ror:8 row_mask:0xf bank_mask:0xf bound_ctrl:1
	s_nop 1
	v_readlane_b32 s1, v238, 0
	v_readlane_b32 s3, v238, 16
	v_readlane_b32 s16, v238, 32
	v_readlane_b32 s17, v238, 48
	s_nop 1
	v_mov_b32_e32 v238, s1
	v_add_f32_e32 v238, s3, v238
	v_add_f32_e32 v238, s16, v238
	v_add_f32_e32 v238, s17, v238
	v_mov_b32_e32 v239, 0x358637bd
	v_fmac_f32_e32 v239, 0x3a800000, v238
	v_rsq_f32_e32 v238, v239
	s_nop 0
	s_waitcnt vmcnt(0)
	v_add_f32_e32 v194, 1.0, v194
	v_add_f32_e32 v195, 1.0, v195
	v_add_f32_e32 v196, 1.0, v196
	v_add_f32_e32 v197, 1.0, v197
	v_add_f32_e32 v198, 1.0, v198
	v_add_f32_e32 v199, 1.0, v199
	v_add_f32_e32 v200, 1.0, v200
	v_add_f32_e32 v201, 1.0, v201
	v_add_f32_e32 v202, 1.0, v202
	v_add_f32_e32 v203, 1.0, v203
	v_add_f32_e32 v204, 1.0, v204
	v_add_f32_e32 v205, 1.0, v205
	v_add_f32_e32 v206, 1.0, v206
	v_add_f32_e32 v207, 1.0, v207
	v_add_f32_e32 v208, 1.0, v208
	v_add_f32_e32 v209, 1.0, v209
	v_mul_f32_e32 v0, v0, v238
	v_mul_f32_e32 v1, v1, v238
	v_mul_f32_e32 v2, v2, v238
	v_mul_f32_e32 v3, v3, v238
	v_mul_f32_e32 v4, v4, v238
	v_mul_f32_e32 v5, v5, v238
	v_mul_f32_e32 v6, v6, v238
	v_mul_f32_e32 v7, v7, v238
	v_mul_f32_e32 v8, v8, v238
	v_mul_f32_e32 v9, v9, v238
	v_mul_f32_e32 v10, v10, v238
	v_mul_f32_e32 v11, v11, v238
	v_mul_f32_e32 v12, v12, v238
	v_mul_f32_e32 v13, v13, v238
	v_mul_f32_e32 v14, v14, v238
	v_mul_f32_e32 v15, v15, v238
	v_mul_f32_e32 v0, v48, v0
	v_mul_f32_e32 v1, v49, v1
	v_mul_f32_e32 v2, v50, v2
	v_mul_f32_e32 v3, v51, v3
	v_mul_f32_e32 v4, v52, v4
	v_mul_f32_e32 v5, v53, v5
	v_mul_f32_e32 v6, v54, v6
	v_mul_f32_e32 v7, v55, v7
	v_mul_f32_e32 v8, v56, v8
	v_mul_f32_e32 v9, v57, v9
	v_mul_f32_e32 v10, v58, v10
	v_mul_f32_e32 v11, v59, v11
	v_mul_f32_e32 v12, v60, v12
	v_mul_f32_e32 v13, v61, v13
	v_mul_f32_e32 v14, v62, v14
	v_mul_f32_e32 v15, v63, v15
	v_fma_f32 v0, v194, v0, v64
	v_fma_f32 v1, v195, v1, v65
	v_fma_f32 v2, v196, v2, v66
	v_fma_f32 v3, v197, v3, v67
	v_fma_f32 v4, v198, v4, v68
	v_fma_f32 v5, v199, v5, v69
	v_fma_f32 v6, v200, v6, v70
	v_fma_f32 v7, v201, v7, v71
	v_fma_f32 v8, v202, v8, v72
	v_fma_f32 v9, v203, v9, v73
	v_fma_f32 v10, v204, v10, v74
	v_fma_f32 v11, v205, v11, v75
	v_fma_f32 v12, v206, v12, v76
	v_fma_f32 v13, v207, v13, v77
	v_fma_f32 v14, v208, v14, v78
	v_fma_f32 v15, v209, v15, v79
	v_cvt_pk_bf16_f32 v248, v0, v1
	v_cvt_pk_bf16_f32 v249, v2, v3
	v_cvt_pk_bf16_f32 v250, v4, v5
	v_cvt_pk_bf16_f32 v251, v6, v7
	v_cvt_pk_bf16_f32 v252, v8, v9
	v_cvt_pk_bf16_f32 v253, v10, v11
	v_cvt_pk_bf16_f32 v254, v12, v13
	v_cvt_pk_bf16_f32 v255, v14, v15
	global_store_dwordx2 v237, v[248:249], s[10:11] offset:0
	global_store_dwordx2 v237, v[250:251], s[10:11] offset:512
	global_store_dwordx2 v237, v[252:253], s[10:11] offset:1024
	global_store_dwordx2 v237, v[254:255], s[10:11] offset:1536
	s_add_u32 s10, s10, 0x880
	s_addc_u32 s11, s11, 0

.Lnl2_orig:
	v_lshlrev_b32_e32 v0, 2, v32
	v_and_b32_e32 v34, 0xfc, v0
	v_readlane_b32 s8, v192, 11
	v_mov_b32_e32 v49, 0
	v_lshlrev_b32_e32 v48, 2, v34
	v_readlane_b32 s10, v192, 13
	v_readlane_b32 s11, v192, 14
	s_mov_b64 s[0:1], 0x1000
	v_ashrrev_i32_e32 v55, 31, v54
	v_lshl_add_u64 v[0:1], s[10:11], 0, v[48:49]
	s_waitcnt vmcnt(2)
	v_lshl_add_u64 v[16:17], v[0:1], 0, s[0:1]
	v_add_co_u32_e32 v18, vcc, 0x1000, v0
	v_mbcnt_hi_u32_b32 v33, -1, v175
	s_nop 0
	v_addc_co_u32_e32 v19, vcc, 0, v1, vcc
	global_load_dwordx4 v[0:3], v[16:17], off offset:1024
	global_load_dwordx4 v[4:7], v[16:17], off offset:2048
	global_load_dwordx4 v[8:11], v[18:19], off
	global_load_dwordx4 v[12:15], v[16:17], off offset:3072
	v_lshlrev_b64 v[16:17], 12, v[54:55]
	v_lshl_add_u64 v[16:17], s[82:83], 0, v[16:17]
	v_lshl_add_u64 v[36:37], v[16:17], 0, v[48:49]
	global_load_dwordx4 v[28:31], v[36:37], off
	global_load_dwordx4 v[24:27], v[36:37], off offset:1024
	global_load_dwordx4 v[20:23], v[36:37], off offset:2048
	global_load_dwordx4 v[16:19], v[36:37], off offset:3072
	v_and_b32_e32 v35, 64, v33
	v_add_u32_e32 v35, 64, v35
	v_xor_b32_e32 v36, 32, v33
	v_cmp_lt_i32_e32 vcc, v36, v35
	s_movk_i32 s0, 0x880
	v_readlane_b32 s9, v192, 12
	v_cndmask_b32_e32 v36, v33, v36, vcc
	v_lshlrev_b32_e32 v55, 2, v36
	v_xor_b32_e32 v36, 16, v33
	v_cmp_lt_i32_e32 vcc, v36, v35
	v_readlane_b32 s12, v192, 15
	v_readlane_b32 s13, v192, 16
	v_cndmask_b32_e32 v36, v33, v36, vcc
	v_lshlrev_b32_e32 v56, 2, v36
	v_xor_b32_e32 v36, 8, v33
	v_cmp_lt_i32_e32 vcc, v36, v35
	v_readlane_b32 s16, v192, 19
	v_readlane_b32 s17, v192, 20
	v_cndmask_b32_e32 v36, v33, v36, vcc
	v_lshlrev_b32_e32 v57, 2, v36
	v_xor_b32_e32 v36, 4, v33
	v_cmp_lt_i32_e32 vcc, v36, v35
	v_readlane_b32 s18, v192, 21
	v_readlane_b32 s19, v192, 22
	v_cndmask_b32_e32 v36, v33, v36, vcc
	v_lshlrev_b32_e32 v58, 2, v36
	v_xor_b32_e32 v36, 2, v33
	v_cmp_lt_i32_e32 vcc, v36, v35
	s_ashr_i32 s75, s74, 31
	s_lshl_b64 s[6:7], s[74:75], 12
	v_cndmask_b32_e32 v36, v33, v36, vcc
	v_lshlrev_b32_e32 v59, 2, v36
	v_xor_b32_e32 v36, 1, v33
	v_cmp_lt_i32_e32 vcc, v36, v35
	v_and_b32_e32 v35, 63, v32
	v_lshlrev_b32_e32 v48, 3, v35
	v_cndmask_b32_e32 v33, v33, v36, vcc
	v_lshlrev_b32_e32 v60, 2, v33
	v_mad_i64_i32 v[32:33], s[0:1], v54, s0, v[48:49]
	v_lshl_add_u64 v[32:33], s[84:85], 0, v[32:33]
	s_mov_b64 s[0:1], 0x3018000
	v_lshl_add_u64 v[50:51], v[32:33], 0, s[0:1]
	v_add_u32_e32 v32, s74, v54
	v_ashrrev_i32_e32 v33, 31, v32
	v_lshlrev_b64 v[32:33], 12, v[32:33]
	v_lshl_or_b32 v32, v35, 4, v32
	v_lshl_add_u64 v[52:53], s[82:83], 0, v[32:33]
	s_mov_b64 s[8:9], 0
	s_movk_i32 s16, 0x407f
	s_movk_i32 s17, 0x4000
	s_movk_i32 s18, 0x6000
	v_lshlrev_b32_e32 v48, 2, v34
	s_mov_b64 s[10:11], 0x3000
	s_mov_b64 s[12:13], 0x4000
	v_mov_b32_e32 v61, 0x358637bd
	s_mov_b32 s19, 0x800000
	v_readlane_b32 s14, v192, 17
	v_readlane_b32 s15, v192, 18
	v_readlane_b32 s20, v192, 23
	v_readlane_b32 s21, v192, 24
	v_readlane_b32 s22, v192, 25
	v_readlane_b32 s23, v192, 26
	s_branch .LBB0_2948
